# f32 division expansions (div_scale/fma chain/div_fmas/div_fixup, 180 sites in sigmoid/silu/tanh/gelu) replaced by v_rcp_f32 (times numerator), hazard distances re-checked; plus ffn_act token bands per
# speedup vs baseline: 1.1068x; 1.0301x over previous
.LBB0_8:
	v_lshl_add_u64 v[6:7], v[4:5], 2, s[16:17]
	v_lshl_add_u64 v[6:7], v[6:7], 0, s[8:9]
	v_cmp_gt_i32_e32 vcc, s12, v4
	s_nop 1
	v_cndmask_b32_e32 v7, v7, v3, vcc
	v_cndmask_b32_e32 v6, v6, v2, vcc
	global_load_dword v6, v[6:7], off
	v_add_u32_e32 v7, 0x200, v4
	v_cmp_lt_i32_e32 vcc, s13, v4
	v_mov_b32_e32 v4, v7
	s_or_b64 s[4:5], vcc, s[4:5]
	v_lshl_add_u64 v[2:3], v[2:3], 0, s[10:11]
	s_waitcnt vmcnt(0)
	v_mul_f32_e32 v7, 0xbfb8aa3b, v6
	v_exp_f32_e32 v7, v7
	s_nop 0
	v_add_f32_e32 v7, 1.0, v7
	v_rcp_f32_e32 v7, v7
	s_nop 0
	v_mul_f32_e32 v6, v6, v7
	ds_write_b32 v1, v6
	v_add_u32_e32 v1, 0x800, v1
	s_andn2_b64 exec, exec, s[4:5]
	s_cbranch_execnz .LBB0_8

.LBB0_22:
	v_lshl_add_u64 v[4:5], s[8:9], 0, v[2:3]
	global_load_dword v8, v[4:5], off
	v_add_co_u32_e32 v4, vcc, 0x1000, v4
	v_add_u32_e32 v1, s74, v1
	s_nop 0
	v_addc_co_u32_e32 v5, vcc, 0, v5, vcc
	global_load_dword v9, v[4:5], off
	v_cmp_lt_i32_e32 vcc, s26, v1
	s_or_b64 s[24:25], vcc, s[24:25]
	v_lshl_add_u64 v[4:5], s[2:3], 0, v[2:3]
	v_lshl_add_u64 v[2:3], v[2:3], 0, s[4:5]
	s_waitcnt vmcnt(0)
	v_sub_f32_e32 v8, v9, v8
	v_mul_f32_e32 v8, 0x3fb8aa3b, v8
	v_exp_f32_e32 v8, v8
	s_nop 0
	v_add_f32_e32 v8, 1.0, v8
	v_rcp_f32_e32 v8, v8
	s_nop 0
	global_store_dword v[4:5], v8, off
	s_andn2_b64 exec, exec, s[24:25]
	s_cbranch_execnz .LBB0_22

.LBB0_299:
	v_add_u32_e32 v2, s10, v4
	v_mul_hi_i32 v3, v2, s30
	v_lshrrev_b32_e32 v6, 31, v3
	v_ashrrev_i32_e32 v3, 5, v3
	v_add_u32_e32 v3, v3, v6
	v_mad_u64_u32 v[6:7], s[2:3], v3, s47, v[2:3]
	v_mul_lo_u32 v3, v3, s48
	v_add_u32_e32 v9, 0, v5
	v_add3_u32 v3, 0, v3, v8
	ds_read_u16 v7, v9
	ds_read_u16 v12, v9 offset:384
	ds_read2st64_b32 v[10:11], v3 offset0:99 offset1:102
	ds_read_u16 v13, v9 offset:768
	ds_read_b32 v14, v3 offset:26880
	s_waitcnt lgkmcnt(4)
	v_lshlrev_b32_e32 v7, 16, v7
	s_waitcnt lgkmcnt(3)
	v_lshlrev_b32_e32 v3, 16, v12
	s_waitcnt lgkmcnt(2)
	v_mul_f32_e32 v3, v11, v3
	v_fmac_f32_e32 v3, v10, v7
	s_waitcnt lgkmcnt(1)
	v_lshlrev_b32_e32 v7, 16, v13
	s_waitcnt lgkmcnt(0)
	v_fmac_f32_e32 v3, v14, v7
	v_cmp_lt_i32_e32 vcc, 63, v6
	s_and_saveexec_b64 s[2:3], vcc
	s_xor_b64 s[2:3], exec, s[2:3]
	s_cbranch_execz .LBB0_303
	v_cmp_lt_u32_e32 vcc, s49, v6
	s_and_saveexec_b64 s[4:5], vcc
	s_cbranch_execz .LBB0_302
	v_mul_f32_e32 v3, 0xbfb8aa3b, v3
	v_exp_f32_e32 v3, v3
	s_nop 0
	v_add_f32_e32 v3, 1.0, v3
	v_rcp_f32_e32 v3, v3
	s_nop 0

.LBB0_303:
	s_andn2_saveexec_b64 s[2:3], s[2:3]
	s_cbranch_execz .LBB0_305
	v_add_f32_e32 v3, v3, v3
	v_mul_f32_e32 v3, 0x3fb8aa3b, v3
	v_exp_f32_e32 v3, v3
	s_nop 0
	v_add_f32_e32 v3, 1.0, v3
	v_rcp_f32_e32 v6, v3
	s_nop 0
	v_mul_f32_e32 v3, 2.0, v6
	v_sub_f32_e32 v3, 1.0, v3
.LBB0_305:
	s_or_b64 exec, exec, s[2:3]
	v_cvt_pk_bf16_f32 v3, v3, v3
	v_add_u32_e32 v6, 0x200, v2
	global_store_short v[0:1], v3, off offset:-3072
	v_mul_hi_i32 v3, v6, s30
	v_lshrrev_b32_e32 v7, 31, v3
	v_ashrrev_i32_e32 v3, 5, v3
	v_add_u32_e32 v3, v3, v7
	v_mad_u64_u32 v[6:7], s[2:3], v3, s47, v[6:7]
	v_mul_lo_u32 v3, v3, s48
	v_add3_u32 v3, 0, v3, v8
	ds_read_u16 v7, v9 offset:1024
	ds_read_u16 v12, v9 offset:1408
	ds_read2st64_b32 v[10:11], v3 offset0:107 offset1:110
	ds_read_b32 v13, v3 offset:28928
	ds_read_u16 v14, v9 offset:1792
	s_waitcnt lgkmcnt(4)
	v_lshlrev_b32_e32 v7, 16, v7
	s_waitcnt lgkmcnt(3)
	v_lshlrev_b32_e32 v3, 16, v12
	s_waitcnt lgkmcnt(2)
	v_mul_f32_e32 v3, v11, v3
	v_fmac_f32_e32 v3, v10, v7
	s_waitcnt lgkmcnt(0)
	v_lshlrev_b32_e32 v7, 16, v14
	v_fmac_f32_e32 v3, v13, v7
	v_cmp_lt_i32_e32 vcc, 63, v6
	s_and_saveexec_b64 s[2:3], vcc
	s_xor_b64 s[2:3], exec, s[2:3]
	s_cbranch_execz .LBB0_309
	v_cmp_lt_u32_e32 vcc, s49, v6
	s_and_saveexec_b64 s[4:5], vcc
	s_cbranch_execz .LBB0_308
	v_mul_f32_e32 v3, 0xbfb8aa3b, v3
	v_exp_f32_e32 v3, v3
	s_nop 0
	v_add_f32_e32 v3, 1.0, v3
	v_rcp_f32_e32 v3, v3
	s_nop 0

.LBB0_311:
	s_or_b64 exec, exec, s[2:3]
	v_cvt_pk_bf16_f32 v3, v3, v3
	v_add_u32_e32 v6, 0x400, v2
	global_store_short v[0:1], v3, off offset:-2048
	v_mul_hi_i32 v3, v6, s30
	v_lshrrev_b32_e32 v7, 31, v3
	v_ashrrev_i32_e32 v3, 5, v3
	v_add_u32_e32 v3, v3, v7
	v_mad_u64_u32 v[6:7], s[2:3], v3, s47, v[6:7]
	v_mul_lo_u32 v3, v3, s48
	v_add3_u32 v3, 0, v3, v8
	ds_read_u16 v7, v9 offset:2048
	ds_read_u16 v12, v9 offset:2432
	ds_read2st64_b32 v[10:11], v3 offset0:115 offset1:118
	ds_read_b32 v13, v3 offset:30976
	ds_read_u16 v14, v9 offset:2816
	s_waitcnt lgkmcnt(4)
	v_lshlrev_b32_e32 v7, 16, v7
	s_waitcnt lgkmcnt(3)
	v_lshlrev_b32_e32 v3, 16, v12
	s_waitcnt lgkmcnt(2)
	v_mul_f32_e32 v3, v11, v3
	v_fmac_f32_e32 v3, v10, v7
	s_waitcnt lgkmcnt(0)
	v_lshlrev_b32_e32 v7, 16, v14
	v_fmac_f32_e32 v3, v13, v7
	v_cmp_lt_i32_e32 vcc, 63, v6
	s_and_saveexec_b64 s[2:3], vcc
	s_xor_b64 s[2:3], exec, s[2:3]
	s_cbranch_execz .LBB0_315
	v_cmp_lt_u32_e32 vcc, s49, v6
	s_and_saveexec_b64 s[4:5], vcc
	s_cbranch_execz .LBB0_314
	v_mul_f32_e32 v3, 0xbfb8aa3b, v3
	v_exp_f32_e32 v3, v3
	s_nop 0
	v_add_f32_e32 v3, 1.0, v3
	v_rcp_f32_e32 v3, v3
	s_nop 0

.LBB0_317:
	s_or_b64 exec, exec, s[2:3]
	v_cvt_pk_bf16_f32 v3, v3, v3
	v_add_u32_e32 v2, 0x600, v2
	global_store_short v[0:1], v3, off offset:-1024
	v_mul_hi_i32 v3, v2, s30
	v_lshrrev_b32_e32 v6, 31, v3
	v_ashrrev_i32_e32 v3, 5, v3
	v_add_u32_e32 v6, v3, v6
	v_mad_u64_u32 v[2:3], s[2:3], v6, s47, v[2:3]
	v_mul_lo_u32 v3, v6, s48
	v_add3_u32 v3, 0, v3, v8
	ds_read_u16 v10, v9 offset:3072
	ds_read_u16 v11, v9 offset:3456
	ds_read2st64_b32 v[6:7], v3 offset0:123 offset1:126
	ds_read_b32 v12, v3 offset:33024
	ds_read_u16 v9, v9 offset:3840
	s_waitcnt lgkmcnt(4)
	v_lshlrev_b32_e32 v10, 16, v10
	s_waitcnt lgkmcnt(3)
	v_lshlrev_b32_e32 v3, 16, v11
	s_waitcnt lgkmcnt(2)
	v_mul_f32_e32 v3, v7, v3
	v_fmac_f32_e32 v3, v6, v10
	s_waitcnt lgkmcnt(0)
	v_lshlrev_b32_e32 v6, 16, v9
	v_fmac_f32_e32 v3, v12, v6
	v_cmp_lt_i32_e32 vcc, 63, v2
	s_and_saveexec_b64 s[2:3], vcc
	s_xor_b64 s[2:3], exec, s[2:3]
	s_cbranch_execz .LBB0_321
	v_cmp_lt_u32_e32 vcc, s49, v2
	s_and_saveexec_b64 s[4:5], vcc
	s_cbranch_execz .LBB0_320
	v_mul_f32_e32 v2, 0xbfb8aa3b, v3
	v_exp_f32_e32 v2, v2
	s_nop 0
	v_add_f32_e32 v2, 1.0, v2
	v_rcp_f32_e32 v3, v2
	s_nop 0

.LBB0_321:
	s_andn2_saveexec_b64 s[2:3], s[2:3]
	s_cbranch_execz .LBB0_298
	v_add_f32_e32 v2, v3, v3
	v_mul_f32_e32 v2, 0x3fb8aa3b, v2
	v_exp_f32_e32 v2, v2
	s_nop 0
	v_add_f32_e32 v2, 1.0, v2
	v_rcp_f32_e32 v3, v2
	s_nop 0
	v_mul_f32_e32 v2, 2.0, v3
	v_sub_f32_e32 v3, 1.0, v2
	s_branch .LBB0_298

.LBB0_428:
	s_or_b64 exec, exec, s[0:1]
	s_movk_i32 s0, 0x100
	v_ashrrev_i32_e32 v158, 6, v150
	v_cmp_gt_u32_e64 s[38:39], s0, v150
	s_movk_i32 s0, 0xff
	v_and_b32_e32 v154, 3, v158
	s_waitcnt lgkmcnt(0)
	s_barrier
	v_cmp_lt_u32_e64 s[40:41], s0, v150
	s_lshl_b32 s0, s50, 6
	v_lshlrev_b32_e32 v155, 2, v152
	v_or_b32_e32 v0, s0, v149
	v_lshlrev_b32_e32 v153, 4, v154
	v_lshlrev_b32_e32 v2, 2, v0
	v_lshlrev_b32_e32 v164, 1, v149
	v_or_b32_e32 v151, v153, v149
	v_or_b32_e32 v148, v153, v155
	v_lshl_add_u32 v157, v149, 2, 0
	v_add_lshl_u32 v159, v149, s0, 2
	s_and_saveexec_b64 s[0:1], s[40:41]
	s_xor_b64 s[42:43], exec, s[0:1]
	s_cbranch_execz .LBB0_430
	v_readlane_b32 s80, v252, 18
	v_readlane_b32 s94, v252, 32
	v_readlane_b32 s95, v252, 33
	v_mul_u32_u24_e32 v0, 0x190, v151
	v_and_b32_e32 v3, 48, v150
	v_readlane_b32 s0, v254, 52
	v_readlane_b32 s81, v252, 19
	v_readlane_b32 s82, v252, 20
	global_load_dword v74, v2, s[94:95]
	v_readlane_b32 s83, v252, 21
	v_readlane_b32 s84, v252, 22
	v_readlane_b32 s85, v252, 23
	v_readlane_b32 s86, v252, 24
	v_readlane_b32 s87, v252, 25
	v_readlane_b32 s88, v252, 26
	v_readlane_b32 s89, v252, 27
	v_readlane_b32 s90, v252, 28
	v_readlane_b32 s91, v252, 29
	v_readlane_b32 s92, v252, 30
	v_readlane_b32 s93, v252, 31
	v_add3_u32 v0, s0, v0, v3
	s_mov_b64 s[62:63], s[94:95]
	v_readlane_b32 s80, v252, 35
	ds_read_b128 v[64:67], v0 offset:128
	v_readlane_b32 s84, v252, 39
	v_readlane_b32 s85, v252, 40
	v_readlane_b32 s86, v252, 41
	v_readlane_b32 s87, v252, 42
	v_readlane_b32 s88, v252, 43
	v_readlane_b32 s89, v252, 44
	v_readlane_b32 s90, v252, 45
	v_readlane_b32 s91, v252, 46
	v_readlane_b32 s92, v252, 47
	v_readlane_b32 s93, v252, 48
	s_mov_b64 s[52:53], s[84:85]
	s_mov_b64 s[54:55], s[86:87]
	global_load_dword v0, v2, s[52:53]
	global_load_dword v76, v2, s[54:55]
	v_mul_u32_u24_e32 v3, 0x300, v148
	v_add_u32_e32 v100, 0xc400, v157
	v_add_u32_e32 v102, 0xcc00, v157
	v_add_u32_e32 v103, 0xd000, v157
	v_add3_u32 v117, 0, v3, v164
	ds_read2_b32 v[72:73], v100 offset0:192 offset1:208
	ds_read2_b32 v[78:79], v102 offset0:64 offset1:80
	ds_read2_b32 v[84:85], v103 offset0:192 offset1:208
	ds_read_u16 v87, v117 offset:896
	ds_read_u16 v93, v117 offset:1664
	ds_read_u16 v3, v117 offset:2432
	ds_read_u16 v95, v117 offset:3200
	ds_read_u16 v99, v117 offset:3968
	s_waitcnt lgkmcnt(8)
	v_mfma_f32_16x16x32_bf16 v[68:71], v[64:67], v[24:27], 0
	s_waitcnt lgkmcnt(5)
	v_mov_b32_e32 v168, v85
	s_waitcnt lgkmcnt(2)
	v_lshlrev_b32_e32 v86, 16, v3
	v_lshlrev_b32_e32 v142, 16, v93
	s_waitcnt lgkmcnt(1)
	v_lshlrev_b32_e32 v143, 16, v95
	s_mov_b32 s4, 0x2b8cbccc
	s_mov_b32 s10, 0x45800000
	v_readlane_b32 s81, v252, 36
	v_readlane_b32 s82, v252, 37
	v_readlane_b32 s83, v252, 38
	v_readlane_b32 s94, v252, 49
	v_readlane_b32 s95, v252, 50
	s_mov_b64 s[56:57], s[88:89]
	s_mov_b64 s[58:59], s[90:91]
	s_mov_b64 s[60:61], s[92:93]
	s_waitcnt vmcnt(2)
	v_add_f32_e32 v2, v74, v68
	v_add_f32_e32 v3, v74, v69
	v_mul_f32_e32 v2, 0xbfb8aa3b, v2
	v_mul_f32_e32 v3, 0xbfb8aa3b, v3
	v_exp_f32_e32 v2, v2
	v_exp_f32_e32 v3, v3
	s_nop 0
	v_pk_add_f32 v[2:3], v[2:3], 1.0 op_sel_hi:[1,0]
	s_nop 0
	s_nop 0
	v_rcp_f32_e32 v3, v3
	s_nop 0
	v_div_scale_f32 v68, s[0:1], v2, v2, 1.0
	v_rcp_f32_e32 v69, v68
	s_nop 0
	v_fma_f32 v75, -v68, v69, 1.0
	v_fmac_f32_e32 v69, v75, v69
	v_div_scale_f32 v75, vcc, 1.0, v2, 1.0
	v_mul_f32_e32 v77, v75, v69
	v_fma_f32 v80, -v68, v77, v75
	v_fmac_f32_e32 v77, v80, v69
	global_load_dword v81, v159, s[62:63] offset:64
	global_load_dword v92, v159, s[52:53] offset:64
	global_load_dword v80, v159, s[54:55] offset:64
	v_fma_f32 v68, -v68, v77, v75
	v_div_fmas_f32 v68, v68, v69, v77
	v_div_fixup_f32 v2, v68, v2, 1.0
	v_pk_add_f32 v[68:69], v[2:3], -1.0 op_sel_hi:[1,0]
	ds_read_u16 v109, v117 offset:128
	ds_read_u16 v113, v117 offset:160
	ds_read_u16 v115, v117 offset:928
	ds_read_u16 v118, v117 offset:1696
	s_waitcnt vmcnt(3)
	v_pk_fma_f32 v[88:89], v[76:77], v[68:69], 1.0 op_sel_hi:[0,1,0]
	v_add_f32_e32 v68, v74, v70
	v_add_f32_e32 v69, v74, v71
	v_mul_f32_e32 v68, 0xbfb8aa3b, v68
	v_mul_f32_e32 v69, 0xbfb8aa3b, v69
	v_exp_f32_e32 v68, v68
	v_exp_f32_e32 v69, v69
	ds_read_u16 v82, v117 offset:2464
	ds_read_u16 v119, v117 offset:3232
	ds_read_u16 v120, v117 offset:4000
	v_pk_add_f32 v[68:69], v[68:69], 1.0 op_sel_hi:[1,0]
	s_waitcnt lgkmcnt(3)
	v_lshlrev_b32_e32 v140, 16, v118
	s_waitcnt lgkmcnt(2)
	v_lshlrev_b32_e32 v94, 16, v82
	s_waitcnt lgkmcnt(1)
	v_lshlrev_b32_e32 v141, 16, v119
	v_rcp_f32_e32 v75, v69
	s_nop 0
	v_div_scale_f32 v69, s[0:1], v68, v68, 1.0
	v_rcp_f32_e32 v70, v69
	s_nop 0
	v_fma_f32 v71, -v69, v70, 1.0
	v_fmac_f32_e32 v70, v71, v70
	v_div_scale_f32 v71, vcc, 1.0, v68, 1.0
	v_mul_f32_e32 v74, v71, v70
	v_fma_f32 v77, -v69, v74, v71
	v_fmac_f32_e32 v74, v77, v70
	v_fma_f32 v69, -v69, v74, v71
	v_div_fmas_f32 v69, v69, v70, v74
	v_div_fixup_f32 v74, v69, v68, 1.0
	v_pk_add_f32 v[68:69], v[74:75], -1.0 op_sel_hi:[1,0]
	s_nop 0
	v_pk_fma_f32 v[76:77], v[76:77], v[68:69], 1.0 op_sel_hi:[0,1,0]
	v_mfma_f32_16x16x32_bf16 v[68:71], v[64:67], v[32:35], 0
	s_waitcnt vmcnt(2)
	s_nop 6
	v_add_f32_e32 v68, v81, v68
	v_add_f32_e32 v69, v81, v69
	v_mul_f32_e32 v68, 0xbfb8aa3b, v68
	v_mul_f32_e32 v69, 0xbfb8aa3b, v69
	v_exp_f32_e32 v68, v68
	v_exp_f32_e32 v69, v69
	s_nop 0
	v_pk_add_f32 v[68:69], v[68:69], 1.0 op_sel_hi:[1,0]
	s_nop 0
	s_nop 0
	v_rcp_f32_e32 v91, v69
	s_nop 0
	s_nop 0
	v_rcp_f32_e32 v90, v68
	s_nop 0
	v_pk_add_f32 v[68:69], v[90:91], -1.0 op_sel_hi:[1,0]
	s_waitcnt vmcnt(0)
	v_pk_fma_f32 v[96:97], v[80:81], v[68:69], 1.0 op_sel_hi:[0,1,0]
	v_add_f32_e32 v68, v81, v70
	v_add_f32_e32 v69, v81, v71
	v_mul_f32_e32 v68, 0xbfb8aa3b, v68
	v_mul_f32_e32 v69, 0xbfb8aa3b, v69
	v_exp_f32_e32 v68, v68
	v_exp_f32_e32 v69, v69
	s_nop 0
	v_pk_add_f32 v[68:69], v[68:69], 1.0 op_sel_hi:[1,0]
	s_nop 0
	s_nop 0
	v_rcp_f32_e32 v107, v69
	s_nop 0
	v_div_scale_f32 v69, s[0:1], v68, v68, 1.0
	v_rcp_f32_e32 v70, v69
	s_nop 0
	v_fma_f32 v71, -v69, v70, 1.0
	v_fmac_f32_e32 v70, v71, v70
	v_div_scale_f32 v71, vcc, 1.0, v68, 1.0
	v_mul_f32_e32 v81, v71, v70
	v_fma_f32 v82, -v69, v81, v71
	v_fmac_f32_e32 v81, v82, v70
	global_load_dword v83, v159, s[62:63] offset:128
	global_load_dword v98, v159, s[52:53] offset:128
	global_load_dword v82, v159, s[54:55] offset:128
	v_fma_f32 v69, -v69, v81, v71
	v_div_fmas_f32 v69, v69, v70, v81
	v_div_fixup_f32 v106, v69, v68, 1.0
	v_pk_add_f32 v[68:69], v[106:107], -1.0 op_sel_hi:[1,0]
	ds_read2_b32 v[100:101], v100 offset0:224 offset1:240
	ds_read2_b32 v[104:105], v102 offset0:96 offset1:112
	ds_read2_b32 v[102:103], v103 offset0:224 offset1:240
	ds_read_u16 v145, v117 offset:192
	ds_read_u16 v164, v117 offset:960
	ds_read_u16 v121, v117 offset:1728
	v_pk_fma_f32 v[80:81], v[80:81], v[68:69], 1.0 op_sel_hi:[0,1,0]
	v_mfma_f32_16x16x32_bf16 v[68:71], v[64:67], v[48:51], 0
	ds_read_u16 v108, v117 offset:2496
	ds_read_u16 v133, v117 offset:3264
	ds_read_u16 v134, v117 offset:4032
	v_mfma_f32_16x16x32_bf16 v[64:67], v[64:67], v[56:59], 0
	s_waitcnt lgkmcnt(6)
	v_mov_b32_e32 v144, v103
	s_waitcnt lgkmcnt(2)
	v_lshlrev_b32_e32 v108, 16, v108
	s_waitcnt lgkmcnt(1)
	v_lshlrev_b32_e32 v133, 16, v133
	s_waitcnt lgkmcnt(0)
	v_lshlrev_b32_e32 v135, 16, v134
	v_mov_b32_e32 v134, v133
	s_waitcnt vmcnt(2)
	v_add_f32_e32 v68, v83, v68
	v_add_f32_e32 v69, v83, v69
	v_mul_f32_e32 v68, 0xbfb8aa3b, v68
	v_mul_f32_e32 v69, 0xbfb8aa3b, v69
	v_exp_f32_e32 v68, v68
	v_exp_f32_e32 v69, v69
	v_add_f32_e32 v70, v83, v70
	v_add_f32_e32 v71, v83, v71
	v_mul_f32_e32 v70, 0xbfb8aa3b, v70
	v_pk_add_f32 v[68:69], v[68:69], 1.0 op_sel_hi:[1,0]
	v_mul_f32_e32 v71, 0xbfb8aa3b, v71
	v_exp_f32_e32 v70, v70
	v_exp_f32_e32 v71, v71
	v_rcp_f32_e32 v69, v69
	s_nop 0
	v_pk_add_f32 v[70:71], v[70:71], 1.0 op_sel_hi:[1,0]
	v_rcp_f32_e32 v68, v68
	s_nop 0
	v_pk_add_f32 v[110:111], v[68:69], -1.0 op_sel_hi:[1,0]
	s_waitcnt vmcnt(0)
	v_pk_fma_f32 v[110:111], v[82:83], v[110:111], 1.0 op_sel_hi:[0,1,0]
	s_nop 0
	v_rcp_f32_e32 v71, v71
	s_nop 0
	v_div_scale_f32 v83, s[0:1], v70, v70, 1.0
	v_rcp_f32_e32 v112, v83
	s_nop 0
	v_fma_f32 v114, -v83, v112, 1.0
	v_fmac_f32_e32 v112, v114, v112
	v_div_scale_f32 v114, vcc, 1.0, v70, 1.0
	v_mul_f32_e32 v116, v114, v112
	v_fma_f32 v122, -v83, v116, v114
	v_fmac_f32_e32 v116, v122, v112
	v_fma_f32 v83, -v83, v116, v114
	v_div_fmas_f32 v83, v83, v112, v116
	global_load_dword v128, v159, s[62:63] offset:192
	global_load_dword v112, v159, s[52:53] offset:192
	global_load_dword v116, v159, s[54:55] offset:192
	v_div_fixup_f32 v70, v83, v70, 1.0
	v_pk_add_f32 v[122:123], v[70:71], -1.0 op_sel_hi:[1,0]
	ds_read_u16 v159, v117 offset:224
	ds_read_u16 v165, v117 offset:992
	ds_read_u16 v130, v117 offset:1760
	v_pk_fma_f32 v[82:83], v[82:83], v[122:123], 1.0 op_sel_hi:[0,1,0]
	ds_read_u16 v114, v117 offset:2528
	ds_read_u16 v132, v117 offset:3296
	s_waitcnt lgkmcnt(1)
	v_lshlrev_b32_e32 v114, 16, v114
	s_waitcnt vmcnt(2)
	v_add_f32_e32 v64, v128, v64
	v_add_f32_e32 v65, v128, v65
	v_mul_f32_e32 v64, 0xbfb8aa3b, v64
	v_mul_f32_e32 v65, 0xbfb8aa3b, v65
	v_exp_f32_e32 v64, v64
	v_exp_f32_e32 v65, v65
	s_nop 0
	v_pk_add_f32 v[64:65], v[64:65], 1.0 op_sel_hi:[1,0]
	s_nop 0
	s_nop 0
	v_rcp_f32_e32 v127, v65
	s_nop 0
	s_nop 0
	v_rcp_f32_e32 v126, v64
	s_nop 0
	v_pk_add_f32 v[64:65], v[126:127], -1.0 op_sel_hi:[1,0]
	s_waitcnt vmcnt(0)
	v_pk_fma_f32 v[122:123], v[116:117], v[64:65], 1.0 op_sel_hi:[0,1,0]
	v_add_f32_e32 v64, v128, v66
	v_add_f32_e32 v65, v128, v67
	v_mul_f32_e32 v64, 0xbfb8aa3b, v64
	v_mul_f32_e32 v65, 0xbfb8aa3b, v65
	v_exp_f32_e32 v64, v64
	v_exp_f32_e32 v65, v65
	ds_read_u16 v117, v117 offset:4064
	v_pk_add_f32 v[64:65], v[64:65], 1.0 op_sel_hi:[1,0]
	s_nop 0
	s_nop 0
	v_rcp_f32_e32 v129, v65
	s_nop 0
	s_nop 0
	v_and_b32_e32 v67, 64, v179
	v_xor_b32_e32 v66, 1, v179
	v_add_u32_e32 v67, 64, v67
	v_cmp_lt_i32_e32 vcc, v66, v67
	v_rcp_f32_e32 v128, v64
	s_nop 0
	v_pk_add_f32 v[64:65], v[128:129], -1.0 op_sel_hi:[1,0]
	v_cndmask_b32_e32 v66, v179, v66, vcc
	v_lshlrev_b32_e32 v169, 2, v66
	v_xor_b32_e32 v66, 2, v179
	v_cmp_lt_i32_e32 vcc, v66, v67
	s_waitcnt lgkmcnt(0)
	v_pk_fma_f32 v[64:65], v[116:117], v[64:65], 1.0 op_sel_hi:[0,1,0]
	v_lshlrev_b32_e32 v116, 16, v130
	v_cndmask_b32_e32 v66, v179, v66, vcc
	v_lshlrev_b32_e32 v170, 2, v66
	v_xor_b32_e32 v66, 4, v179
	v_cmp_lt_i32_e32 vcc, v66, v67
	v_lshlrev_b32_e32 v131, 16, v117
	v_lshlrev_b32_e32 v117, 16, v132
	v_cndmask_b32_e32 v66, v179, v66, vcc
	v_lshlrev_b32_e32 v171, 2, v66
	v_xor_b32_e32 v66, 8, v179
	v_cmp_lt_i32_e32 vcc, v66, v67
	v_mov_b32_e32 v67, v105
	v_mov_b32_e32 v130, v117
	v_cndmask_b32_e32 v66, v179, v66, vcc
	v_lshlrev_b32_e32 v172, 2, v66
	v_mov_b32_e32 v66, v101
	v_pk_mul_f32 v[136:137], v[66:67], v[114:115] op_sel:[1,0] op_sel_hi:[0,0]
	v_pk_fma_f32 v[66:67], v[66:67], v[116:117], v[136:137]
	v_lshlrev_b32_e32 v132, 16, v121
	v_pk_fma_f32 v[66:67], v[144:145], v[130:131], v[66:67] op_sel_hi:[0,1,1]
	v_pk_mul_f32 v[64:65], v[64:65], v[66:67]
	v_pk_mul_f32 v[130:131], v[112:113], v[66:67] op_sel_hi:[0,1]
	v_mov_b32_e32 v66, v100
	v_mov_b32_e32 v67, v104
	v_pk_mul_f32 v[136:137], v[66:67], v[108:109] op_sel:[1,0] op_sel_hi:[0,0]
	v_pk_fma_f32 v[66:67], v[66:67], v[132:133], v[136:137]
	v_lshlrev_b32_e32 v121, 16, v120
	v_pk_fma_f32 v[134:135], v[102:103], v[134:135], v[66:67] op_sel_hi:[0,1,1]
	v_pk_mul_f32 v[66:67], v[82:83], v[134:135]
	v_mov_b32_e32 v82, v73
	v_mov_b32_e32 v83, v79
	v_pk_mul_f32 v[118:119], v[82:83], v[94:95] op_sel:[1,0] op_sel_hi:[0,0]
	v_mov_b32_e32 v120, v141
	v_pk_fma_f32 v[82:83], v[82:83], v[140:141], v[118:119]
	v_pk_mul_f32 v[166:167], v[98:99], v[134:135] op_sel_hi:[0,1]
	v_pk_fma_f32 v[82:83], v[168:169], v[120:121], v[82:83] op_sel_hi:[0,1,1]
	v_pk_mul_f32 v[120:121], v[92:93], v[82:83] op_sel_hi:[0,1]
	v_pk_mul_f32 v[118:119], v[80:81], v[82:83]
	v_mov_b32_e32 v82, v72
	v_mov_b32_e32 v83, v78
	v_pk_mul_f32 v[136:137], v[82:83], v[86:87] op_sel:[1,0] op_sel_hi:[0,0]
	v_lshlrev_b32_e32 v135, 16, v99
	v_mov_b32_e32 v134, v143
	v_pk_fma_f32 v[82:83], v[82:83], v[142:143], v[136:137]
	v_pk_mul_f32 v[80:81], v[120:121], v[120:121]
	v_pk_fma_f32 v[82:83], v[84:85], v[134:135], v[82:83] op_sel_hi:[0,1,1]
	v_pk_mul_f32 v[138:139], v[0:1], v[82:83] op_sel_hi:[0,1]
	v_pk_mul_f32 v[136:137], v[76:77], v[82:83]
	v_pk_fma_f32 v[76:77], v[138:139], v[138:139], v[80:81]
	v_mov_b32_e32 v117, v114
	v_pk_fma_f32 v[76:77], v[166:167], v[166:167], v[76:77]
	v_mov_b32_e32 v114, v105
	v_pk_fma_f32 v[76:77], v[130:131], v[130:131], v[76:77]
	ds_bpermute_b32 v80, v169, v76
	ds_bpermute_b32 v81, v169, v77
	v_mov_b32_e32 v133, v108
	v_mov_b32_e32 v141, v94
	v_mov_b32_e32 v94, v73
	v_mov_b32_e32 v143, v86
	s_waitcnt lgkmcnt(0)
	v_pk_add_f32 v[76:77], v[76:77], v[80:81]
	ds_bpermute_b32 v80, v170, v76
	ds_bpermute_b32 v81, v170, v77
	s_waitcnt lgkmcnt(0)
	v_pk_add_f32 v[76:77], v[76:77], v[80:81]
	ds_bpermute_b32 v80, v171, v76
	ds_bpermute_b32 v81, v171, v77
	s_waitcnt lgkmcnt(0)
	v_pk_add_f32 v[76:77], v[76:77], v[80:81]
	ds_bpermute_b32 v80, v172, v76
	ds_bpermute_b32 v81, v172, v77
	s_waitcnt lgkmcnt(0)
	v_pk_add_f32 v[76:77], v[76:77], v[80:81]
	s_nop 0
	v_pk_add_f32 v[76:77], v[76:77], s[4:5] op_sel_hi:[1,0]
	s_nop 0
	v_mul_f32_e32 v80, 0x4b800000, v76
	v_cmp_gt_f32_e64 s[0:1], s29, v76
	v_cmp_gt_f32_e32 vcc, s29, v77
	s_nop 0
	v_cndmask_b32_e64 v76, v76, v80, s[0:1]
	v_mul_f32_e32 v80, 0x4b800000, v77
	v_cndmask_b32_e32 v77, v77, v80, vcc
	v_rsq_f32_e32 v76, v76
	v_rsq_f32_e32 v77, v77
	s_nop 0
	v_pk_mul_f32 v[80:81], v[76:77], s[10:11] op_sel_hi:[1,0]
	s_nop 0
	v_cndmask_b32_e32 v135, v77, v81, vcc
	v_cndmask_b32_e64 v134, v76, v80, s[0:1]
	v_pk_mul_f32 v[80:81], v[138:139], v[134:135]
	v_pk_mul_f32 v[76:77], v[166:167], v[134:135]
	v_pk_mul_f32 v[138:139], v[74:75], v[80:81]
	v_pk_mul_f32 v[74:75], v[70:71], v[76:77]
	v_lshlrev_b32_e32 v71, 16, v165
	v_lshlrev_b32_e32 v70, 16, v159
	v_pk_mul_f32 v[82:83], v[120:121], v[134:135]
	v_pk_mov_b32 v[166:167], v[70:71], v[116:117] op_sel:[1,0]
	v_pk_mul_f32 v[120:121], v[106:107], v[82:83]
	v_mov_b32_e32 v106, v101
	v_pk_mul_f32 v[166:167], v[114:115], v[166:167] op_sel_hi:[0,1]
	v_pk_fma_f32 v[70:71], v[106:107], v[70:71], v[166:167] op_sel_hi:[0,1,1]
	v_pk_fma_f32 v[106:107], v[144:145], v[116:117], v[70:71] op_sel_hi:[0,1,1]
	v_lshlrev_b32_e32 v117, 16, v164
	v_lshlrev_b32_e32 v116, 16, v145
	v_pk_mul_f32 v[70:71], v[122:123], v[106:107]
	v_pk_mov_b32 v[122:123], v[116:117], v[132:133] op_sel:[1,0]
	v_pk_mul_f32 v[106:107], v[112:113], v[106:107] op_sel_hi:[0,1]
	v_pk_mul_f32 v[104:105], v[104:105], v[122:123] op_sel_hi:[0,1]
	v_pk_fma_f32 v[100:101], v[100:101], v[116:117], v[104:105] op_sel_hi:[0,1,1]
	v_pk_fma_f32 v[100:101], v[102:103], v[132:133], v[100:101] op_sel_hi:[0,1,1]
	v_pk_mul_f32 v[116:117], v[110:111], v[100:101]
	v_pk_mul_f32 v[98:99], v[98:99], v[100:101] op_sel_hi:[0,1]
	v_lshlrev_b32_e32 v101, 16, v115
	v_lshlrev_b32_e32 v100, 16, v113
	v_mov_b32_e32 v102, v79
	v_pk_mov_b32 v[104:105], v[100:101], v[140:141] op_sel:[1,0]
	s_nop 0
	v_pk_mul_f32 v[102:103], v[102:103], v[104:105] op_sel_hi:[0,1]
	v_pk_fma_f32 v[94:95], v[94:95], v[100:101], v[102:103] op_sel_hi:[0,1,1]
	v_pk_fma_f32 v[94:95], v[168:169], v[140:141], v[94:95] op_sel_hi:[0,1,1]
	v_pk_mul_f32 v[132:133], v[96:97], v[94:95]
	v_lshlrev_b32_e32 v97, 16, v87
	v_lshlrev_b32_e32 v96, 16, v109
	v_pk_mov_b32 v[86:87], v[96:97], v[142:143] op_sel:[1,0]
	v_pk_mul_f32 v[92:93], v[92:93], v[94:95] op_sel_hi:[0,1]
	v_pk_mul_f32 v[78:79], v[78:79], v[86:87] op_sel_hi:[0,1]
	v_pk_fma_f32 v[72:73], v[72:73], v[96:97], v[78:79] op_sel_hi:[0,1,1]
	v_pk_fma_f32 v[72:73], v[84:85], v[142:143], v[72:73] op_sel_hi:[0,1,1]
	v_pk_mul_f32 v[94:95], v[92:93], v[92:93]
	v_pk_mul_f32 v[78:79], v[0:1], v[72:73] op_sel_hi:[0,1]
	v_pk_mul_f32 v[142:143], v[88:89], v[72:73]
	v_pk_fma_f32 v[72:73], v[78:79], v[78:79], v[94:95]
	s_nop 0
	v_pk_fma_f32 v[72:73], v[98:99], v[98:99], v[72:73]
	s_nop 0
	v_pk_fma_f32 v[72:73], v[106:107], v[106:107], v[72:73]
	ds_bpermute_b32 v84, v169, v72
	ds_bpermute_b32 v85, v169, v73
	s_waitcnt lgkmcnt(0)
	v_pk_add_f32 v[72:73], v[72:73], v[84:85]
	ds_bpermute_b32 v84, v170, v72
	ds_bpermute_b32 v85, v170, v73
	s_waitcnt lgkmcnt(0)
	v_pk_add_f32 v[72:73], v[72:73], v[84:85]
	ds_bpermute_b32 v84, v171, v72
	ds_bpermute_b32 v85, v171, v73
	s_waitcnt lgkmcnt(0)
	v_pk_add_f32 v[72:73], v[72:73], v[84:85]
	ds_bpermute_b32 v84, v172, v72
	ds_bpermute_b32 v85, v172, v73
	s_waitcnt lgkmcnt(0)
	v_pk_add_f32 v[72:73], v[72:73], v[84:85]
	s_nop 0
	v_pk_add_f32 v[72:73], v[72:73], s[4:5] op_sel_hi:[1,0]
	s_nop 0
	v_mul_f32_e32 v0, 0x4b800000, v72
	v_cmp_gt_f32_e64 s[0:1], s29, v72
	v_cmp_gt_f32_e32 vcc, s29, v73
	s_nop 0
	v_cndmask_b32_e64 v0, v72, v0, s[0:1]
	v_rsq_f32_e32 v72, v0
	v_mul_f32_e32 v0, 0x4b800000, v73
	v_cndmask_b32_e32 v0, v73, v0, vcc
	v_rsq_f32_e32 v73, v0
	s_nop 0
	v_pk_mul_f32 v[84:85], v[72:73], s[10:11] op_sel_hi:[1,0]
	s_nop 0
	v_cndmask_b32_e32 v73, v73, v85, vcc
	v_cndmask_b32_e64 v72, v72, v84, s[0:1]
	v_pk_mul_f32 v[84:85], v[78:79], v[72:73]
	v_pk_mul_f32 v[78:79], v[98:99], v[72:73]
	v_pk_mul_f32 v[86:87], v[92:93], v[72:73]
	v_pk_mul_f32 v[122:123], v[68:69], v[78:79]
	v_pk_mul_f32 v[112:113], v[106:107], v[72:73]
	v_pk_mul_f32 v[68:69], v[130:131], v[134:135]
	v_pk_mul_f32 v[144:145], v[2:3], v[84:85]
	v_pk_mul_f32 v[140:141], v[90:91], v[86:87]
	v_pk_mul_f32 v[114:115], v[126:127], v[112:113]
	v_pk_mul_f32 v[72:73], v[128:129], v[68:69]
.LBB0_430:
	s_or_saveexec_b64 s[0:1], s[42:43]
	v_mov_b32_e32 v130, 0
	v_mov_b32_e32 v131, 0
	v_mov_b32_e32 v126, 0
	v_mov_b32_e32 v127, 0
	v_mov_b32_e32 v108, 0
	v_mov_b32_e32 v109, 0
	v_mov_b32_e32 v104, 0
	v_mov_b32_e32 v105, 0
	v_mov_b32_e32 v100, 0
	v_mov_b32_e32 v101, 0
	v_mov_b32_e32 v96, 0
	v_mov_b32_e32 v97, 0
	v_mov_b32_e32 v92, 0
	v_mov_b32_e32 v93, 0
	v_mov_b32_e32 v88, 0
	v_mov_b32_e32 v89, 0
	v_mov_b32_e32 v134, 0
	v_mov_b32_e32 v135, 0
	v_mov_b32_e32 v128, 0
	v_mov_b32_e32 v129, 0
	v_mov_b32_e32 v110, 0
	v_mov_b32_e32 v111, 0
	v_mov_b32_e32 v106, 0
	v_mov_b32_e32 v107, 0
	v_mov_b32_e32 v102, 0
	v_mov_b32_e32 v103, 0
	v_mov_b32_e32 v98, 0
	v_mov_b32_e32 v99, 0
	v_mov_b32_e32 v94, 0
	v_mov_b32_e32 v95, 0
	v_mov_b32_e32 v90, 0
	v_mov_b32_e32 v91, 0
	s_xor_b64 exec, exec, s[0:1]
	s_cbranch_execz .LBB0_432
	v_lshlrev_b32_e32 v0, 4, v158
	v_readlane_b32 s80, v252, 18
	v_or_b32_e32 v3, v0, v149
	v_readlane_b32 s88, v252, 26
	v_readlane_b32 s89, v252, 27
	v_mul_lo_u32 v3, v3, s6
	v_lshlrev_b32_e32 v64, 4, v152
	v_readlane_b32 s4, v254, 52
	v_readlane_b32 s90, v252, 28
	v_readlane_b32 s91, v252, 29
	s_mov_b64 s[56:57], s[88:89]
	v_add3_u32 v3, s4, v3, v64
	s_mov_b64 s[58:59], s[90:91]
	ds_read_b128 v[64:67], v3
	ds_read_b128 v[68:71], v3 offset:64
	global_load_dword v92, v2, s[58:59]
	global_load_dword v94, v2, s[58:59] offset:2048
	s_waitcnt lgkmcnt(1)
	v_mfma_f32_16x16x32_bf16 v[72:75], v[64:67], v[24:27], 0
	s_mov_b32 s6, 0xbf1b4598
	v_or_b32_e32 v0, v155, v0
	v_mul_lo_u32 v0, v0, s13
	s_waitcnt lgkmcnt(0)
	v_mfma_f32_16x16x32_bf16 v[76:79], v[68:71], v[20:23], 0
	v_add_u32_e32 v104, 0xc800, v157
	v_add_u32_e32 v105, 0xcc00, v157
	v_add_u32_e32 v106, 0xd400, v157
	v_add3_u32 v0, 0, v0, v164
	ds_read2_b32 v[2:3], v104 offset1:16
	ds_read2_b32 v[82:83], v105 offset0:128 offset1:144
	ds_read2_b32 v[86:87], v106 offset1:16
	v_readlane_b32 s81, v252, 19
	v_readlane_b32 s82, v252, 20
	v_readlane_b32 s83, v252, 21
	v_readlane_b32 s84, v252, 22
	v_readlane_b32 s85, v252, 23
	v_readlane_b32 s86, v252, 24
	v_readlane_b32 s87, v252, 25
	v_readlane_b32 s92, v252, 30
	v_readlane_b32 s93, v252, 31
	v_readlane_b32 s94, v252, 32
	v_readlane_b32 s95, v252, 33
	s_waitcnt vmcnt(1)
	v_add_f32_e32 v72, v72, v92
	v_mul_f32_e32 v72, 0xbfb8aa3b, v72
	v_exp_f32_e32 v81, v72
	s_waitcnt vmcnt(0)
	v_add_f32_e32 v72, v76, v94
	v_mul_f32_e32 v72, 0xbfb8aa3b, v72
	v_exp_f32_e32 v85, v72
	v_add_f32_e32 v72, v73, v92
	v_mul_f32_e32 v72, 0xbfb8aa3b, v72
	v_exp_f32_e32 v80, v72
	s_nop 0
	v_pk_add_f32 v[72:73], v[80:81], 1.0 op_sel_hi:[1,0]
	s_nop 0
	s_nop 0
	v_rcp_f32_e32 v73, v73
	s_nop 0
	s_nop 0
	v_rcp_f32_e32 v72, v72
	s_nop 0
	v_pk_mul_f32 v[88:89], v[72:73], s[6:7] op_sel_hi:[1,0]
	v_add_f32_e32 v72, v77, v94
	v_mul_f32_e32 v72, 0xbfb8aa3b, v72
	v_exp_f32_e32 v84, v72
	s_nop 0
	v_pk_add_f32 v[72:73], v[84:85], 1.0 op_sel_hi:[1,0]
	s_nop 0
	s_nop 0
	v_rcp_f32_e32 v73, v73
	s_nop 0
	s_nop 0
	v_rcp_f32_e32 v72, v72
	s_nop 0
	v_pk_mul_f32 v[90:91], v[72:73], s[6:7] op_sel_hi:[1,0]
	v_add_f32_e32 v72, v74, v92
	v_mul_f32_e32 v72, 0xbfb8aa3b, v72
	v_exp_f32_e32 v73, v72
	v_add_f32_e32 v72, v78, v94
	v_mul_f32_e32 v72, 0xbfb8aa3b, v72
	v_exp_f32_e32 v77, v72
	v_add_f32_e32 v72, v75, v92
	v_mul_f32_e32 v72, 0xbfb8aa3b, v72
	v_exp_f32_e32 v72, v72
	s_nop 0
	v_pk_add_f32 v[72:73], v[72:73], 1.0 op_sel_hi:[1,0]
	s_nop 0
	s_nop 0
	v_rcp_f32_e32 v73, v73
	s_nop 0
	s_nop 0
	v_rcp_f32_e32 v72, v72
	s_nop 0
	v_pk_mul_f32 v[92:93], v[72:73], s[6:7] op_sel_hi:[1,0]
	v_add_f32_e32 v72, v79, v94
	v_mul_f32_e32 v72, 0xbfb8aa3b, v72
	v_exp_f32_e32 v76, v72
	s_nop 0
	v_pk_add_f32 v[72:73], v[76:77], 1.0 op_sel_hi:[1,0]
	s_nop 0
	s_nop 0
	v_rcp_f32_e32 v73, v73
	s_nop 0
	s_nop 0
	v_rcp_f32_e32 v72, v72
	s_nop 0
	v_pk_mul_f32 v[94:95], v[72:73], s[6:7] op_sel_hi:[1,0]
	ds_read_u16 v72, v0 offset:1792
	ds_read_u16 v73, v0 offset:2560
	ds_read_u16 v74, v0 offset:3328
	ds_read_u16 v75, v0 offset:4096
	s_waitcnt lgkmcnt(3)
	v_lshlrev_b32_e32 v72, 16, v72
	s_waitcnt lgkmcnt(1)
	v_lshlrev_b32_e32 v77, 16, v74
	ds_read_u16 v74, v0 offset:1024
	v_lshlrev_b32_e32 v73, 16, v73
	v_mov_b32_e32 v76, v73
	s_waitcnt lgkmcnt(1)
	v_lshlrev_b32_e32 v75, 16, v75
	s_waitcnt lgkmcnt(0)
	v_lshlrev_b32_e32 v79, 16, v74
	ds_read_u16 v74, v0 offset:256
	ds_read_u16 v107, v0 offset:288
	s_waitcnt lgkmcnt(1)
	v_lshlrev_b32_e32 v78, 16, v74
	v_pk_mov_b32 v[80:81], v[78:79], v[72:73] op_sel:[1,0]
	v_mov_b32_e32 v74, v77
	v_pk_mul_f32 v[80:81], v[82:83], v[80:81] op_sel_hi:[0,1]
	v_pk_fma_f32 v[78:79], v[2:3], v[78:79], v[80:81] op_sel_hi:[0,1,1]
	v_pk_mul_f32 v[76:77], v[82:83], v[76:77] op_sel_hi:[0,1]
	v_pk_fma_f32 v[84:85], v[86:87], v[72:73], v[78:79] op_sel_hi:[0,1,1]
	v_pk_fma_f32 v[72:73], v[2:3], v[72:73], v[76:77] op_sel_hi:[0,1,1]
	global_load_dword v2, v159, s[58:59] offset:64
	global_load_dword v82, v159, s[58:59] offset:2112
	v_pk_fma_f32 v[80:81], v[86:87], v[74:75], v[72:73] op_sel_hi:[0,1,1]
	v_mfma_f32_16x16x32_bf16 v[72:75], v[68:71], v[28:31], 0
	v_mfma_f32_16x16x32_bf16 v[76:79], v[64:67], v[32:35], 0
	s_waitcnt vmcnt(0)
	s_nop 5
	v_add_f32_e32 v72, v72, v82
	v_mul_f32_e32 v72, 0xbfb8aa3b, v72
	v_add_f32_e32 v76, v76, v2
	v_exp_f32_e32 v99, v72
	v_add_f32_e32 v72, v77, v2
	v_mul_f32_e32 v76, 0xbfb8aa3b, v76
	v_mul_f32_e32 v72, 0xbfb8aa3b, v72
	v_exp_f32_e32 v97, v76
	v_exp_f32_e32 v96, v72
	s_nop 0
	v_pk_add_f32 v[76:77], v[96:97], 1.0 op_sel_hi:[1,0]
	s_nop 0
	s_nop 0
	v_rcp_f32_e32 v77, v77
	s_nop 0
	s_nop 0
	v_rcp_f32_e32 v76, v76
	s_nop 0
	v_add_f32_e32 v72, v73, v82
	v_mul_f32_e32 v72, 0xbfb8aa3b, v72
	v_exp_f32_e32 v98, v72
	v_pk_mul_f32 v[96:97], v[76:77], s[6:7] op_sel_hi:[1,0]
	v_pk_add_f32 v[72:73], v[98:99], 1.0 op_sel_hi:[1,0]
	s_nop 0
	s_nop 0
	v_rcp_f32_e32 v73, v73
	s_nop 0
	s_nop 0
	v_rcp_f32_e32 v72, v72
	s_nop 0
	v_pk_mul_f32 v[98:99], v[72:73], s[6:7] op_sel_hi:[1,0]
	v_add_f32_e32 v72, v78, v2
	v_mul_f32_e32 v72, 0xbfb8aa3b, v72
	v_exp_f32_e32 v73, v72
	v_add_f32_e32 v72, v74, v82
	v_add_f32_e32 v2, v79, v2
	v_mul_f32_e32 v72, 0xbfb8aa3b, v72
	v_mul_f32_e32 v2, 0xbfb8aa3b, v2
	v_exp_f32_e32 v77, v72
	v_exp_f32_e32 v72, v2
	s_nop 0
	v_pk_add_f32 v[72:73], v[72:73], 1.0 op_sel_hi:[1,0]
	s_nop 0
	s_nop 0
	v_rcp_f32_e32 v73, v73
	s_nop 0
	s_nop 0
	v_rcp_f32_e32 v72, v72
	s_nop 0
	v_add_f32_e32 v2, v75, v82
	v_mul_f32_e32 v2, 0xbfb8aa3b, v2
	v_exp_f32_e32 v76, v2
	v_pk_mul_f32 v[100:101], v[72:73], s[6:7] op_sel_hi:[1,0]
	s_waitcnt lgkmcnt(0)
	v_lshlrev_b32_e32 v78, 16, v107
	v_mov_b32_e32 v82, v83
	v_pk_add_f32 v[72:73], v[76:77], 1.0 op_sel_hi:[1,0]
	s_nop 0
	s_nop 0
	v_rcp_f32_e32 v73, v73
	s_nop 0
	s_nop 0
	v_rcp_f32_e32 v72, v72
	s_nop 0
	v_pk_mul_f32 v[102:103], v[72:73], s[6:7] op_sel_hi:[1,0]
	ds_read_u16 v2, v0 offset:1824
	ds_read_u16 v73, v0 offset:2592
	s_waitcnt lgkmcnt(1)
	v_lshlrev_b32_e32 v72, 16, v2
	ds_read_u16 v2, v0 offset:3360
	ds_read_u16 v74, v0 offset:4128
	s_waitcnt lgkmcnt(2)
	v_lshlrev_b32_e32 v73, 16, v73
	v_mov_b32_e32 v76, v73
	s_waitcnt lgkmcnt(1)
	v_lshlrev_b32_e32 v77, 16, v2
	ds_read_u16 v2, v0 offset:1056
	s_waitcnt lgkmcnt(1)
	v_lshlrev_b32_e32 v75, 16, v74
	v_mov_b32_e32 v74, v77
	v_pk_mul_f32 v[76:77], v[82:83], v[76:77] op_sel_hi:[0,1]
	s_waitcnt lgkmcnt(0)
	v_lshlrev_b32_e32 v79, 16, v2
	v_pk_mov_b32 v[108:109], v[78:79], v[72:73] op_sel:[1,0]
	v_mov_b32_e32 v2, v3
	v_pk_mul_f32 v[108:109], v[82:83], v[108:109] op_sel_hi:[0,1]
	v_pk_fma_f32 v[78:79], v[2:3], v[78:79], v[108:109] op_sel_hi:[0,1,1]
	v_mov_b32_e32 v108, v87
	v_pk_fma_f32 v[2:3], v[2:3], v[72:73], v[76:77] op_sel_hi:[0,1,1]
	v_pk_fma_f32 v[86:87], v[108:109], v[72:73], v[78:79] op_sel_hi:[0,1,1]
	v_pk_fma_f32 v[82:83], v[108:109], v[74:75], v[2:3] op_sel_hi:[0,1,1]
	global_load_dword v108, v159, s[58:59] offset:128
	global_load_dword v110, v159, s[58:59] offset:2176
	v_mfma_f32_16x16x32_bf16 v[72:75], v[68:71], v[36:39], 0
	ds_read2_b32 v[112:113], v104 offset0:32 offset1:48
	ds_read2_b32 v[114:115], v105 offset0:160 offset1:176
	ds_read2_b32 v[2:3], v106 offset0:32 offset1:48
	v_mfma_f32_16x16x32_bf16 v[76:79], v[64:67], v[48:51], 0
	s_waitcnt vmcnt(0)
	s_nop 2
	v_add_f32_e32 v72, v72, v110
	v_mul_f32_e32 v72, 0xbfb8aa3b, v72
	s_nop 1
	v_add_f32_e32 v76, v76, v108
	v_exp_f32_e32 v107, v72
	v_add_f32_e32 v72, v77, v108
	v_mul_f32_e32 v76, 0xbfb8aa3b, v76
	v_mul_f32_e32 v72, 0xbfb8aa3b, v72
	v_exp_f32_e32 v105, v76
	v_exp_f32_e32 v104, v72
	s_nop 0
	v_pk_add_f32 v[76:77], v[104:105], 1.0 op_sel_hi:[1,0]
	s_nop 0
	s_nop 0
	v_rcp_f32_e32 v77, v77
	s_nop 0
	s_nop 0
	v_rcp_f32_e32 v76, v76
	s_nop 0
	v_add_f32_e32 v72, v73, v110
	v_mul_f32_e32 v72, 0xbfb8aa3b, v72
	v_exp_f32_e32 v106, v72
	v_pk_mul_f32 v[104:105], v[76:77], s[6:7] op_sel_hi:[1,0]
	v_pk_add_f32 v[72:73], v[106:107], 1.0 op_sel_hi:[1,0]
	s_nop 0
	s_nop 0
	v_rcp_f32_e32 v73, v73
	s_nop 0
	s_nop 0
	v_rcp_f32_e32 v72, v72
	s_nop 0
	v_pk_mul_f32 v[106:107], v[72:73], s[6:7] op_sel_hi:[1,0]
	v_add_f32_e32 v72, v78, v108
	v_mul_f32_e32 v72, 0xbfb8aa3b, v72
	v_exp_f32_e32 v73, v72
	v_add_f32_e32 v72, v74, v110
	v_mul_f32_e32 v72, 0xbfb8aa3b, v72
	v_exp_f32_e32 v77, v72
	v_add_f32_e32 v72, v79, v108
	v_mul_f32_e32 v72, 0xbfb8aa3b, v72
	v_exp_f32_e32 v72, v72
	s_nop 0
	v_pk_add_f32 v[72:73], v[72:73], 1.0 op_sel_hi:[1,0]
	s_nop 0
	s_nop 0
	v_rcp_f32_e32 v73, v73
	s_nop 0
	s_nop 0
	v_rcp_f32_e32 v72, v72
	s_nop 0
	v_pk_mul_f32 v[108:109], v[72:73], s[6:7] op_sel_hi:[1,0]
	v_add_f32_e32 v72, v75, v110
	v_mul_f32_e32 v72, 0xbfb8aa3b, v72
	v_exp_f32_e32 v76, v72
	s_nop 0
	v_pk_add_f32 v[72:73], v[76:77], 1.0 op_sel_hi:[1,0]
	s_nop 0
	s_nop 0
	v_rcp_f32_e32 v73, v73
	s_nop 0
	s_nop 0
	v_rcp_f32_e32 v72, v72
	s_nop 0
	v_pk_mul_f32 v[110:111], v[72:73], s[6:7] op_sel_hi:[1,0]
	ds_read_u16 v72, v0 offset:1856
	ds_read_u16 v73, v0 offset:2624
	ds_read_u16 v74, v0 offset:3392
	ds_read_u16 v75, v0 offset:4160
	s_waitcnt lgkmcnt(3)
	v_lshlrev_b32_e32 v72, 16, v72
	s_waitcnt lgkmcnt(1)
	v_lshlrev_b32_e32 v77, 16, v74
	ds_read_u16 v74, v0 offset:320
	ds_read_u16 v78, v0 offset:1088
	v_lshlrev_b32_e32 v73, 16, v73
	v_mov_b32_e32 v76, v73
	s_waitcnt lgkmcnt(2)
	v_lshlrev_b32_e32 v75, 16, v75
	s_waitcnt lgkmcnt(0)
	v_lshlrev_b32_e32 v79, 16, v78
	v_lshlrev_b32_e32 v78, 16, v74
	v_pk_mov_b32 v[116:117], v[78:79], v[72:73] op_sel:[1,0]
	v_mov_b32_e32 v74, v77
	v_pk_mul_f32 v[116:117], v[114:115], v[116:117] op_sel_hi:[0,1]
	v_pk_fma_f32 v[78:79], v[112:113], v[78:79], v[116:117] op_sel_hi:[0,1,1]
	v_pk_mul_f32 v[76:77], v[114:115], v[76:77] op_sel_hi:[0,1]
	v_pk_fma_f32 v[78:79], v[2:3], v[72:73], v[78:79] op_sel_hi:[0,1,1]
	v_pk_fma_f32 v[72:73], v[112:113], v[72:73], v[76:77] op_sel_hi:[0,1,1]
	v_pk_fma_f32 v[76:77], v[2:3], v[74:75], v[72:73] op_sel_hi:[0,1,1]
	global_load_dword v2, v159, s[58:59] offset:192
	global_load_dword v112, v159, s[58:59] offset:2240
	v_mfma_f32_16x16x32_bf16 v[72:75], v[64:67], v[56:59], 0
	v_mfma_f32_16x16x32_bf16 v[64:67], v[68:71], v[60:63], 0
	s_waitcnt vmcnt(1)
	s_nop 5
	v_add_f32_e32 v68, v72, v2
	s_waitcnt vmcnt(0)
	v_add_f32_e32 v64, v64, v112
	v_mul_f32_e32 v64, 0xbfb8aa3b, v64
	v_exp_f32_e32 v71, v64
	v_add_f32_e32 v64, v73, v2
	v_mul_f32_e32 v68, 0xbfb8aa3b, v68
	v_mul_f32_e32 v64, 0xbfb8aa3b, v64
	v_exp_f32_e32 v69, v68
	v_exp_f32_e32 v68, v64
	s_nop 0
	v_pk_add_f32 v[68:69], v[68:69], 1.0 op_sel_hi:[1,0]
	s_nop 0
	s_nop 0
	v_rcp_f32_e32 v69, v69
	s_nop 0
	s_nop 0
	v_rcp_f32_e32 v68, v68
	s_nop 0
	v_add_f32_e32 v64, v65, v112
	v_mul_f32_e32 v64, 0xbfb8aa3b, v64
	v_exp_f32_e32 v70, v64
	v_pk_mul_f32 v[126:127], v[68:69], s[6:7] op_sel_hi:[1,0]
	v_pk_add_f32 v[64:65], v[70:71], 1.0 op_sel_hi:[1,0]
	s_nop 0
	s_nop 0
	v_rcp_f32_e32 v65, v65
	s_nop 0
	s_nop 0
	v_rcp_f32_e32 v64, v64
	s_nop 0
	v_pk_mul_f32 v[128:129], v[64:65], s[6:7] op_sel_hi:[1,0]
	v_add_f32_e32 v64, v74, v2
	v_mul_f32_e32 v64, 0xbfb8aa3b, v64
	v_exp_f32_e32 v65, v64
	v_add_f32_e32 v64, v66, v112
	v_add_f32_e32 v2, v75, v2
	v_mul_f32_e32 v64, 0xbfb8aa3b, v64
	v_mul_f32_e32 v2, 0xbfb8aa3b, v2
	v_exp_f32_e32 v69, v64
	v_exp_f32_e32 v64, v2
	s_nop 0
	v_pk_add_f32 v[64:65], v[64:65], 1.0 op_sel_hi:[1,0]
	s_nop 0
	s_nop 0
	v_rcp_f32_e32 v65, v65
	s_nop 0
	s_nop 0
	v_rcp_f32_e32 v64, v64
	s_nop 0
	v_add_f32_e32 v2, v67, v112
	v_mul_f32_e32 v2, 0xbfb8aa3b, v2
	v_exp_f32_e32 v68, v2
	v_pk_mul_f32 v[130:131], v[64:65], s[6:7] op_sel_hi:[1,0]
	v_pk_add_f32 v[64:65], v[68:69], 1.0 op_sel_hi:[1,0]
	s_nop 0
	s_nop 0
	v_rcp_f32_e32 v65, v65
	s_nop 0
	s_nop 0
	v_rcp_f32_e32 v64, v64
	s_nop 0
	v_pk_mul_f32 v[134:135], v[64:65], s[6:7] op_sel_hi:[1,0]
	ds_read_u16 v2, v0 offset:1888
	ds_read_u16 v65, v0 offset:2656
	s_waitcnt lgkmcnt(1)
	v_lshlrev_b32_e32 v64, 16, v2
	ds_read_u16 v2, v0 offset:3424
	ds_read_u16 v66, v0 offset:4192
	s_waitcnt lgkmcnt(2)
	v_lshlrev_b32_e32 v65, 16, v65
	v_mov_b32_e32 v68, v65
	s_waitcnt lgkmcnt(1)
	v_lshlrev_b32_e32 v69, 16, v2
	ds_read_u16 v2, v0 offset:352
	ds_read_u16 v0, v0 offset:1120
	s_waitcnt lgkmcnt(2)
	v_lshlrev_b32_e32 v67, 16, v66
	v_mov_b32_e32 v66, v69
	s_waitcnt lgkmcnt(1)
	v_lshlrev_b32_e32 v70, 16, v2
	s_waitcnt lgkmcnt(0)
	v_lshlrev_b32_e32 v71, 16, v0
	v_mov_b32_e32 v2, v115
	v_pk_mov_b32 v[72:73], v[70:71], v[64:65] op_sel:[1,0]
	v_mov_b32_e32 v0, v113
	v_pk_mul_f32 v[72:73], v[2:3], v[72:73] op_sel_hi:[0,1]
	v_pk_fma_f32 v[70:71], v[0:1], v[70:71], v[72:73] op_sel_hi:[0,1,1]
	v_mov_b32_e32 v72, v3
	v_pk_mul_f32 v[2:3], v[2:3], v[68:69] op_sel_hi:[0,1]
	v_pk_fma_f32 v[2:3], v[0:1], v[64:65], v[2:3] op_sel_hi:[0,1,1]
	v_pk_fma_f32 v[112:113], v[72:73], v[64:65], v[70:71] op_sel_hi:[0,1,1]
	v_pk_fma_f32 v[68:69], v[72:73], v[66:67], v[2:3] op_sel_hi:[0,1,1]
	v_mov_b32_e32 v72, 0
	v_mov_b32_e32 v73, v72
	v_mov_b32_e32 v114, v72
	v_mov_b32_e32 v115, v72
	v_mov_b32_e32 v74, v72
	v_mov_b32_e32 v75, v72
	v_mov_b32_e32 v122, v72
	v_mov_b32_e32 v123, v72
	v_mov_b32_e32 v120, v72
	v_mov_b32_e32 v121, v72
	v_mov_b32_e32 v140, v72
	v_mov_b32_e32 v141, v72
	v_mov_b32_e32 v138, v72
	v_mov_b32_e32 v139, v72
	v_mov_b32_e32 v144, v72
	v_mov_b32_e32 v145, v72
	v_mov_b32_e32 v64, v72
	v_mov_b32_e32 v65, v72
	v_mov_b32_e32 v70, v72
	v_mov_b32_e32 v71, v72
	v_mov_b32_e32 v66, v72
	v_mov_b32_e32 v67, v72
	v_mov_b32_e32 v116, v72
	v_mov_b32_e32 v117, v72
	v_mov_b32_e32 v118, v72
	v_mov_b32_e32 v119, v72
	v_mov_b32_e32 v132, v72
	v_mov_b32_e32 v133, v72
	v_mov_b32_e32 v136, v72
	v_mov_b32_e32 v137, v72
	v_mov_b32_e32 v142, v72
	v_mov_b32_e32 v143, v72

.LBB0_657:
	s_and_b32 s25, s24, 1
	s_cmp_eq_u32 s25, 0
	s_cselect_b64 s[64:65], -1, 0
	s_waitcnt vmcnt(4)
	ds_write_b128 v61, v[2:5] offset:40960
	s_waitcnt vmcnt(3)
	ds_write_b128 v62, v[6:9] offset:40960
	s_waitcnt vmcnt(2)
	ds_write_b128 v63, v[10:13] offset:40960
	s_waitcnt vmcnt(0)
	ds_write_b128 v64, v[14:17] offset:40960
	v_cndmask_b32_e64 v18, v66, v65, s[64:65]
	s_waitcnt lgkmcnt(0)
	s_barrier
	v_mad_u64_u32 v[22:23], s[0:1], v18, s13, v[0:1]
	ds_read_u16 v18, v22 offset:41216
	v_sub_f32_e32 v51, 1.0, v98
	s_add_i32 s70, s24, s78
	s_cmpk_gt_i32 s70, 0x3ff
	s_waitcnt lgkmcnt(0)
	v_lshlrev_b32_e32 v18, 16, v18
	v_mul_f32_e32 v18, 0xbfb8aa3b, v18
	v_exp_f32_e32 v18, v18
	s_nop 0
	v_add_f32_e32 v18, 1.0, v18
	s_nop 0
	v_rcp_f32_e32 v18, v18
	s_nop 0
	v_fma_f32 v18, v51, v18, v98
	v_cmp_gt_f32_e32 vcc, s29, v18
	ds_read_u16 v21, v22 offset:40960
	s_nop 0
	v_cndmask_b32_e64 v19, 0, 32, vcc
	v_ldexp_f32 v19, v18, v19
	v_log_f32_e32 v19, v19
	s_nop 0
	v_mul_f32_e32 v20, 0x3f317217, v19
	v_fma_f32 v20, v19, s31, -v20
	v_fmac_f32_e32 v20, 0x3377d1cf, v19
	v_fmac_f32_e32 v20, 0x3f317217, v19
	v_cmp_lt_f32_e64 s[0:1], |v19|, s96
	s_nop 1
	v_cndmask_b32_e64 v19, v19, v20, s[0:1]
	v_cndmask_b32_e32 v20, 0, v187, vcc
	v_sub_f32_e32 v20, v19, v20
	v_cndmask_b32_e64 v19, v68, v67, s[64:65]
	v_mad_u64_u32 v[24:25], s[0:1], v19, s13, v[0:1]
	ds_read_u16 v19, v24 offset:41216
	s_waitcnt lgkmcnt(0)
	v_lshlrev_b32_e32 v19, 16, v19
	v_mul_f32_e32 v19, 0xbfb8aa3b, v19
	v_exp_f32_e32 v19, v19
	s_nop 0
	v_add_f32_e32 v19, 1.0, v19
	s_nop 0
	v_rcp_f32_e32 v19, v19
	s_nop 0
	v_fma_f32 v22, v51, v19, v98
	v_cmp_gt_f32_e32 vcc, s29, v22
	s_nop 1
	v_cndmask_b32_e64 v19, 0, 32, vcc
	v_ldexp_f32 v19, v22, v19
	v_log_f32_e32 v19, v19
	s_nop 0
	v_mul_f32_e32 v23, 0x3f317217, v19
	v_fma_f32 v23, v19, s31, -v23
	v_fmac_f32_e32 v23, 0x3377d1cf, v19
	v_fmac_f32_e32 v23, 0x3f317217, v19
	v_cmp_lt_f32_e64 s[0:1], |v19|, s96
	s_nop 1
	v_cndmask_b32_e64 v19, v19, v23, s[0:1]
	v_cndmask_b32_e32 v23, 0, v187, vcc
	v_sub_f32_e32 v19, v19, v23
	ds_read_u16 v23, v24 offset:40960
	v_cndmask_b32_e64 v24, v70, v69, s[64:65]
	v_mad_u64_u32 v[48:49], s[0:1], v24, s13, v[0:1]
	ds_read_u16 v24, v48 offset:41216
	s_waitcnt lgkmcnt(0)
	v_lshlrev_b32_e32 v24, 16, v24
	v_mul_f32_e32 v24, 0xbfb8aa3b, v24
	v_exp_f32_e32 v24, v24
	s_nop 0
	v_add_f32_e32 v24, 1.0, v24
	s_nop 0
	v_rcp_f32_e32 v24, v24
	s_nop 0
	v_fma_f32 v24, v51, v24, v98
	v_cmp_gt_f32_e32 vcc, s29, v24
	s_nop 1
	v_cndmask_b32_e64 v25, 0, 32, vcc
	v_ldexp_f32 v25, v24, v25
	v_log_f32_e32 v25, v25
	s_nop 0
	v_mul_f32_e32 v29, 0x3f317217, v25
	v_fma_f32 v29, v25, s31, -v29
	v_fmac_f32_e32 v29, 0x3377d1cf, v25
	v_fmac_f32_e32 v29, 0x3f317217, v25
	v_cmp_lt_f32_e64 s[0:1], |v25|, s96
	s_nop 1
	v_cndmask_b32_e64 v25, v25, v29, s[0:1]
	v_cndmask_b32_e32 v29, 0, v187, vcc
	v_sub_f32_e32 v29, v25, v29
	ds_read_u16 v25, v48 offset:40960
	v_cndmask_b32_e64 v48, v72, v71, s[64:65]
	v_mad_u64_u32 v[102:103], s[0:1], v48, s13, v[0:1]
	ds_read_u16 v48, v102 offset:41216
	s_waitcnt lgkmcnt(0)
	v_lshlrev_b32_e32 v48, 16, v48
	v_mul_f32_e32 v48, 0xbfb8aa3b, v48
	v_exp_f32_e32 v48, v48
	s_nop 0
	v_add_f32_e32 v48, 1.0, v48
	s_nop 0
	v_rcp_f32_e32 v48, v48
	s_nop 0
	v_fma_f32 v48, v51, v48, v98
	v_cmp_gt_f32_e32 vcc, s29, v48
	v_cndmask_b32_e64 v101, v74, v73, s[64:65]
	s_nop 0
	v_cndmask_b32_e64 v49, 0, 32, vcc
	v_ldexp_f32 v49, v48, v49
	v_log_f32_e32 v49, v49
	s_nop 0
	v_mul_f32_e32 v50, 0x3f317217, v49
	v_fma_f32 v50, v49, s31, -v50
	v_fmac_f32_e32 v50, 0x3377d1cf, v49
	v_fmac_f32_e32 v50, 0x3f317217, v49
	v_cmp_lt_f32_e64 s[0:1], |v49|, s96
	s_nop 1
	v_cndmask_b32_e64 v49, v49, v50, s[0:1]
	v_cndmask_b32_e32 v50, 0, v187, vcc
	v_sub_f32_e32 v50, v49, v50
	ds_read_u16 v49, v102 offset:40960
	v_mad_u64_u32 v[102:103], s[0:1], v101, s13, v[0:1]
	ds_read_u16 v101, v102 offset:41216
	ds_read_u16 v102, v102 offset:40960
	s_waitcnt lgkmcnt(1)
	v_lshlrev_b32_e32 v101, 16, v101
	v_mul_f32_e32 v101, 0xbfb8aa3b, v101
	v_exp_f32_e32 v101, v101
	s_nop 0
	v_add_f32_e32 v101, 1.0, v101
	s_nop 0
	v_rcp_f32_e32 v101, v101
	s_nop 0
	v_fma_f32 v101, v51, v101, v98
	v_cmp_gt_f32_e32 vcc, s29, v101
	s_nop 1
	v_cndmask_b32_e64 v103, 0, 32, vcc
	v_ldexp_f32 v103, v101, v103
	v_log_f32_e32 v103, v103
	s_nop 0
	v_mul_f32_e32 v104, 0x3f317217, v103
	v_fma_f32 v104, v103, s31, -v104
	v_fmac_f32_e32 v104, 0x3377d1cf, v103
	v_fmac_f32_e32 v104, 0x3f317217, v103
	v_cmp_lt_f32_e64 s[0:1], |v103|, s96
	s_nop 1
	v_cndmask_b32_e64 v103, v103, v104, s[0:1]
	v_cndmask_b32_e32 v104, 0, v187, vcc
	v_sub_f32_e32 v103, v103, v104
	v_cndmask_b32_e64 v104, v76, v75, s[64:65]
	v_mad_u64_u32 v[108:109], s[0:1], v104, s13, v[0:1]
	ds_read_u16 v104, v108 offset:41216
	s_waitcnt lgkmcnt(0)
	v_lshlrev_b32_e32 v104, 16, v104
	v_mul_f32_e32 v104, 0xbfb8aa3b, v104
	v_exp_f32_e32 v104, v104
	s_nop 0
	v_add_f32_e32 v104, 1.0, v104
	s_nop 0
	v_rcp_f32_e32 v104, v104
	s_nop 0
	v_fma_f32 v104, v51, v104, v98
	v_cmp_gt_f32_e32 vcc, s29, v104
	v_cndmask_b32_e64 v107, v78, v77, s[64:65]
	s_nop 0
	v_cndmask_b32_e64 v105, 0, 32, vcc
	v_ldexp_f32 v105, v104, v105
	v_log_f32_e32 v105, v105
	s_nop 0
	v_mul_f32_e32 v106, 0x3f317217, v105
	v_fma_f32 v106, v105, s31, -v106
	v_fmac_f32_e32 v106, 0x3377d1cf, v105
	v_fmac_f32_e32 v106, 0x3f317217, v105
	v_cmp_lt_f32_e64 s[0:1], |v105|, s96
	s_nop 1
	v_cndmask_b32_e64 v105, v105, v106, s[0:1]
	v_cndmask_b32_e32 v106, 0, v187, vcc
	v_sub_f32_e32 v106, v105, v106
	ds_read_u16 v105, v108 offset:40960
	v_mad_u64_u32 v[108:109], s[0:1], v107, s13, v[0:1]
	ds_read_u16 v107, v108 offset:41216
	ds_read_u16 v108, v108 offset:40960
	s_waitcnt lgkmcnt(1)
	v_lshlrev_b32_e32 v107, 16, v107
	v_mul_f32_e32 v107, 0xbfb8aa3b, v107
	v_exp_f32_e32 v107, v107
	s_nop 0
	v_add_f32_e32 v107, 1.0, v107
	s_nop 0
	v_rcp_f32_e32 v107, v107
	s_nop 0
	v_fma_f32 v107, v51, v107, v98
	v_cmp_gt_f32_e32 vcc, s29, v107
	s_nop 1
	v_cndmask_b32_e64 v109, 0, 32, vcc
	v_ldexp_f32 v109, v107, v109
	v_log_f32_e32 v109, v109
	s_nop 0
	v_mul_f32_e32 v110, 0x3f317217, v109
	v_fma_f32 v110, v109, s31, -v110
	v_fmac_f32_e32 v110, 0x3377d1cf, v109
	v_fmac_f32_e32 v110, 0x3f317217, v109
	v_cmp_lt_f32_e64 s[0:1], |v109|, s96
	s_nop 1
	v_cndmask_b32_e64 v109, v109, v110, s[0:1]
	v_cndmask_b32_e32 v110, 0, v187, vcc
	v_sub_f32_e32 v109, v109, v110
	v_cndmask_b32_e64 v110, v80, v79, s[64:65]
	v_mad_u64_u32 v[114:115], s[0:1], v110, s13, v[0:1]
	ds_read_u16 v110, v114 offset:41216
	s_waitcnt lgkmcnt(0)
	v_lshlrev_b32_e32 v110, 16, v110
	v_mul_f32_e32 v110, 0xbfb8aa3b, v110
	v_exp_f32_e32 v110, v110
	s_nop 0
	v_add_f32_e32 v110, 1.0, v110
	s_nop 0
	v_rcp_f32_e32 v110, v110
	s_nop 0
	v_fma_f32 v110, v51, v110, v98
	v_cmp_gt_f32_e32 vcc, s29, v110
	v_cndmask_b32_e64 v113, v82, v81, s[64:65]
	s_nop 0
	v_cndmask_b32_e64 v111, 0, 32, vcc
	v_ldexp_f32 v111, v110, v111
	v_log_f32_e32 v111, v111
	s_nop 0
	v_mul_f32_e32 v112, 0x3f317217, v111
	v_fma_f32 v112, v111, s31, -v112
	v_fmac_f32_e32 v112, 0x3377d1cf, v111
	v_fmac_f32_e32 v112, 0x3f317217, v111
	v_cmp_lt_f32_e64 s[0:1], |v111|, s96
	s_nop 1
	v_cndmask_b32_e64 v111, v111, v112, s[0:1]
	v_cndmask_b32_e32 v112, 0, v187, vcc
	v_sub_f32_e32 v112, v111, v112
	ds_read_u16 v111, v114 offset:40960
	v_mad_u64_u32 v[114:115], s[0:1], v113, s13, v[0:1]
	ds_read_u16 v113, v114 offset:41216
	ds_read_u16 v114, v114 offset:40960
	s_waitcnt lgkmcnt(1)
	v_lshlrev_b32_e32 v113, 16, v113
	v_mul_f32_e32 v113, 0xbfb8aa3b, v113
	v_exp_f32_e32 v113, v113
	s_nop 0
	v_add_f32_e32 v113, 1.0, v113
	s_nop 0
	v_rcp_f32_e32 v113, v113
	s_nop 0
	v_fma_f32 v113, v51, v113, v98
	v_cmp_gt_f32_e32 vcc, s29, v113
	s_nop 1
	v_cndmask_b32_e64 v115, 0, 32, vcc
	v_ldexp_f32 v115, v113, v115
	v_log_f32_e32 v115, v115
	s_nop 0
	v_mul_f32_e32 v116, 0x3f317217, v115
	v_fma_f32 v116, v115, s31, -v116
	v_fmac_f32_e32 v116, 0x3377d1cf, v115
	v_fmac_f32_e32 v116, 0x3f317217, v115
	v_cmp_lt_f32_e64 s[0:1], |v115|, s96
	s_nop 1
	v_cndmask_b32_e64 v115, v115, v116, s[0:1]
	v_cndmask_b32_e32 v116, 0, v187, vcc
	v_sub_f32_e32 v115, v115, v116
	v_cndmask_b32_e64 v116, v84, v83, s[64:65]
	v_mad_u64_u32 v[120:121], s[0:1], v116, s13, v[0:1]
	ds_read_u16 v116, v120 offset:41216
	s_waitcnt lgkmcnt(0)
	v_lshlrev_b32_e32 v116, 16, v116
	v_mul_f32_e32 v116, 0xbfb8aa3b, v116
	v_exp_f32_e32 v116, v116
	s_nop 0
	v_add_f32_e32 v116, 1.0, v116
	s_nop 0
	v_rcp_f32_e32 v116, v116
	s_nop 0
	v_fma_f32 v116, v51, v116, v98
	v_cmp_gt_f32_e32 vcc, s29, v116
	v_cndmask_b32_e64 v119, v86, v85, s[64:65]
	s_nop 0
	v_cndmask_b32_e64 v117, 0, 32, vcc
	v_ldexp_f32 v117, v116, v117
	v_log_f32_e32 v117, v117
	s_nop 0
	v_mul_f32_e32 v118, 0x3f317217, v117
	v_fma_f32 v118, v117, s31, -v118
	v_fmac_f32_e32 v118, 0x3377d1cf, v117
	v_fmac_f32_e32 v118, 0x3f317217, v117
	v_cmp_lt_f32_e64 s[0:1], |v117|, s96
	s_nop 1
	v_cndmask_b32_e64 v117, v117, v118, s[0:1]
	v_cndmask_b32_e32 v118, 0, v187, vcc
	v_sub_f32_e32 v118, v117, v118
	ds_read_u16 v117, v120 offset:40960
	v_mad_u64_u32 v[120:121], s[0:1], v119, s13, v[0:1]
	ds_read_u16 v119, v120 offset:41216
	ds_read_u16 v120, v120 offset:40960
	s_waitcnt lgkmcnt(1)
	v_lshlrev_b32_e32 v119, 16, v119
	v_mul_f32_e32 v119, 0xbfb8aa3b, v119
	v_exp_f32_e32 v119, v119
	s_nop 0
	v_add_f32_e32 v119, 1.0, v119
	s_nop 0
	v_rcp_f32_e32 v119, v119
	s_nop 0
	v_fma_f32 v119, v51, v119, v98
	v_cmp_gt_f32_e32 vcc, s29, v119
	s_nop 1
	v_cndmask_b32_e64 v121, 0, 32, vcc
	v_ldexp_f32 v121, v119, v121
	v_log_f32_e32 v121, v121
	s_nop 0
	v_mul_f32_e32 v122, 0x3f317217, v121
	v_fma_f32 v122, v121, s31, -v122
	v_fmac_f32_e32 v122, 0x3377d1cf, v121
	v_fmac_f32_e32 v122, 0x3f317217, v121
	v_cmp_lt_f32_e64 s[0:1], |v121|, s96
	s_nop 1
	v_cndmask_b32_e64 v121, v121, v122, s[0:1]
	v_cndmask_b32_e32 v122, 0, v187, vcc
	v_sub_f32_e32 v121, v121, v122
	v_cndmask_b32_e64 v122, v88, v87, s[64:65]
	v_mad_u64_u32 v[128:129], s[0:1], v122, s13, v[0:1]
	ds_read_u16 v122, v128 offset:41216
	s_waitcnt lgkmcnt(0)
	v_lshlrev_b32_e32 v122, 16, v122
	v_mul_f32_e32 v122, 0xbfb8aa3b, v122
	v_exp_f32_e32 v122, v122
	s_nop 0
	v_add_f32_e32 v122, 1.0, v122
	s_nop 0
	v_rcp_f32_e32 v122, v122
	s_nop 0
	v_fma_f32 v122, v51, v122, v98
	v_cmp_gt_f32_e32 vcc, s29, v122
	v_cndmask_b32_e64 v127, v90, v89, s[64:65]
	s_nop 0
	v_cndmask_b32_e64 v123, 0, 32, vcc
	v_ldexp_f32 v123, v122, v123
	v_log_f32_e32 v123, v123
	s_nop 0
	v_mul_f32_e32 v126, 0x3f317217, v123
	v_fma_f32 v126, v123, s31, -v126
	v_fmac_f32_e32 v126, 0x3377d1cf, v123
	v_fmac_f32_e32 v126, 0x3f317217, v123
	v_cmp_lt_f32_e64 s[0:1], |v123|, s96
	s_nop 1
	v_cndmask_b32_e64 v123, v123, v126, s[0:1]
	v_cndmask_b32_e32 v126, 0, v187, vcc
	v_sub_f32_e32 v126, v123, v126
	ds_read_u16 v123, v128 offset:40960
	v_mad_u64_u32 v[128:129], s[0:1], v127, s13, v[0:1]
	ds_read_u16 v127, v128 offset:41216
	ds_read_u16 v128, v128 offset:40960
	s_waitcnt lgkmcnt(1)
	v_lshlrev_b32_e32 v127, 16, v127
	v_mul_f32_e32 v127, 0xbfb8aa3b, v127
	v_exp_f32_e32 v127, v127
	s_nop 0
	v_add_f32_e32 v127, 1.0, v127
	s_nop 0
	v_rcp_f32_e32 v127, v127
	s_nop 0
	v_fma_f32 v127, v51, v127, v98
	v_cmp_gt_f32_e32 vcc, s29, v127
	s_nop 1
	v_cndmask_b32_e64 v129, 0, 32, vcc
	v_ldexp_f32 v129, v127, v129
	v_log_f32_e32 v129, v129
	s_nop 0
	v_mul_f32_e32 v130, 0x3f317217, v129
	v_fma_f32 v130, v129, s31, -v130
	v_fmac_f32_e32 v130, 0x3377d1cf, v129
	v_fmac_f32_e32 v130, 0x3f317217, v129
	v_cmp_lt_f32_e64 s[0:1], |v129|, s96
	s_nop 1
	v_cndmask_b32_e64 v129, v129, v130, s[0:1]
	v_cndmask_b32_e32 v130, 0, v187, vcc
	v_sub_f32_e32 v129, v129, v130
	v_cndmask_b32_e64 v130, v92, v91, s[64:65]
	v_mad_u64_u32 v[134:135], s[0:1], v130, s13, v[0:1]
	ds_read_u16 v130, v134 offset:41216
	s_waitcnt lgkmcnt(0)
	v_lshlrev_b32_e32 v130, 16, v130
	v_mul_f32_e32 v130, 0xbfb8aa3b, v130
	v_exp_f32_e32 v130, v130
	s_nop 0
	v_add_f32_e32 v130, 1.0, v130
	s_nop 0
	v_rcp_f32_e32 v130, v130
	s_nop 0
	v_fma_f32 v130, v51, v130, v98
	v_cmp_gt_f32_e32 vcc, s29, v130
	v_cndmask_b32_e64 v133, v94, v93, s[64:65]
	s_nop 0
	v_cndmask_b32_e64 v131, 0, 32, vcc
	v_ldexp_f32 v131, v130, v131
	v_log_f32_e32 v131, v131
	s_nop 0
	v_mul_f32_e32 v132, 0x3f317217, v131
	v_fma_f32 v132, v131, s31, -v132
	v_fmac_f32_e32 v132, 0x3377d1cf, v131
	v_fmac_f32_e32 v132, 0x3f317217, v131
	v_cmp_lt_f32_e64 s[0:1], |v131|, s96
	s_nop 1
	v_cndmask_b32_e64 v131, v131, v132, s[0:1]
	v_cndmask_b32_e32 v132, 0, v187, vcc
	v_sub_f32_e32 v132, v131, v132
	ds_read_u16 v131, v134 offset:40960
	v_mad_u64_u32 v[134:135], s[0:1], v133, s13, v[0:1]
	ds_read_u16 v133, v134 offset:41216
	ds_read_u16 v134, v134 offset:40960
	s_waitcnt lgkmcnt(1)
	v_lshlrev_b32_e32 v133, 16, v133
	v_mul_f32_e32 v133, 0xbfb8aa3b, v133
	v_exp_f32_e32 v133, v133
	s_nop 0
	v_add_f32_e32 v133, 1.0, v133
	s_nop 0
	v_rcp_f32_e32 v133, v133
	s_nop 0
	v_fma_f32 v133, v51, v133, v98
	v_cmp_gt_f32_e32 vcc, s29, v133
	s_nop 1
	v_cndmask_b32_e64 v135, 0, 32, vcc
	v_ldexp_f32 v135, v133, v135
	v_log_f32_e32 v135, v135
	s_nop 0
	v_mul_f32_e32 v136, 0x3f317217, v135
	v_fma_f32 v136, v135, s31, -v136
	v_fmac_f32_e32 v136, 0x3377d1cf, v135
	v_fmac_f32_e32 v136, 0x3f317217, v135
	v_cmp_lt_f32_e64 s[0:1], |v135|, s96
	s_nop 1
	v_cndmask_b32_e64 v135, v135, v136, s[0:1]
	v_cndmask_b32_e32 v136, 0, v187, vcc
	v_sub_f32_e32 v135, v135, v136
	v_cndmask_b32_e64 v136, v96, v95, s[64:65]
	v_mad_u64_u32 v[136:137], s[0:1], v136, s13, v[0:1]
	ds_read_u16 v137, v136 offset:41216
	ds_read_u16 v136, v136 offset:40960
	s_waitcnt lgkmcnt(1)
	v_lshlrev_b32_e32 v137, 16, v137
	v_mul_f32_e32 v137, 0xbfb8aa3b, v137
	v_exp_f32_e32 v137, v137
	s_nop 0
	v_add_f32_e32 v137, 1.0, v137
	s_nop 0
	v_rcp_f32_e32 v137, v137
	s_nop 0
	v_fma_f32 v51, v51, v137, v98
	v_cmp_gt_f32_e32 vcc, s29, v51
	v_add_f32_e32 v140, v20, v19
	v_add_f32_e32 v141, v140, v29
	v_cndmask_b32_e64 v137, 0, 32, vcc
	v_ldexp_f32 v137, v51, v137
	v_log_f32_e32 v137, v137
	v_add_f32_e32 v50, v141, v50
	v_add_f32_e32 v142, v50, v103
	v_add_f32_e32 v143, v142, v106
	v_mul_f32_e32 v138, 0x3f317217, v137
	v_fma_f32 v138, v137, s31, -v138
	v_fmac_f32_e32 v138, 0x3377d1cf, v137
	v_fmac_f32_e32 v138, 0x3f317217, v137
	v_cmp_lt_f32_e64 s[0:1], |v137|, s96
	v_add_f32_e32 v19, v143, v109
	v_add_f32_e32 v139, v19, v112
	v_cndmask_b32_e64 v137, v137, v138, s[0:1]
	v_cndmask_b32_e32 v138, 0, v187, vcc
	v_sub_f32_e32 v137, v137, v138
	v_add_f32_e32 v138, v139, v115
	v_add_f32_e32 v118, v138, v118
	v_add_f32_e32 v112, v118, v121
	v_add_f32_e32 v115, v112, v126
	v_add_f32_e32 v106, v115, v129
	v_add_f32_e32 v109, v106, v132
	v_add_f32_e32 v29, v109, v135
	v_add_f32_e32 v103, v29, v137
	ds_write_b32 v97, v103 offset:36864
	s_waitcnt lgkmcnt(0)
	s_barrier
	s_cselect_b64 s[0:1], -1, 0
	s_and_b64 vcc, exec, s[0:1]
	s_cbranch_vccnz .LBB0_659
	s_and_b32 s72, s28, 0x180
	s_and_b32 s74, s10, 0x200
	s_or_b32 s74, s72, s74
	s_add_i32 s73, s72, 0xffffff00
	s_add_i32 s75, s74, 0x380
	s_bitset1_b32 s72, 9
	v_mov_b32_e32 v16, s73
	v_mov_b32_e32 v17, s75
	s_and_b32 s71, s33, 0xffffffc0
	v_cndmask_b32_e64 v2, v16, v17, s[46:47]
	v_mov_b32_e32 v98, s72
	v_cndmask_b32_e64 v12, v16, v17, s[50:51]
	s_add_i32 s71, s71, s4
	v_cndmask_b32_e64 v2, v2, v98, s[38:39]
	v_cndmask_b32_e64 v12, v12, v98, s[42:43]
	v_add_u32_e32 v2, v2, v52
	v_add_u32_e32 v3, s71, v53
	v_mov_b64_e32 v[10:11], s[16:17]
	v_add_u32_e32 v12, v12, v56
	v_add_u32_e32 v13, s71, v57
	v_mad_i64_i32 v[4:5], s[72:73], v3, s12, v[10:11]
	v_ashrrev_i32_e32 v3, 31, v2
	v_mad_i64_i32 v[14:15], s[72:73], v13, s12, v[10:11]
	v_ashrrev_i32_e32 v13, 31, v12
	v_lshl_add_u64 v[2:3], v[2:3], 1, v[4:5]
	v_cndmask_b32_e64 v4, v16, v17, s[48:49]
	v_lshl_add_u64 v[12:13], v[12:13], 1, v[14:15]
	v_cndmask_b32_e64 v14, v16, v17, s[52:53]
	v_cndmask_b32_e64 v4, v4, v98, s[40:41]
	v_cndmask_b32_e64 v14, v14, v98, s[44:45]
	v_add_u32_e32 v4, v4, v54
	v_add_u32_e32 v5, s71, v55
	v_add_u32_e32 v14, v14, v58
	v_add_u32_e32 v15, s71, v59
	v_mad_i64_i32 v[6:7], s[72:73], v5, s12, v[10:11]
	v_ashrrev_i32_e32 v5, 31, v4
	v_mad_i64_i32 v[10:11], s[72:73], v15, s12, v[10:11]
	v_ashrrev_i32_e32 v15, 31, v14
	v_or_b32_e32 v98, s74, v60
	v_readlane_b32 s6, v253, 21
	v_lshl_add_u64 v[6:7], v[4:5], 1, v[6:7]
	v_lshl_add_u64 v[14:15], v[14:15], 1, v[10:11]
	v_lshlrev_b32_e32 v98, 2, v98
	v_readlane_b32 s7, v253, 22
	global_load_dwordx4 v[2:5], v[2:3], off
	s_nop 0
	global_load_dwordx4 v[6:9], v[6:7], off
	s_nop 0
	global_load_dwordx4 v[10:13], v[12:13], off
	s_nop 0
	global_load_dwordx4 v[14:17], v[14:15], off
	v_readlane_b32 s74, v255, 2
	global_load_dword v98, v98, s[6:7]
	v_readlane_b32 s75, v255, 3

.LBB0_850:
	s_or_b64 exec, exec, s[0:1]
	s_movk_i32 s0, 0x100
	v_ashrrev_i32_e32 v202, 6, v196
	v_cmp_gt_u32_e64 s[36:37], s0, v196
	s_movk_i32 s0, 0xff
	v_and_b32_e32 v198, 3, v202
	s_waitcnt lgkmcnt(0)
	s_barrier
	v_cmp_lt_u32_e64 s[38:39], s0, v196
	s_lshl_b32 s0, s74, 6
	v_lshlrev_b32_e32 v195, 4, v198
	v_or_b32_e32 v191, s0, v192
	v_and_b32_e32 v200, 48, v196
	v_lshlrev_b32_e32 v118, 1, v192
	v_or_b32_e32 v197, v195, v192
	v_lshlrev_b32_e32 v190, 2, v191
	v_lshl_add_u32 v116, v192, 2, 0
	v_add_lshl_u32 v201, v192, s0, 2
	s_and_saveexec_b64 s[0:1], s[38:39]
	s_xor_b64 s[44:45], exec, s[0:1]
	s_cbranch_execz .LBB0_852
	v_readlane_b32 s80, v252, 18
	v_readlane_b32 s94, v252, 32
	v_readlane_b32 s95, v252, 33
	v_mul_u32_u24_e32 v0, 0x190, v197
	v_readlane_b32 s0, v254, 52
	v_readlane_b32 s81, v252, 19
	v_readlane_b32 s82, v252, 20
	v_add3_u32 v0, s0, v0, v200
	global_load_dword v76, v190, s[94:95]
	ds_read_b128 v[64:67], v0 offset:128
	v_readlane_b32 s83, v252, 21
	v_readlane_b32 s84, v252, 22
	v_readlane_b32 s85, v252, 23
	v_readlane_b32 s86, v252, 24
	v_readlane_b32 s87, v252, 25
	v_readlane_b32 s88, v252, 26
	v_readlane_b32 s89, v252, 27
	v_readlane_b32 s90, v252, 28
	v_readlane_b32 s91, v252, 29
	v_readlane_b32 s92, v252, 30
	v_readlane_b32 s93, v252, 31
	v_lshl_or_b32 v0, v194, 2, v195
	s_mov_b64 s[54:55], s[94:95]
	v_readlane_b32 s80, v252, 35
	v_mul_u32_u24_e32 v2, 0x300, v0
	v_readlane_b32 s81, v252, 36
	v_readlane_b32 s82, v252, 37
	v_readlane_b32 s83, v252, 38
	v_readlane_b32 s84, v252, 39
	v_readlane_b32 s85, v252, 40
	v_readlane_b32 s86, v252, 41
	v_readlane_b32 s87, v252, 42
	v_readlane_b32 s88, v252, 43
	v_readlane_b32 s89, v252, 44
	v_readlane_b32 s90, v252, 45
	v_readlane_b32 s91, v252, 46
	v_readlane_b32 s92, v252, 47
	v_readlane_b32 s93, v252, 48
	s_mov_b64 s[80:81], s[84:85]
	v_add_u32_e32 v77, 0xc400, v116
	v_add_u32_e32 v90, 0xcc00, v116
	v_add_u32_e32 v96, 0xd000, v116
	v_add3_u32 v85, 0, v2, v118
	s_waitcnt lgkmcnt(0)
	v_mfma_f32_16x16x32_bf16 v[72:75], v[64:67], v[24:27], 0
	s_mov_b64 s[82:83], s[86:87]
	global_load_dword v3, v190, s[80:81]
	global_load_dword v0, v190, s[82:83]
	ds_read2_b32 v[68:69], v77 offset0:192 offset1:208
	ds_read2_b32 v[80:81], v90 offset0:64 offset1:80
	ds_read2_b32 v[70:71], v96 offset0:192 offset1:208
	ds_read_u16 v2, v85 offset:128
	ds_read_u16 v82, v85 offset:160
	ds_read_u16 v79, v85 offset:896
	ds_read_u16 v107, v85 offset:1664
	ds_read_u16 v88, v85 offset:2432
	v_mfma_f32_16x16x32_bf16 v[112:115], v[64:67], v[48:51], 0
	s_waitcnt lgkmcnt(4)
	v_lshlrev_b32_e32 v78, 16, v2
	v_mov_b32_e32 v137, v81
	v_mov_b32_e32 v149, v71
	v_mov_b32_e32 v150, v81
	v_mov_b32_e32 v151, v80
	v_mov_b32_e32 v152, v71
	v_mov_b32_e32 v153, v70
	s_mov_b32 s4, 0x2b8cbccc
	v_readlane_b32 s94, v252, 49
	v_readlane_b32 s95, v252, 50
	s_mov_b64 s[84:85], s[88:89]
	s_mov_b64 s[86:87], s[90:91]
	s_mov_b64 s[88:89], s[92:93]
	s_waitcnt vmcnt(2)
	v_add_f32_e32 v2, v76, v72
	v_mul_f32_e32 v2, 0xbfb8aa3b, v2
	v_exp_f32_e32 v84, v2
	v_add_f32_e32 v2, v76, v73
	v_mul_f32_e32 v2, 0xbfb8aa3b, v2
	v_exp_f32_e32 v86, v2
	ds_read_u16 v2, v85 offset:3200
	s_waitcnt lgkmcnt(0)
	v_lshlrev_b32_e32 v83, 16, v2
	v_add_f32_e32 v2, v76, v74
	v_mul_f32_e32 v2, 0xbfb8aa3b, v2
	v_exp_f32_e32 v87, v2
	ds_read_u16 v2, v85 offset:3968
	v_pk_add_f32 v[86:87], v[86:87], 1.0 op_sel_hi:[1,0]
	s_waitcnt lgkmcnt(0)
	v_lshlrev_b32_e32 v89, 16, v2
	v_add_f32_e32 v2, v76, v75
	v_mul_f32_e32 v2, 0xbfb8aa3b, v2
	v_exp_f32_e32 v93, v2
	global_load_dword v2, v201, s[54:55] offset:64
	global_load_dword v101, v201, s[80:81] offset:64
	global_load_dword v102, v201, s[82:83] offset:64
	v_mfma_f32_16x16x32_bf16 v[72:75], v[64:67], v[32:35], 0
	ds_read_u16 v134, v85 offset:928
	ds_read_u16 v135, v85 offset:1696
	v_mfma_f32_16x16x32_bf16 v[64:67], v[64:67], v[56:59], 0
	s_waitcnt vmcnt(2)
	s_nop 3
	v_add_f32_e32 v72, v2, v72
	v_add_f32_e32 v73, v2, v73
	v_mul_f32_e32 v72, 0xbfb8aa3b, v72
	v_mul_f32_e32 v73, 0xbfb8aa3b, v73
	v_exp_f32_e32 v92, v72
	ds_read_u16 v72, v85 offset:2464
	v_exp_f32_e32 v108, v73
	ds_read_u16 v73, v85 offset:3232
	v_pk_add_f32 v[92:93], v[92:93], 1.0 op_sel_hi:[1,0]
	s_waitcnt lgkmcnt(0)
	v_lshlrev_b32_e32 v105, 16, v73
	v_add_f32_e32 v73, v2, v74
	v_add_f32_e32 v2, v2, v75
	v_mul_f32_e32 v73, 0xbfb8aa3b, v73
	v_mul_f32_e32 v2, 0xbfb8aa3b, v2
	v_exp_f32_e32 v109, v73
	ds_read_u16 v73, v85 offset:4000
	v_exp_f32_e32 v75, v2
	global_load_dword v76, v201, s[54:55] offset:128
	global_load_dword v91, v201, s[80:81] offset:128
	global_load_dword v2, v201, s[82:83] offset:128
	ds_read2_b32 v[94:95], v77 offset0:224 offset1:240
	ds_read2_b32 v[98:99], v90 offset0:96 offset1:112
	ds_read2_b32 v[96:97], v96 offset0:224 offset1:240
	ds_read_u16 v104, v85 offset:192
	ds_read_u16 v100, v85 offset:960
	ds_read_u16 v130, v85 offset:1728
	s_waitcnt lgkmcnt(4)
	v_mov_b32_e32 v128, v99
	v_mov_b32_e32 v129, v98
	v_mov_b32_e32 v116, v95
	v_mov_b32_e32 v117, v99
	s_waitcnt lgkmcnt(3)
	v_mov_b32_e32 v132, v97
	v_mov_b32_e32 v133, v96
	s_waitcnt lgkmcnt(1)
	v_lshlrev_b32_e32 v144, 16, v100
	s_waitcnt lgkmcnt(0)
	v_lshlrev_b32_e32 v145, 16, v130
	v_mov_b32_e32 v130, v94
	v_lshlrev_b32_e32 v73, 16, v73
	v_mov_b32_e32 v148, v96
	v_pk_add_f32 v[108:109], v[108:109], 1.0 op_sel_hi:[1,0]
	s_waitcnt vmcnt(2)
	v_add_f32_e32 v77, v76, v113
	v_mul_f32_e32 v77, 0xbfb8aa3b, v77
	v_add_f32_e32 v74, v76, v112
	ds_read_u16 v112, v85 offset:2496
	v_exp_f32_e32 v120, v77
	ds_read_u16 v77, v85 offset:3264
	v_mul_f32_e32 v74, 0xbfb8aa3b, v74
	v_exp_f32_e32 v74, v74
	s_waitcnt lgkmcnt(0)
	v_lshlrev_b32_e32 v119, 16, v77
	v_add_f32_e32 v77, v76, v114
	ds_read_u16 v114, v85 offset:4032
	global_load_dword v110, v201, s[54:55] offset:192
	global_load_dword v90, v201, s[80:81] offset:192
	global_load_dword v106, v201, s[82:83] offset:192
	v_add_f32_e32 v76, v76, v115
	v_mul_f32_e32 v77, 0xbfb8aa3b, v77
	v_mul_f32_e32 v76, 0xbfb8aa3b, v76
	v_exp_f32_e32 v121, v77
	v_exp_f32_e32 v77, v76
	ds_read_u16 v113, v85 offset:224
	ds_read_u16 v111, v85 offset:992
	ds_read_u16 v115, v85 offset:1760
	ds_read_u16 v118, v85 offset:2528
	ds_read_u16 v126, v85 offset:3296
	v_pk_add_f32 v[74:75], v[74:75], 1.0 op_sel_hi:[1,0]
	s_waitcnt lgkmcnt(3)
	v_lshlrev_b32_e32 v122, 16, v111
	s_waitcnt vmcnt(2)
	v_add_f32_e32 v64, v110, v64
	v_mul_f32_e32 v64, 0xbfb8aa3b, v64
	v_exp_f32_e32 v76, v64
	v_add_f32_e32 v64, v110, v65
	v_add_f32_e32 v65, v110, v66
	ds_read_u16 v66, v85 offset:4064
	v_mul_f32_e32 v64, 0xbfb8aa3b, v64
	v_mul_f32_e32 v65, 0xbfb8aa3b, v65
	v_exp_f32_e32 v64, v64
	v_exp_f32_e32 v65, v65
	s_waitcnt lgkmcnt(0)
	v_lshlrev_b32_e32 v103, 16, v66
	v_add_f32_e32 v66, v110, v67
	v_mul_f32_e32 v66, 0xbfb8aa3b, v66
	v_and_b32_e32 v67, 64, v179
	v_exp_f32_e32 v85, v66
	v_xor_b32_e32 v66, 1, v179
	v_add_u32_e32 v67, 64, v67
	v_cmp_lt_i32_e32 vcc, v66, v67
	v_pk_add_f32 v[64:65], v[64:65], 1.0 op_sel_hi:[1,0]
	v_lshlrev_b32_e32 v123, 16, v118
	v_cndmask_b32_e32 v66, v179, v66, vcc
	v_lshlrev_b32_e32 v143, 2, v66
	v_xor_b32_e32 v66, 2, v179
	v_cmp_lt_i32_e32 vcc, v66, v67
	v_pk_add_f32 v[76:77], v[76:77], 1.0 op_sel_hi:[1,0]
	v_lshlrev_b32_e32 v127, 16, v126
	v_cndmask_b32_e32 v66, v179, v66, vcc
	v_lshlrev_b32_e32 v142, 2, v66
	v_xor_b32_e32 v66, 4, v179
	v_cmp_lt_i32_e32 vcc, v66, v67
	v_mov_b32_e32 v126, v123
	v_pk_add_f32 v[84:85], v[84:85], 1.0 op_sel_hi:[1,0]
	v_cndmask_b32_e32 v66, v179, v66, vcc
	v_lshlrev_b32_e32 v141, 2, v66
	v_xor_b32_e32 v66, 8, v179
	v_cmp_lt_i32_e32 vcc, v66, v67
	s_nop 1
	v_cndmask_b32_e32 v66, v179, v66, vcc
	v_lshlrev_b32_e32 v140, 2, v66
	s_nop 0
	v_rcp_f32_e32 v111, v65
	s_nop 0
	s_nop 0
	v_lshlrev_b32_e32 v67, 16, v112
	v_lshlrev_b32_e32 v66, 16, v113
	v_rcp_f32_e32 v110, v64
	s_nop 0
	v_mov_b32_e32 v64, v95
	v_mov_b32_e32 v65, v94
	v_rcp_f32_e32 v113, v77
	s_nop 0
	s_nop 0
	v_mov_b32_e32 v118, v122
	v_rcp_f32_e32 v112, v76
	s_nop 0
	v_lshlrev_b32_e32 v77, 16, v114
	v_lshlrev_b32_e32 v76, 16, v115
	v_pk_mul_f32 v[114:115], v[128:129], v[118:119]
	v_mov_b32_e32 v136, v98
	v_pk_fma_f32 v[64:65], v[64:65], v[66:67], v[114:115]
	v_mov_b32_e32 v66, v97
	v_pk_fma_f32 v[138:139], v[132:133], v[76:77], v[64:65]
	v_pk_mul_f32 v[76:77], v[116:117], v[76:77] op_sel:[1,0] op_sel_hi:[0,0]
	v_mov_b32_e32 v64, v112
	v_mov_b32_e32 v65, v110
	v_pk_fma_f32 v[76:77], v[116:117], v[122:123], v[76:77]
	v_pk_add_f32 v[64:65], v[64:65], -1.0 op_sel_hi:[1,0]
	v_pk_fma_f32 v[128:129], v[66:67], v[126:127], v[76:77] op_sel_hi:[0,1,1]
	s_waitcnt vmcnt(0)
	v_pk_fma_f32 v[64:65], v[106:107], v[64:65], 1.0 op_sel_hi:[0,1,0]
	v_mov_b32_e32 v76, v138
	v_mov_b32_e32 v77, v128
	v_pk_mul_f32 v[76:77], v[64:65], v[76:77]
	v_pk_add_f32 v[64:65], v[120:121], 1.0 op_sel_hi:[1,0]
	v_pk_mul_f32 v[116:117], v[90:91], v[128:129] op_sel_hi:[0,1]
	v_mov_b32_e32 v131, v69
	v_pk_mul_f32 v[114:115], v[90:91], v[138:139]
	v_rcp_f32_e32 v121, v65
	s_nop 0
	s_nop 0
	v_rcp_f32_e32 v120, v64
	s_nop 0
	v_mov_b32_e32 v64, v121
	v_mov_b32_e32 v65, v113
	v_pk_add_f32 v[64:65], v[64:65], -1.0 op_sel_hi:[1,0]
	v_mov_b32_e32 v66, v145
	v_pk_fma_f32 v[146:147], v[2:3], v[64:65], 1.0 op_sel_hi:[0,1,0]
	v_lshlrev_b32_e32 v65, 16, v72
	v_lshlrev_b32_e32 v64, 16, v104
	v_mov_b32_e32 v118, v67
	v_pk_mul_f32 v[66:67], v[98:99], v[66:67] op_sel_hi:[0,1]
	v_pk_fma_f32 v[66:67], v[94:95], v[144:145], v[66:67] op_sel_hi:[0,1,1]
	v_rcp_f32_e32 v133, v75
	s_nop 0
	v_pk_fma_f32 v[66:67], v[96:97], v[118:119], v[66:67] op_sel_hi:[0,1,1]
	v_mov_b32_e32 v100, v91
	v_mov_b32_e32 v138, v67
	v_mov_b32_e32 v104, v144
	v_rcp_f32_e32 v132, v74
	s_nop 0
	v_pk_mul_f32 v[74:75], v[136:137], v[104:105]
	v_mov_b32_e32 v72, v145
	v_pk_fma_f32 v[74:75], v[130:131], v[64:65], v[74:75]
	v_mov_b32_e32 v104, v65
	v_pk_fma_f32 v[148:149], v[148:149], v[72:73], v[74:75]
	v_mov_b32_e32 v72, v132
	v_mov_b32_e32 v73, v120
	v_pk_add_f32 v[72:73], v[72:73], -1.0 op_sel_hi:[1,0]
	v_mov_b32_e32 v74, v148
	v_pk_fma_f32 v[72:73], v[2:3], v[72:73], 1.0 op_sel_hi:[0,1,0]
	v_mov_b32_e32 v2, v91
	v_pk_mul_f32 v[118:119], v[2:3], v[66:67] op_sel_hi:[0,1]
	v_mov_b32_e32 v75, v66
	v_pk_mul_f32 v[72:73], v[72:73], v[74:75]
	v_pk_mul_f32 v[74:75], v[146:147], v[138:139]
	v_rcp_f32_e32 v109, v109
	s_nop 0
	v_lshlrev_b32_e32 v138, 16, v82
	v_lshlrev_b32_e32 v139, 16, v88
	v_lshlrev_b32_e32 v67, 16, v135
	v_lshlrev_b32_e32 v66, 16, v134
	v_mov_b32_e32 v134, v109
	v_mov_b32_e32 v135, v133
	v_pk_add_f32 v[134:135], v[134:135], -1.0 op_sel_hi:[1,0]
	v_pk_fma_f32 v[144:145], v[102:103], v[134:135], 1.0 op_sel_hi:[0,1,0]
	v_rcp_f32_e32 v135, v93
	s_nop 0
	v_mov_b32_e32 v146, v69
	v_mov_b32_e32 v147, v68
	v_rcp_f32_e32 v108, v108
	s_nop 0
	v_rcp_f32_e32 v134, v92
	s_nop 0
	v_mov_b32_e32 v82, v66
	v_pk_mul_f32 v[92:93], v[150:151], v[82:83]
	v_mov_b32_e32 v88, v67
	v_pk_fma_f32 v[92:93], v[146:147], v[138:139], v[92:93]
	v_mov_b32_e32 v64, v67
	v_mov_b32_e32 v2, v101
	v_pk_fma_f32 v[92:93], v[152:153], v[88:89], v[92:93]
	v_mov_b32_e32 v82, v81
	v_pk_mul_f32 v[88:89], v[2:3], v[92:93]
	v_mov_b32_e32 v2, v69
	v_pk_mul_f32 v[64:65], v[82:83], v[64:65] op_sel_hi:[0,1]
	v_pk_fma_f32 v[64:65], v[2:3], v[66:67], v[64:65] op_sel_hi:[0,1,1]
	v_mov_b32_e32 v2, v71
	v_pk_fma_f32 v[66:67], v[2:3], v[104:105], v[64:65] op_sel_hi:[0,1,1]
	v_mov_b32_e32 v2, v101
	v_pk_mul_f32 v[130:131], v[100:101], v[148:149]
	v_pk_mul_f32 v[100:101], v[2:3], v[66:67] op_sel_hi:[0,1]
	v_mov_b32_e32 v148, v67
	v_mov_b32_e32 v65, v66
	v_pk_mul_f32 v[66:67], v[144:145], v[148:149]
	v_lshlrev_b32_e32 v144, 16, v79
	v_rcp_f32_e32 v87, v87
	s_nop 0
	v_mov_b32_e32 v146, v134
	v_mov_b32_e32 v147, v108
	v_pk_add_f32 v[146:147], v[146:147], -1.0 op_sel_hi:[1,0]
	v_rcp_f32_e32 v86, v86
	s_nop 0
	v_mov_b32_e32 v104, v87
	v_mov_b32_e32 v105, v135
	v_pk_fma_f32 v[146:147], v[102:103], v[146:147], 1.0 op_sel_hi:[0,1,0]
	v_mov_b32_e32 v64, v92
	v_pk_add_f32 v[104:105], v[104:105], -1.0 op_sel_hi:[1,0]
	v_pk_mul_f32 v[64:65], v[146:147], v[64:65]
	v_pk_fma_f32 v[146:147], v[0:1], v[104:105], 1.0 op_sel_hi:[0,1,0]
	v_rcp_f32_e32 v105, v85
	s_nop 0
	v_mov_b32_e32 v85, v86
	v_lshlrev_b32_e32 v145, 16, v107
	v_mov_b32_e32 v122, v144
	v_rcp_f32_e32 v104, v84
	s_nop 0
	v_mov_b32_e32 v84, v104
	v_mov_b32_e32 v69, v99
	v_mov_b32_e32 v79, v127
	v_pk_add_f32 v[84:85], v[84:85], -1.0 op_sel_hi:[1,0]
	v_pk_mul_f32 v[78:79], v[68:69], v[78:79]
	v_mov_b32_e32 v81, v95
	v_pk_fma_f32 v[148:149], v[0:1], v[84:85], 1.0 op_sel_hi:[0,1,0]
	v_mov_b32_e32 v84, v111
	v_mov_b32_e32 v85, v105
	v_mov_b32_e32 v71, v97
	v_pk_fma_f32 v[78:79], v[80:81], v[122:123], v[78:79]
	v_mov_b32_e32 v102, v145
	v_pk_add_f32 v[84:85], v[84:85], -1.0 op_sel_hi:[1,0]
	v_pk_fma_f32 v[94:95], v[70:71], v[102:103], v[78:79]
	v_pk_fma_f32 v[84:85], v[106:107], v[84:85], 1.0 op_sel_hi:[0,1,0]
	v_mov_b32_e32 v78, v129
	v_mov_b32_e32 v79, v95
	v_mov_b32_e32 v138, v145
	v_pk_mul_f32 v[78:79], v[84:85], v[78:79]
	v_mov_b32_e32 v84, v3
	v_mov_b32_e32 v85, v90
	v_pk_mul_f32 v[84:85], v[84:85], v[94:95]
	v_pk_mul_f32 v[80:81], v[80:81], v[138:139] op_sel_hi:[0,1]
	v_pk_fma_f32 v[68:69], v[68:69], v[144:145], v[80:81] op_sel_hi:[0,1,1]
	v_mov_b32_e32 v80, v84
	v_mov_b32_e32 v81, v131
	v_pk_mul_f32 v[80:81], v[80:81], v[80:81]
	v_mov_b32_e32 v136, v130
	v_mov_b32_e32 v137, v115
	v_pk_fma_f32 v[80:81], v[88:89], v[88:89], v[80:81]
	v_mov_b32_e32 v90, v114
	v_mov_b32_e32 v91, v85
	v_pk_fma_f32 v[80:81], v[136:137], v[136:137], v[80:81]
	v_mov_b32_e32 v82, v139
	v_pk_fma_f32 v[80:81], v[90:91], v[90:91], v[80:81]
	ds_bpermute_b32 v90, v143, v80
	ds_bpermute_b32 v91, v143, v81
	v_pk_fma_f32 v[70:71], v[70:71], v[82:83], v[68:69] op_sel_hi:[0,1,1]
	v_mov_b32_e32 v0, v3
	v_pk_mul_f32 v[2:3], v[0:1], v[70:71] op_sel_hi:[0,1]
	v_pk_mul_f32 v[82:83], v[100:101], v[100:101]
	s_waitcnt lgkmcnt(0)
	v_pk_add_f32 v[80:81], v[80:81], v[90:91]
	ds_bpermute_b32 v90, v142, v80
	ds_bpermute_b32 v91, v142, v81
	v_pk_fma_f32 v[82:83], v[2:3], v[2:3], v[82:83]
	v_mov_b32_e32 v92, v71
	v_pk_fma_f32 v[82:83], v[118:119], v[118:119], v[82:83]
	v_mov_b32_e32 v95, v70
	s_waitcnt lgkmcnt(0)
	v_pk_add_f32 v[80:81], v[80:81], v[90:91]
	ds_bpermute_b32 v90, v141, v80
	ds_bpermute_b32 v91, v141, v81
	v_pk_fma_f32 v[82:83], v[116:117], v[116:117], v[82:83]
	v_pk_mul_f32 v[70:71], v[146:147], v[92:93]
	v_pk_mul_f32 v[68:69], v[148:149], v[94:95]
	s_waitcnt lgkmcnt(0)
	v_pk_add_f32 v[80:81], v[80:81], v[90:91]
	ds_bpermute_b32 v90, v140, v80
	ds_bpermute_b32 v91, v140, v81
	s_waitcnt lgkmcnt(0)
	v_pk_add_f32 v[80:81], v[80:81], v[90:91]
	ds_bpermute_b32 v90, v143, v82
	ds_bpermute_b32 v91, v143, v83
	v_pk_add_f32 v[80:81], v[80:81], s[4:5] op_sel_hi:[1,0]
	s_waitcnt lgkmcnt(0)
	v_pk_add_f32 v[82:83], v[82:83], v[90:91]
	ds_bpermute_b32 v90, v142, v82
	ds_bpermute_b32 v91, v142, v83
	v_mul_f32_e32 v0, 0x4b800000, v80
	v_cmp_gt_f32_e64 s[0:1], s29, v80
	v_cmp_gt_f32_e32 vcc, s29, v81
	s_waitcnt lgkmcnt(0)
	v_pk_add_f32 v[82:83], v[82:83], v[90:91]
	ds_bpermute_b32 v90, v141, v82
	ds_bpermute_b32 v91, v141, v83
	v_cndmask_b32_e64 v0, v80, v0, s[0:1]
	v_rsq_f32_e32 v80, v0
	s_waitcnt lgkmcnt(0)
	v_pk_add_f32 v[82:83], v[82:83], v[90:91]
	ds_bpermute_b32 v90, v140, v82
	ds_bpermute_b32 v91, v140, v83
	s_waitcnt lgkmcnt(0)
	v_pk_add_f32 v[82:83], v[82:83], v[90:91]
	s_nop 0
	v_pk_add_f32 v[82:83], v[82:83], s[4:5] op_sel_hi:[1,0]
	s_mov_b32 s4, 0x45800000
	v_mul_f32_e32 v0, 0x4b800000, v82
	v_cmp_gt_f32_e64 s[42:43], s29, v82
	v_cmp_gt_f32_e64 s[40:41], s29, v83
	s_nop 0
	v_cndmask_b32_e64 v0, v82, v0, s[42:43]
	v_rsq_f32_e32 v82, v0
	v_mul_f32_e32 v0, 0x4b800000, v83
	v_cndmask_b32_e64 v0, v83, v0, s[40:41]
	v_rsq_f32_e32 v83, v0
	v_mul_f32_e32 v0, 0x4b800000, v81
	v_cndmask_b32_e32 v0, v81, v0, vcc
	v_rsq_f32_e32 v81, v0
	v_pk_mul_f32 v[90:91], v[82:83], s[4:5] op_sel_hi:[1,0]
	s_nop 0
	v_cndmask_b32_e64 v83, v83, v91, s[40:41]
	v_cndmask_b32_e64 v82, v82, v90, s[42:43]
	v_pk_mul_f32 v[90:91], v[80:81], s[4:5] op_sel_hi:[1,0]
	v_pk_mul_f32 v[140:141], v[2:3], v[82:83]
	v_cndmask_b32_e32 v81, v81, v91, vcc
	v_cndmask_b32_e64 v80, v80, v90, s[0:1]
	v_pk_mul_f32 v[128:129], v[88:89], v[80:81]
	v_pk_mul_f32 v[130:131], v[130:131], v[80:81]
	v_pk_mul_f32 v[126:127], v[84:85], v[80:81]
	v_pk_mul_f32 v[92:93], v[86:87], v[140:141]
	v_pk_mul_f32 v[90:91], v[134:135], v[128:129]
	v_pk_mul_f32 v[138:139], v[100:101], v[82:83]
	v_pk_mul_f32 v[86:87], v[132:133], v[130:131]
	v_pk_mul_f32 v[136:137], v[118:119], v[82:83]
	v_pk_mul_f32 v[132:133], v[114:115], v[80:81]
	v_pk_mul_f32 v[134:135], v[116:117], v[82:83]
	v_pk_mul_f32 v[88:89], v[108:109], v[138:139]
	v_pk_mul_f32 v[84:85], v[120:121], v[136:137]
	v_pk_mul_f32 v[80:81], v[112:113], v[132:133]
	v_pk_mul_f32 v[2:3], v[110:111], v[134:135]
	v_pk_mul_f32 v[82:83], v[104:105], v[126:127]
.LBB0_852:
	s_or_saveexec_b64 s[0:1], s[44:45]
	v_mov_b32_e32 v98, 0
	v_mov_b32_e32 v99, 0
	v_mov_b32_e32 v94, 0
	v_mov_b32_e32 v95, 0
	v_mov_b32_e32 v102, 0
	v_mov_b32_e32 v103, 0
	v_mov_b32_e32 v100, 0
	v_mov_b32_e32 v101, 0
	v_mov_b32_e32 v142, 0
	v_mov_b32_e32 v143, 0
	v_mov_b32_e32 v120, 0
	v_mov_b32_e32 v121, 0
	v_mov_b32_e32 v108, 0
	v_mov_b32_e32 v109, 0
	v_mov_b32_e32 v104, 0
	v_mov_b32_e32 v105, 0
	v_mov_b32_e32 v152, 0
	v_mov_b32_e32 v153, 0
	v_mov_b32_e32 v96, 0
	v_mov_b32_e32 v97, 0
	v_mov_b32_e32 v148, 0
	v_mov_b32_e32 v149, 0
	v_mov_b32_e32 v146, 0
	v_mov_b32_e32 v147, 0
	v_mov_b32_e32 v144, 0
	v_mov_b32_e32 v145, 0
	v_mov_b32_e32 v122, 0
	v_mov_b32_e32 v123, 0
	v_mov_b32_e32 v110, 0
	v_mov_b32_e32 v111, 0
	v_mov_b32_e32 v106, 0
	v_mov_b32_e32 v107, 0
	s_xor_b64 exec, exec, s[0:1]
	s_cbranch_execz .LBB0_854
	v_lshlrev_b32_e32 v66, 4, v202
	v_or_b32_e32 v0, v66, v192
	v_mul_lo_u32 v0, v0, s6
	v_lshlrev_b32_e32 v2, 4, v194
	v_readlane_b32 s4, v254, 52
	v_mov_b32_e32 v3, v1
	s_mul_i32 s10, s74, 0x3000
	v_add3_u32 v67, s4, v0, v2
	v_mul_u32_u24_e32 v0, 0x60, v192
	v_readlane_b32 s4, v253, 3
	v_lshlrev_b32_e32 v0, 1, v0
	v_readlane_b32 s5, v253, 4
	ds_read_b128 v[76:79], v67
	ds_read_b128 v[80:83], v67 offset:64
	v_lshl_add_u64 v[64:65], s[4:5], 0, v[0:1]
	v_lshl_add_u64 v[154:155], v[64:65], 0, v[2:3]
	v_lshl_add_u64 v[2:3], v[154:155], 0, s[10:11]
	ds_read_b128 v[92:95], v67 offset:192
	ds_read_b128 v[88:91], v67 offset:256
	ds_read_b128 v[84:87], v67 offset:320
	global_load_dwordx4 v[68:71], v[2:3], off
	global_load_dwordx4 v[96:99], v[2:3], off offset:64
	v_readlane_b32 s40, v252, 18
	v_readlane_b32 s44, v252, 22
	v_readlane_b32 s45, v252, 23
	v_readlane_b32 s46, v252, 24
	v_readlane_b32 s47, v252, 25
	v_readlane_b32 s48, v252, 26
	v_readlane_b32 s49, v252, 27
	v_readlane_b32 s50, v252, 28
	v_readlane_b32 s51, v252, 29
	s_mov_b64 s[44:45], s[48:49]
	s_mov_b64 s[46:47], s[50:51]
	s_waitcnt lgkmcnt(4)
	v_mfma_f32_16x16x32_bf16 v[72:75], v[76:79], v[24:27], 0
	v_lshl_or_b32 v0, v194, 2, v66
	v_mul_lo_u32 v0, v0, s13
	v_add_u32_e32 v132, 0xc800, v116
	s_waitcnt lgkmcnt(3)
	v_mfma_f32_16x16x32_bf16 v[64:67], v[80:83], v[20:23], 0
	v_add_u32_e32 v133, 0xcc00, v116
	v_add_u32_e32 v136, 0xd400, v116
	v_add_u32_e32 v137, 0xc400, v116
	v_add_u32_e32 v146, 0xd000, v116
	v_add3_u32 v119, 0, v0, v118
	s_mov_b32 s6, 0xbf1b4598
	v_readlane_b32 s41, v252, 19
	v_readlane_b32 s42, v252, 20
	v_readlane_b32 s43, v252, 21
	v_readlane_b32 s52, v252, 30
	v_readlane_b32 s53, v252, 31
	v_readlane_b32 s54, v252, 32
	v_readlane_b32 s55, v252, 33
	s_waitcnt vmcnt(1) lgkmcnt(2)
	v_mfma_f32_16x16x32_bf16 v[68:71], v[92:95], v[68:71], 0
	s_waitcnt vmcnt(0) lgkmcnt(1)
	v_mfma_f32_16x16x32_bf16 v[68:71], v[88:91], v[96:99], v[68:71]
	global_load_dwordx4 v[96:99], v[2:3], off offset:128
	global_load_dword v108, v190, s[46:47]
	global_load_dword v110, v190, s[46:47] offset:2048
	ds_read2_b32 v[100:101], v132 offset1:16
	ds_read2_b32 v[102:103], v133 offset0:128 offset1:144
	ds_read2_b32 v[130:131], v136 offset1:16
	ds_read2_b32 v[112:113], v137 offset0:128 offset1:144
	ds_read2_b32 v[114:115], v133 offset1:16
	ds_read2_b32 v[116:117], v146 offset0:128 offset1:144
	s_waitcnt vmcnt(2) lgkmcnt(6)
	v_mfma_f32_16x16x32_bf16 v[68:71], v[84:87], v[96:99], v[68:71]
	s_waitcnt vmcnt(1)
	v_add_f32_e32 v2, v72, v108
	v_mul_f32_e32 v2, 0xbfb8aa3b, v2
	v_exp_f32_e32 v97, v2
	s_waitcnt vmcnt(0)
	v_add_f32_e32 v2, v64, v110
	v_mul_f32_e32 v2, 0xbfb8aa3b, v2
	v_exp_f32_e32 v99, v2
	ds_read_u16 v0, v119
	ds_read_u16 v2, v119 offset:32
	s_waitcnt lgkmcnt(3)
	v_mov_b32_e32 v210, v115
	v_mov_b32_e32 v211, v114
	v_mov_b32_e32 v208, v113
	s_waitcnt lgkmcnt(1)
	v_lshlrev_b32_e32 v118, 16, v0
	v_add_f32_e32 v0, v73, v108
	v_mul_f32_e32 v0, 0xbfb8aa3b, v0
	v_exp_f32_e32 v96, v0
	v_mov_b32_e32 v209, v112
	v_pk_add_f32 v[72:73], v[96:97], 1.0 op_sel_hi:[1,0]
	s_nop 0
	s_nop 0
	v_rcp_f32_e32 v73, v73
	s_nop 0
	s_nop 0
	v_rcp_f32_e32 v72, v72
	s_nop 0
	v_add_f32_e32 v0, v65, v110
	v_mul_f32_e32 v0, 0xbfb8aa3b, v0
	v_exp_f32_e32 v98, v0
	v_pk_mul_f32 v[104:105], v[72:73], s[6:7] op_sel_hi:[1,0]
	v_pk_add_f32 v[64:65], v[98:99], 1.0 op_sel_hi:[1,0]
	s_nop 0
	s_nop 0
	v_rcp_f32_e32 v65, v65
	s_nop 0
	s_nop 0
	v_rcp_f32_e32 v64, v64
	s_nop 0
	ds_read_u16 v0, v119 offset:256
	ds_read_u16 v3, v119 offset:1024
	v_pk_mul_f32 v[106:107], v[64:65], s[6:7] op_sel_hi:[1,0]
	s_waitcnt lgkmcnt(1)
	v_lshlrev_b32_e32 v64, 16, v0
	ds_read_u16 v0, v119 offset:2560
	ds_read_u16 v65, v119 offset:1792
	s_waitcnt lgkmcnt(1)
	v_lshlrev_b32_e32 v73, 16, v0
	s_waitcnt lgkmcnt(0)
	v_lshlrev_b32_e32 v72, 16, v65
	v_lshlrev_b32_e32 v65, 16, v3
	v_mov_b32_e32 v96, v65
	v_mov_b32_e32 v97, v72
	v_pk_mul_f32 v[96:97], v[102:103], v[96:97] op_sel_hi:[0,1]
	v_add_f32_e32 v0, v74, v108
	v_pk_fma_f32 v[64:65], v[100:101], v[64:65], v[96:97] op_sel_hi:[0,1,1]
	v_mul_f32_e32 v0, 0xbfb8aa3b, v0
	v_pk_fma_f32 v[126:127], v[130:131], v[72:73], v[64:65] op_sel_hi:[0,1,1]
	v_exp_f32_e32 v65, v0
	v_add_f32_e32 v0, v66, v110
	v_mul_f32_e32 v0, 0xbfb8aa3b, v0
	v_exp_f32_e32 v97, v0
	ds_read_u16 v0, v119 offset:3072
	s_waitcnt lgkmcnt(0)
	v_lshlrev_b32_e32 v3, 16, v0
	v_add_f32_e32 v0, v75, v108
	v_mul_f32_e32 v0, 0xbfb8aa3b, v0
	v_exp_f32_e32 v64, v0
	s_nop 0
	v_pk_add_f32 v[64:65], v[64:65], 1.0 op_sel_hi:[1,0]
	s_nop 0
	s_nop 0
	v_rcp_f32_e32 v65, v65
	s_nop 0
	s_nop 0
	v_rcp_f32_e32 v64, v64
	s_nop 0
	v_add_f32_e32 v0, v67, v110
	v_mul_f32_e32 v0, 0xbfb8aa3b, v0
	v_exp_f32_e32 v96, v0
	v_pk_mul_f32 v[108:109], v[64:65], s[6:7] op_sel_hi:[1,0]
	v_pk_add_f32 v[64:65], v[96:97], 1.0 op_sel_hi:[1,0]
	s_nop 0
	v_mfma_f32_16x16x32_bf16 v[96:99], v[76:79], v[32:35], 0
	v_rcp_f32_e32 v65, v65
	s_nop 0
	s_nop 0
	v_rcp_f32_e32 v64, v64
	s_nop 0
	v_pk_mul_f32 v[110:111], v[64:65], s[6:7] op_sel_hi:[1,0]
	ds_read_u16 v0, v119 offset:4096
	ds_read_u16 v64, v119 offset:3328
	s_waitcnt lgkmcnt(1)
	v_lshlrev_b32_e32 v65, 16, v0
	ds_read_u16 v0, v119 offset:3840
	s_waitcnt lgkmcnt(1)
	v_lshlrev_b32_e32 v64, 16, v64
	v_pk_mov_b32 v[66:67], v[72:73], v[64:65] op_sel:[1,0]
	s_waitcnt lgkmcnt(0)
	v_lshlrev_b32_e32 v153, 16, v0
	v_or_b32_e32 v0, 16, v191
	v_sub_u32_e32 v0, v0, v192
	v_mul_u32_u24_e32 v0, 0x60, v0
	v_pk_mul_f32 v[66:67], v[102:103], v[66:67] op_sel_hi:[0,1]
	v_lshlrev_b32_e32 v0, 1, v0
	v_pk_fma_f32 v[66:67], v[100:101], v[72:73], v[66:67] op_sel_hi:[0,1,1]
	v_lshl_add_u64 v[134:135], v[154:155], 0, v[0:1]
	v_pk_fma_f32 v[128:129], v[130:131], v[64:65], v[66:67] op_sel_hi:[0,1,1]
	global_load_dwordx4 v[64:67], v[134:135], off
	global_load_dwordx4 v[120:123], v[134:135], off offset:64
	v_mfma_f32_16x16x32_bf16 v[72:75], v[80:83], v[28:31], 0
	s_waitcnt vmcnt(1)
	v_mfma_f32_16x16x32_bf16 v[64:67], v[92:95], v[64:67], 0
	s_waitcnt vmcnt(0)
	v_mfma_f32_16x16x32_bf16 v[64:67], v[88:91], v[120:123], v[64:67]
	global_load_dwordx4 v[120:123], v[134:135], off offset:128
	global_load_dword v130, v201, s[46:47] offset:64
	global_load_dword v138, v201, s[46:47] offset:2112
	s_waitcnt vmcnt(1)
	v_add_f32_e32 v0, v96, v130
	v_mul_f32_e32 v0, 0xbfb8aa3b, v0
	v_mfma_f32_16x16x32_bf16 v[64:67], v[84:87], v[120:123], v[64:67]
	v_exp_f32_e32 v121, v0
	s_waitcnt vmcnt(0)
	v_add_f32_e32 v0, v72, v138
	v_mul_f32_e32 v0, 0xbfb8aa3b, v0
	v_exp_f32_e32 v123, v0
	v_add_f32_e32 v0, v97, v130
	v_mul_f32_e32 v0, 0xbfb8aa3b, v0
	v_exp_f32_e32 v120, v0
	s_nop 0
	v_pk_add_f32 v[96:97], v[120:121], 1.0 op_sel_hi:[1,0]
	s_nop 0
	s_nop 0
	v_rcp_f32_e32 v97, v97
	s_nop 0
	s_nop 0
	v_rcp_f32_e32 v96, v96
	s_nop 0
	v_add_f32_e32 v0, v73, v138
	v_mul_f32_e32 v0, 0xbfb8aa3b, v0
	v_exp_f32_e32 v122, v0
	v_pk_mul_f32 v[120:121], v[96:97], s[6:7] op_sel_hi:[1,0]
	v_pk_add_f32 v[72:73], v[122:123], 1.0 op_sel_hi:[1,0]
	s_nop 0
	s_nop 0
	v_rcp_f32_e32 v73, v73
	s_nop 0
	s_nop 0
	v_rcp_f32_e32 v72, v72
	s_nop 0
	v_pk_mul_f32 v[122:123], v[72:73], s[6:7] op_sel_hi:[1,0]
	ds_read_u16 v0, v119 offset:288
	ds_read_u16 v73, v119 offset:1056
	v_mov_b32_e32 v100, v103
	s_waitcnt lgkmcnt(1)
	v_lshlrev_b32_e32 v72, 16, v0
	ds_read_u16 v0, v119 offset:2592
	ds_read_u16 v96, v119 offset:1824
	s_waitcnt lgkmcnt(2)
	v_lshlrev_b32_e32 v73, 16, v73
	v_mov_b32_e32 v134, v73
	s_waitcnt lgkmcnt(1)
	v_lshlrev_b32_e32 v97, 16, v0
	s_waitcnt lgkmcnt(0)
	v_lshlrev_b32_e32 v96, 16, v96
	v_mov_b32_e32 v135, v96
	v_mov_b32_e32 v0, v101
	v_pk_mul_f32 v[102:103], v[100:101], v[134:135] op_sel_hi:[0,1]
	v_pk_fma_f32 v[72:73], v[0:1], v[72:73], v[102:103] op_sel_hi:[0,1,1]
	v_mov_b32_e32 v102, v131
	v_pk_fma_f32 v[134:135], v[102:103], v[96:97], v[72:73] op_sel_hi:[0,1,1]
	v_add_f32_e32 v72, v98, v130
	v_mul_f32_e32 v72, 0xbfb8aa3b, v72
	v_exp_f32_e32 v73, v72
	v_add_f32_e32 v72, v74, v138
	v_mul_f32_e32 v72, 0xbfb8aa3b, v72
	v_exp_f32_e32 v131, v72
	ds_read_u16 v72, v119 offset:3104
	s_waitcnt lgkmcnt(0)
	v_lshlrev_b32_e32 v167, 16, v72
	v_add_f32_e32 v72, v99, v130
	v_mul_f32_e32 v72, 0xbfb8aa3b, v72
	v_exp_f32_e32 v72, v72
	s_nop 0
	v_pk_add_f32 v[72:73], v[72:73], 1.0 op_sel_hi:[1,0]
	s_nop 0
	s_nop 0
	v_rcp_f32_e32 v73, v73
	s_nop 0
	v_div_scale_f32 v74, s[4:5], v72, v72, 1.0
	v_rcp_f32_e32 v98, v74
	s_nop 0
	v_fma_f32 v99, -v74, v98, 1.0
	v_fmac_f32_e32 v98, v99, v98
	v_div_scale_f32 v99, vcc, 1.0, v72, 1.0
	v_mul_f32_e32 v101, v99, v98
	v_fma_f32 v103, -v74, v101, v99
	v_fmac_f32_e32 v101, v103, v98
	v_fma_f32 v74, -v74, v101, v99
	v_div_fmas_f32 v74, v74, v98, v101
	v_div_fixup_f32 v72, v74, v72, 1.0
	v_pk_mul_f32 v[142:143], v[72:73], s[6:7] op_sel_hi:[1,0]
	v_add_f32_e32 v72, v75, v138
	v_mul_f32_e32 v72, 0xbfb8aa3b, v72
	v_exp_f32_e32 v130, v72
	s_nop 0
	v_pk_add_f32 v[72:73], v[130:131], 1.0 op_sel_hi:[1,0]
	s_nop 0
	s_nop 0
	v_rcp_f32_e32 v73, v73
	s_nop 0
	v_div_scale_f32 v74, s[4:5], v72, v72, 1.0
	v_rcp_f32_e32 v75, v74
	s_nop 0
	v_fma_f32 v98, -v74, v75, 1.0
	v_fmac_f32_e32 v75, v98, v75
	v_div_scale_f32 v98, vcc, 1.0, v72, 1.0
	v_mul_f32_e32 v99, v98, v75
	v_fma_f32 v101, -v74, v99, v98
	v_fmac_f32_e32 v99, v101, v75
	v_fma_f32 v74, -v74, v99, v98
	v_div_fmas_f32 v74, v74, v75, v99
	v_div_fixup_f32 v72, v74, v72, 1.0
	v_pk_mul_f32 v[144:145], v[72:73], s[6:7] op_sel_hi:[1,0]
	ds_read_u16 v73, v119 offset:4128
	ds_read_u16 v72, v119 offset:3360
	s_waitcnt lgkmcnt(1)
	v_lshlrev_b32_e32 v73, 16, v73
	s_waitcnt lgkmcnt(0)
	v_lshlrev_b32_e32 v72, 16, v72
	v_pk_mov_b32 v[74:75], v[96:97], v[72:73] op_sel:[1,0]
	s_nop 0
	v_pk_mul_f32 v[74:75], v[100:101], v[74:75] op_sel_hi:[0,1]
	v_pk_fma_f32 v[74:75], v[0:1], v[96:97], v[74:75] op_sel_hi:[0,1,1]
	ds_read_u16 v0, v119 offset:3872
	v_pk_fma_f32 v[130:131], v[102:103], v[72:73], v[74:75] op_sel_hi:[0,1,1]
	v_mfma_f32_16x16x32_bf16 v[96:99], v[80:83], v[36:39], 0
	s_waitcnt lgkmcnt(0)
	v_lshlrev_b32_e32 v169, 16, v0
	v_or_b32_e32 v0, 32, v191
	v_sub_u32_e32 v0, v0, v192
	v_mul_u32_u24_e32 v0, 0x60, v0
	v_lshlrev_b32_e32 v0, 1, v0
	v_lshl_add_u64 v[148:149], v[154:155], 0, v[0:1]
	global_load_dwordx4 v[72:75], v[148:149], off
	global_load_dwordx4 v[138:141], v[148:149], off offset:64
	s_waitcnt vmcnt(1)
	v_mfma_f32_16x16x32_bf16 v[72:75], v[92:95], v[72:75], 0
	s_waitcnt vmcnt(0)
	v_mfma_f32_16x16x32_bf16 v[72:75], v[88:91], v[138:141], v[72:75]
	global_load_dwordx4 v[138:141], v[148:149], off offset:128
	global_load_dword v0, v201, s[46:47] offset:128
	global_load_dword v152, v201, s[46:47] offset:2176
	s_waitcnt vmcnt(0)
	v_add_f32_e32 v96, v96, v152
	v_mfma_f32_16x16x32_bf16 v[100:103], v[76:79], v[48:51], 0
	v_mul_f32_e32 v96, 0xbfb8aa3b, v96
	v_exp_f32_e32 v147, v96
	v_mfma_f32_16x16x32_bf16 v[72:75], v[84:87], v[138:141], v[72:75]
	ds_read2_b32 v[158:159], v132 offset0:32 offset1:48
	ds_read2_b32 v[164:165], v133 offset0:160 offset1:176
	ds_read2_b32 v[156:157], v136 offset0:32 offset1:48
	ds_read2_b32 v[140:141], v137 offset0:160 offset1:176
	ds_read2_b32 v[138:139], v133 offset0:32 offset1:48
	ds_read2_b32 v[136:137], v146 offset0:160 offset1:176
	v_add_f32_e32 v100, v100, v0
	v_add_f32_e32 v96, v101, v0
	v_mul_f32_e32 v100, 0xbfb8aa3b, v100
	v_mul_f32_e32 v96, 0xbfb8aa3b, v96
	v_exp_f32_e32 v133, v100
	v_exp_f32_e32 v132, v96
	v_mfma_f32_16x16x32_bf16 v[80:83], v[80:83], v[60:63], 0
	s_waitcnt lgkmcnt(4)
	v_mov_b32_e32 v176, v165
	s_waitcnt lgkmcnt(3)
	v_mov_b32_e32 v178, v157
	v_pk_add_f32 v[100:101], v[132:133], 1.0 op_sel_hi:[1,0]
	s_nop 0
	s_nop 0
	v_rcp_f32_e32 v101, v101
	s_nop 0
	s_nop 0
	v_rcp_f32_e32 v100, v100
	s_nop 0
	v_add_f32_e32 v96, v97, v152
	v_mul_f32_e32 v96, 0xbfb8aa3b, v96
	v_exp_f32_e32 v146, v96
	v_pk_mul_f32 v[100:101], v[100:101], s[6:7] op_sel_hi:[1,0]
	v_pk_add_f32 v[96:97], v[146:147], 1.0 op_sel_hi:[1,0]
	s_nop 0
	s_nop 0
	v_rcp_f32_e32 v97, v97
	s_nop 0
	s_nop 0
	v_rcp_f32_e32 v96, v96
	s_nop 0
	v_pk_mul_f32 v[146:147], v[96:97], s[6:7] op_sel_hi:[1,0]
	ds_read_u16 v96, v119 offset:320
	ds_read_u16 v97, v119 offset:1088
	ds_read_u16 v133, v119 offset:2624
	ds_read_u16 v132, v119 offset:1856
	s_waitcnt lgkmcnt(3)
	v_lshlrev_b32_e32 v96, 16, v96
	s_waitcnt lgkmcnt(2)
	v_lshlrev_b32_e32 v97, 16, v97
	s_waitcnt lgkmcnt(0)
	v_lshlrev_b32_e32 v132, 16, v132
	v_mov_b32_e32 v148, v97
	v_mov_b32_e32 v149, v132
	v_pk_mul_f32 v[148:149], v[164:165], v[148:149] op_sel_hi:[0,1]
	v_lshlrev_b32_e32 v133, 16, v133
	v_pk_fma_f32 v[96:97], v[158:159], v[96:97], v[148:149] op_sel_hi:[0,1,1]
	v_pk_fma_f32 v[150:151], v[156:157], v[132:133], v[96:97] op_sel_hi:[0,1,1]
	v_add_f32_e32 v96, v102, v0
	v_mul_f32_e32 v96, 0xbfb8aa3b, v96
	v_exp_f32_e32 v97, v96
	v_add_f32_e32 v96, v98, v152
	v_mul_f32_e32 v96, 0xbfb8aa3b, v96
	v_exp_f32_e32 v149, v96
	ds_read_u16 v96, v119 offset:3136
	v_add_f32_e32 v0, v103, v0
	v_mul_f32_e32 v0, 0xbfb8aa3b, v0
	s_waitcnt lgkmcnt(0)
	v_lshlrev_b32_e32 v171, 16, v96
	v_exp_f32_e32 v96, v0
	s_nop 0
	v_pk_add_f32 v[96:97], v[96:97], 1.0 op_sel_hi:[1,0]
	s_nop 0
	s_nop 0
	v_rcp_f32_e32 v97, v97
	s_nop 0
	s_nop 0
	v_rcp_f32_e32 v96, v96
	s_nop 0
	v_add_f32_e32 v0, v99, v152
	v_mul_f32_e32 v0, 0xbfb8aa3b, v0
	v_exp_f32_e32 v148, v0
	v_pk_mul_f32 v[102:103], v[96:97], s[6:7] op_sel_hi:[1,0]
	v_pk_add_f32 v[96:97], v[148:149], 1.0 op_sel_hi:[1,0]
	s_nop 0
	s_nop 0
	v_rcp_f32_e32 v97, v97
	s_nop 0
	s_nop 0
	v_rcp_f32_e32 v96, v96
	s_nop 0
	v_pk_mul_f32 v[148:149], v[96:97], s[6:7] op_sel_hi:[1,0]
	ds_read_u16 v0, v119 offset:4160
	ds_read_u16 v96, v119 offset:3392
	s_waitcnt lgkmcnt(1)
	v_lshlrev_b32_e32 v97, 16, v0
	ds_read_u16 v0, v119 offset:3904
	s_waitcnt lgkmcnt(1)
	v_lshlrev_b32_e32 v96, 16, v96
	v_pk_mov_b32 v[98:99], v[132:133], v[96:97] op_sel:[1,0]
	s_waitcnt lgkmcnt(0)
	v_lshlrev_b32_e32 v173, 16, v0
	v_or_b32_e32 v0, 48, v191
	v_sub_u32_e32 v0, v0, v192
	v_mul_u32_u24_e32 v0, 0x60, v0
	v_pk_mul_f32 v[98:99], v[164:165], v[98:99] op_sel_hi:[0,1]
	v_lshlrev_b32_e32 v0, 1, v0
	v_pk_fma_f32 v[98:99], v[158:159], v[132:133], v[98:99] op_sel_hi:[0,1,1]
	v_lshl_add_u64 v[154:155], v[154:155], 0, v[0:1]
	v_pk_fma_f32 v[132:133], v[156:157], v[96:97], v[98:99] op_sel_hi:[0,1,1]
	v_mfma_f32_16x16x32_bf16 v[96:99], v[76:79], v[56:59], 0
	global_load_dwordx4 v[76:79], v[154:155], off
	s_waitcnt vmcnt(0)
	v_mfma_f32_16x16x32_bf16 v[76:79], v[92:95], v[76:79], 0
	global_load_dwordx4 v[92:95], v[154:155], off offset:64
	s_waitcnt vmcnt(0)
	v_mfma_f32_16x16x32_bf16 v[76:79], v[88:91], v[92:95], v[76:79]
	global_load_dwordx4 v[88:91], v[154:155], off offset:128
	global_load_dword v180, v201, s[46:47] offset:192
	global_load_dword v203, v201, s[46:47] offset:2240
	s_waitcnt vmcnt(1)
	v_add_f32_e32 v0, v96, v180
	v_mul_f32_e32 v0, 0xbfb8aa3b, v0
	v_mfma_f32_16x16x32_bf16 v[76:79], v[84:87], v[88:91], v[76:79]
	v_exp_f32_e32 v85, v0
	s_waitcnt vmcnt(0)
	v_add_f32_e32 v0, v80, v203
	v_mul_f32_e32 v0, 0xbfb8aa3b, v0
	v_exp_f32_e32 v87, v0
	v_add_f32_e32 v0, v97, v180
	v_mul_f32_e32 v0, 0xbfb8aa3b, v0
	v_exp_f32_e32 v84, v0
	v_lshlrev_b32_e32 v90, 16, v2
	v_pk_add_f32 v[84:85], v[84:85], 1.0 op_sel_hi:[1,0]
	s_nop 0
	s_nop 0
	v_rcp_f32_e32 v85, v85
	s_nop 0
	s_nop 0
	v_rcp_f32_e32 v84, v84
	s_nop 0
	v_add_f32_e32 v0, v81, v203
	v_mul_f32_e32 v0, 0xbfb8aa3b, v0
	v_exp_f32_e32 v86, v0
	v_pk_mul_f32 v[94:95], v[84:85], s[6:7] op_sel_hi:[1,0]
	v_pk_add_f32 v[80:81], v[86:87], 1.0 op_sel_hi:[1,0]
	s_nop 0
	s_nop 0
	v_rcp_f32_e32 v81, v81
	s_nop 0
	s_nop 0
	v_rcp_f32_e32 v80, v80
	s_nop 0
	v_pk_mul_f32 v[96:97], v[80:81], s[6:7] op_sel_hi:[1,0]
	ds_read_u16 v0, v119 offset:352
	ds_read_u16 v81, v119 offset:1120
	s_waitcnt lgkmcnt(1)
	v_lshlrev_b32_e32 v80, 16, v0
	ds_read_u16 v0, v119 offset:2656
	ds_read_u16 v84, v119 offset:1888
	s_waitcnt lgkmcnt(2)
	v_lshlrev_b32_e32 v81, 16, v81
	s_waitcnt lgkmcnt(1)
	v_lshlrev_b32_e32 v175, 16, v0
	s_waitcnt lgkmcnt(0)
	v_lshlrev_b32_e32 v174, 16, v84
	v_mov_b32_e32 v84, v81
	v_mov_b32_e32 v85, v174
	v_mov_b32_e32 v0, v159
	v_pk_mul_f32 v[84:85], v[176:177], v[84:85] op_sel_hi:[0,1]
	v_pk_fma_f32 v[80:81], v[0:1], v[80:81], v[84:85] op_sel_hi:[0,1,1]
	v_pk_fma_f32 v[154:155], v[178:179], v[174:175], v[80:81] op_sel_hi:[0,1,1]
	v_add_f32_e32 v80, v98, v180
	v_mul_f32_e32 v80, 0xbfb8aa3b, v80
	v_exp_f32_e32 v205, v80
	v_add_f32_e32 v80, v82, v203
	v_mul_f32_e32 v80, 0xbfb8aa3b, v80
	v_exp_f32_e32 v181, v80
	ds_read_u16 v80, v119 offset:864
	ds_read_u16 v81, v119 offset:1632
	v_mov_b32_e32 v98, v115
	s_waitcnt lgkmcnt(1)
	v_lshlrev_b32_e32 v206, 16, v80
	ds_read_u16 v80, v119 offset:3168
	ds_read_u16 v82, v119 offset:2400
	s_waitcnt lgkmcnt(2)
	v_lshlrev_b32_e32 v207, 16, v81
	v_mov_b32_e32 v156, v207
	v_mov_b32_e32 v172, v207
	s_waitcnt lgkmcnt(1)
	v_lshlrev_b32_e32 v159, 16, v80
	s_waitcnt lgkmcnt(0)
	v_lshlrev_b32_e32 v157, 16, v82
	ds_read_u16 v80, v119 offset:96
	ds_read_u16 v81, v119 offset:2368
	ds_read_u16 v82, v119 offset:832
	ds_read_u16 v84, v119 offset:1600
	v_mov_b32_e32 v158, v157
	s_waitcnt lgkmcnt(3)
	v_lshlrev_b32_e32 v80, 16, v80
	s_waitcnt lgkmcnt(2)
	v_lshlrev_b32_e32 v81, 16, v81
	s_waitcnt lgkmcnt(0)
	v_lshlrev_b32_e32 v85, 16, v84
	v_lshlrev_b32_e32 v84, 16, v82
	ds_read_u16 v82, v119 offset:64
	ds_read_u16 v86, v119 offset:2336
	v_mov_b32_e32 v168, v85
	v_mov_b32_e32 v170, v81
	s_waitcnt lgkmcnt(0)
	v_lshlrev_b32_e32 v87, 16, v86
	v_lshlrev_b32_e32 v86, 16, v82
	ds_read_u16 v82, v119 offset:800
	ds_read_u16 v88, v119 offset:1568
	v_mov_b32_e32 v166, v87
	s_waitcnt lgkmcnt(0)
	v_lshlrev_b32_e32 v89, 16, v88
	v_lshlrev_b32_e32 v88, 16, v82
	ds_read_u16 v82, v119 offset:2304
	v_mov_b32_e32 v152, v89
	s_waitcnt lgkmcnt(0)
	v_lshlrev_b32_e32 v91, 16, v82
	ds_read_u16 v2, v119 offset:768
	ds_read_u16 v82, v119 offset:1536
	v_mov_b32_e32 v93, v91
	s_waitcnt lgkmcnt(1)
	v_lshlrev_b32_e32 v164, 16, v2
	s_waitcnt lgkmcnt(0)
	v_lshlrev_b32_e32 v165, 16, v82
	v_mov_b32_e32 v92, v165
	v_pk_mul_f32 v[92:93], v[114:115], v[92:93] op_sel_hi:[0,1]
	v_mov_b32_e32 v2, v91
	v_pk_fma_f32 v[92:93], v[112:113], v[164:165], v[92:93] op_sel_hi:[0,1,1]
	v_pk_fma_f32 v[92:93], v[116:117], v[2:3], v[92:93] op_sel_hi:[0,1,1]
	v_mov_b32_e32 v2, v88
	v_pk_mul_f32 v[2:3], v[210:211], v[2:3]
	v_mov_b32_e32 v82, v117
	v_pk_fma_f32 v[2:3], v[208:209], v[90:91], v[2:3]
	v_mov_b32_e32 v90, v117
	v_mov_b32_e32 v91, v116
	v_pk_fma_f32 v[90:91], v[90:91], v[152:153], v[2:3]
	v_mov_b32_e32 v153, v87
	v_mov_b32_e32 v2, v113
	v_pk_mul_f32 v[152:153], v[98:99], v[152:153] op_sel_hi:[0,1]
	v_pk_fma_f32 v[2:3], v[2:3], v[88:89], v[152:153] op_sel_hi:[0,1,1]
	v_pk_fma_f32 v[88:89], v[82:83], v[166:167], v[2:3] op_sel_hi:[0,1,1]
	v_mov_b32_e32 v152, v138
	v_mov_b32_e32 v153, v115
	v_mov_b32_e32 v166, v84
	v_mov_b32_e32 v2, v140
	v_mov_b32_e32 v3, v113
	v_pk_mul_f32 v[152:153], v[152:153], v[166:167]
	v_mov_b32_e32 v82, v139
	v_pk_fma_f32 v[2:3], v[2:3], v[86:87], v[152:153]
	v_mov_b32_e32 v86, v136
	v_mov_b32_e32 v87, v117
	v_pk_fma_f32 v[86:87], v[86:87], v[168:169], v[2:3]
	v_mov_b32_e32 v2, v85
	v_mov_b32_e32 v3, v81
	v_pk_mul_f32 v[2:3], v[138:139], v[2:3] op_sel_hi:[0,1]
	v_pk_fma_f32 v[2:3], v[140:141], v[84:85], v[2:3] op_sel_hi:[0,1,1]
	v_pk_fma_f32 v[84:85], v[136:137], v[170:171], v[2:3] op_sel_hi:[0,1,1]
	v_mov_b32_e32 v152, v139
	v_mov_b32_e32 v153, v138
	v_mov_b32_e32 v170, v206
	v_mov_b32_e32 v2, v141
	v_mov_b32_e32 v3, v140
	v_pk_mul_f32 v[152:153], v[152:153], v[170:171]
	v_mov_b32_e32 v140, v127
	v_pk_fma_f32 v[2:3], v[2:3], v[80:81], v[152:153]
	v_mov_b32_e32 v80, v137
	v_mov_b32_e32 v81, v136
	v_pk_fma_f32 v[80:81], v[80:81], v[172:173], v[2:3]
	v_mov_b32_e32 v2, v141
	v_pk_mul_f32 v[152:153], v[82:83], v[156:157] op_sel_hi:[0,1]
	v_pk_fma_f32 v[2:3], v[2:3], v[206:207], v[152:153] op_sel_hi:[0,1,1]
	v_mov_b32_e32 v82, v137
	v_pk_fma_f32 v[2:3], v[82:83], v[158:159], v[2:3] op_sel_hi:[0,1,1]
	v_add_f32_e32 v82, v99, v180
	v_mul_f32_e32 v82, 0xbfb8aa3b, v82
	v_exp_f32_e32 v204, v82
	v_mov_b32_e32 v156, v164
	v_pk_add_f32 v[98:99], v[204:205], 1.0 op_sel_hi:[1,0]
	s_nop 0
	s_nop 0
	v_rcp_f32_e32 v99, v99
	s_nop 0
	s_nop 0
	v_rcp_f32_e32 v98, v98
	s_nop 0
	v_add_f32_e32 v82, v83, v203
	v_mul_f32_e32 v82, 0xbfb8aa3b, v82
	v_exp_f32_e32 v180, v82
	v_pk_mul_f32 v[98:99], v[98:99], s[6:7] op_sel_hi:[1,0]
	v_pk_add_f32 v[82:83], v[180:181], 1.0 op_sel_hi:[1,0]
	s_nop 0
	s_nop 0
	v_rcp_f32_e32 v83, v83
	s_nop 0
	s_nop 0
	v_rcp_f32_e32 v82, v82
	s_nop 0
	v_pk_mul_f32 v[152:153], v[82:83], s[6:7] op_sel_hi:[1,0]
	ds_read_u16 v82, v119 offset:4192
	ds_read_u16 v83, v119 offset:3424
	v_mov_b32_e32 v113, v139
	v_mov_b32_e32 v115, v141
	v_mov_b32_e32 v117, v137
	s_waitcnt lgkmcnt(1)
	v_lshlrev_b32_e32 v167, 16, v82
	s_waitcnt lgkmcnt(0)
	v_lshlrev_b32_e32 v166, 16, v83
	v_pk_mov_b32 v[82:83], v[174:175], v[166:167] op_sel:[1,0]
	v_mov_b32_e32 v141, v128
	v_pk_mul_f32 v[82:83], v[176:177], v[82:83] op_sel_hi:[0,1]
	v_pk_fma_f32 v[82:83], v[0:1], v[174:175], v[82:83] op_sel_hi:[0,1,1]
	ds_read_u16 v0, v119 offset:3936
	v_mov_b32_e32 v119, v159
	v_pk_mul_f32 v[112:113], v[112:113], v[118:119]
	v_pk_fma_f32 v[166:167], v[178:179], v[166:167], v[82:83] op_sel_hi:[0,1,1]
	v_pk_fma_f32 v[112:113], v[114:115], v[156:157], v[112:113]
	s_waitcnt lgkmcnt(0)
	v_lshlrev_b32_e32 v83, 16, v0
	v_mov_b32_e32 v82, v165
	v_pk_fma_f32 v[82:83], v[116:117], v[82:83], v[112:113]
	v_mov_b32_e32 v128, v134
	v_mov_b32_e32 v138, v135
	v_mov_b32_e32 v139, v130
	v_mov_b32_e32 v130, v150
	v_mov_b32_e32 v136, v151
	v_mov_b32_e32 v137, v132
	v_mov_b32_e32 v132, v154
	v_mov_b32_e32 v134, v155
	v_mov_b32_e32 v135, v166
	v_mov_b32_e32 v127, v167

.LBB0_1106:
	ds_read2st64_b32 v[28:29], v120 offset1:1
	v_and_b32_e32 v0, 64, v179
	v_add_u32_e32 v0, 64, v0
	v_xor_b32_e32 v26, 1, v179
	v_cmp_lt_i32_e32 vcc, v26, v0
	s_waitcnt lgkmcnt(0)
	v_pk_mul_f32 v[48:49], v[28:29], v[28:29]
	s_lshl_b32 s10, s4, 1
	v_cndmask_b32_e32 v26, v179, v26, vcc
	v_lshlrev_b32_e32 v47, 2, v26
	v_add_f32_e32 v48, v48, v49
	ds_bpermute_b32 v49, v47, v48
	v_xor_b32_e32 v26, 2, v179
	v_cmp_lt_i32_e32 vcc, v26, v0
	v_lshlrev_b64 v[42:43], 11, v[42:43]
	s_waitcnt lgkmcnt(0)
	v_add_f32_e32 v48, v48, v49
	v_cndmask_b32_e32 v26, v179, v26, vcc
	v_lshlrev_b32_e32 v46, 2, v26
	ds_bpermute_b32 v49, v46, v48
	v_xor_b32_e32 v26, 4, v179
	v_cmp_lt_i32_e32 vcc, v26, v0
	s_waitcnt lgkmcnt(0)
	v_add_f32_e32 v48, v48, v49
	v_cndmask_b32_e32 v26, v179, v26, vcc
	v_lshlrev_b32_e32 v45, 2, v26
	ds_bpermute_b32 v49, v45, v48
	v_xor_b32_e32 v26, 8, v179
	v_cmp_lt_i32_e32 vcc, v26, v0
	s_waitcnt lgkmcnt(0)
	v_add_f32_e32 v48, v48, v49
	v_cndmask_b32_e32 v26, v179, v26, vcc
	v_lshlrev_b32_e32 v44, 2, v26
	ds_bpermute_b32 v49, v44, v48
	v_xor_b32_e32 v26, 16, v179
	v_cmp_lt_i32_e32 vcc, v26, v0
	s_waitcnt lgkmcnt(0)
	v_add_f32_e32 v48, v48, v49
	v_cndmask_b32_e32 v26, v179, v26, vcc
	v_lshlrev_b32_e32 v41, 2, v26
	ds_bpermute_b32 v49, v41, v48
	v_xor_b32_e32 v26, 32, v179
	v_cmp_lt_i32_e32 vcc, v26, v0
	s_waitcnt lgkmcnt(0)
	v_add_f32_e32 v48, v48, v49
	v_cndmask_b32_e32 v0, v179, v26, vcc
	v_lshlrev_b32_e32 v0, 2, v0
	ds_bpermute_b32 v49, v0, v48
	v_lshl_add_u64 v[26:27], v[36:37], 0, s[10:11]
	v_lshl_add_u64 v[42:43], v[26:27], 0, v[42:43]
	s_waitcnt lgkmcnt(0)
	v_add_f32_e32 v48, v48, v49
	v_fmamk_f32 v48, v48, 0x3c000000, v184
	v_cmp_gt_f32_e32 vcc, s29, v48
	v_mul_f32_e32 v49, 0x4b800000, v48
	s_nop 0
	v_cndmask_b32_e32 v48, v48, v49, vcc
	v_rsq_f32_e32 v48, v48
	s_nop 0
	v_mul_f32_e32 v49, 0x45800000, v48
	v_cndmask_b32_e32 v48, v48, v49, vcc
	s_waitcnt vmcnt(15)
	v_lshlrev_b32_e32 v49, 16, v150
	v_mul_f32_e32 v50, 0xbfb8aa3b, v49
	v_exp_f32_e32 v50, v50
	v_mul_f32_e32 v28, v28, v48
	v_mul_f32_e32 v28, v137, v28
	v_add_f32_e32 v50, 1.0, v50
	s_nop 0
	v_rcp_f32_e32 v50, v50
	s_nop 0
	v_mul_f32_e32 v49, v50, v49
	v_mul_f32_e32 v28, v49, v28
	v_cvt_pk_bf16_f32 v28, v28, v28
	global_store_short v[42:43], v28, off
	v_mul_f32_e32 v28, v29, v48
	s_waitcnt vmcnt(15)
	v_lshlrev_b32_e32 v29, 16, v151
	v_mul_f32_e32 v48, 0xbfb8aa3b, v29
	v_exp_f32_e32 v48, v48
	v_mul_f32_e32 v28, v159, v28
	v_add_f32_e32 v48, 1.0, v48
	s_nop 0
	v_rcp_f32_e32 v48, v48
	s_nop 0
	v_mul_f32_e32 v29, v48, v29
	v_mul_f32_e32 v28, v29, v28
	v_cvt_pk_bf16_f32 v28, v28, v28
	global_store_short v[42:43], v28, off offset:128
	ds_read2st64_b32 v[42:43], v122 offset1:1
	v_add_u32_e32 v28, s93, v121
	s_waitcnt lgkmcnt(0)
	v_pk_mul_f32 v[48:49], v[42:43], v[42:43]
	s_nop 0
	v_add_f32_e32 v29, v48, v49
	ds_bpermute_b32 v48, v47, v29
	s_waitcnt lgkmcnt(0)
	v_add_f32_e32 v29, v29, v48
	ds_bpermute_b32 v48, v46, v29
	s_waitcnt lgkmcnt(0)
	v_add_f32_e32 v29, v29, v48
	ds_bpermute_b32 v48, v45, v29
	s_waitcnt lgkmcnt(0)
	v_add_f32_e32 v29, v29, v48
	ds_bpermute_b32 v48, v44, v29
	s_waitcnt lgkmcnt(0)
	v_add_f32_e32 v29, v29, v48
	ds_bpermute_b32 v48, v41, v29
	s_waitcnt lgkmcnt(0)
	v_add_f32_e32 v29, v29, v48
	ds_bpermute_b32 v48, v0, v29
	s_waitcnt lgkmcnt(0)
	v_add_f32_e32 v29, v29, v48
	v_fmamk_f32 v29, v29, 0x3c000000, v184
	v_cmp_gt_f32_e32 vcc, s29, v29
	v_mul_f32_e32 v48, 0x4b800000, v29
	s_nop 0
	v_cndmask_b32_e32 v29, v29, v48, vcc
	v_rsq_f32_e32 v29, v29
	s_nop 0
	v_mul_f32_e32 v48, 0x45800000, v29
	v_cndmask_b32_e32 v48, v29, v48, vcc
	v_mul_f32_e32 v29, v42, v48
	s_waitcnt vmcnt(15)
	v_lshlrev_b32_e32 v42, 16, v152
	v_mul_f32_e32 v49, 0xbfb8aa3b, v42
	v_exp_f32_e32 v49, v49
	v_mul_f32_e32 v29, v137, v29
	v_add_f32_e32 v49, 1.0, v49
	s_nop 0
	v_rcp_f32_e32 v49, v49
	s_nop 0
	v_mul_f32_e32 v42, v49, v42
	v_mul_f32_e32 v29, v42, v29
	v_cvt_pk_bf16_f32 v42, v29, v29
	v_ashrrev_i32_e32 v29, 31, v28
	v_lshlrev_b64 v[28:29], 11, v[28:29]
	v_lshl_add_u64 v[28:29], v[26:27], 0, v[28:29]
	global_store_short v[28:29], v42, off
	v_mul_f32_e32 v42, v43, v48
	s_waitcnt vmcnt(15)
	v_lshlrev_b32_e32 v43, 16, v153
	v_mul_f32_e32 v48, 0xbfb8aa3b, v43
	v_exp_f32_e32 v48, v48
	v_mul_f32_e32 v42, v159, v42
	v_add_f32_e32 v48, 1.0, v48
	s_nop 0
	v_rcp_f32_e32 v48, v48
	s_nop 0
	v_mul_f32_e32 v43, v48, v43
	v_mul_f32_e32 v42, v43, v42
	v_cvt_pk_bf16_f32 v42, v42, v42
	global_store_short v[28:29], v42, off offset:128
	ds_read2st64_b32 v[42:43], v126 offset1:1
	v_add_u32_e32 v28, s93, v123
	s_waitcnt lgkmcnt(0)
	v_pk_mul_f32 v[48:49], v[42:43], v[42:43]
	s_nop 0
	v_add_f32_e32 v29, v48, v49
	ds_bpermute_b32 v48, v47, v29
	s_waitcnt lgkmcnt(0)
	v_add_f32_e32 v29, v29, v48
	ds_bpermute_b32 v48, v46, v29
	s_waitcnt lgkmcnt(0)
	v_add_f32_e32 v29, v29, v48
	ds_bpermute_b32 v48, v45, v29
	s_waitcnt lgkmcnt(0)
	v_add_f32_e32 v29, v29, v48
	ds_bpermute_b32 v48, v44, v29
	s_waitcnt lgkmcnt(0)
	v_add_f32_e32 v29, v29, v48
	ds_bpermute_b32 v48, v41, v29
	s_waitcnt lgkmcnt(0)
	v_add_f32_e32 v29, v29, v48
	ds_bpermute_b32 v48, v0, v29
	s_waitcnt lgkmcnt(0)
	v_add_f32_e32 v29, v29, v48
	v_fmamk_f32 v29, v29, 0x3c000000, v184
	v_cmp_gt_f32_e32 vcc, s29, v29
	v_mul_f32_e32 v48, 0x4b800000, v29
	s_nop 0
	v_cndmask_b32_e32 v29, v29, v48, vcc
	v_rsq_f32_e32 v29, v29
	s_nop 0
	v_mul_f32_e32 v48, 0x45800000, v29
	v_cndmask_b32_e32 v48, v29, v48, vcc
	v_mul_f32_e32 v29, v42, v48
	s_waitcnt vmcnt(15)
	v_lshlrev_b32_e32 v42, 16, v154
	v_mul_f32_e32 v49, 0xbfb8aa3b, v42
	v_exp_f32_e32 v49, v49
	v_mul_f32_e32 v29, v137, v29
	v_add_f32_e32 v49, 1.0, v49
	s_nop 0
	v_rcp_f32_e32 v49, v49
	s_nop 0
	v_mul_f32_e32 v42, v49, v42
	v_mul_f32_e32 v29, v42, v29
	v_cvt_pk_bf16_f32 v42, v29, v29
	v_ashrrev_i32_e32 v29, 31, v28
	v_lshlrev_b64 v[28:29], 11, v[28:29]
	v_lshl_add_u64 v[28:29], v[26:27], 0, v[28:29]
	global_store_short v[28:29], v42, off
	v_mul_f32_e32 v42, v43, v48
	s_waitcnt vmcnt(15)
	v_lshlrev_b32_e32 v43, 16, v155
	v_mul_f32_e32 v48, 0xbfb8aa3b, v43
	v_exp_f32_e32 v48, v48
	v_mul_f32_e32 v42, v159, v42
	v_add_f32_e32 v48, 1.0, v48
	s_nop 0
	v_rcp_f32_e32 v48, v48
	s_nop 0
	v_mul_f32_e32 v43, v48, v43
	v_mul_f32_e32 v42, v43, v42
	v_cvt_pk_bf16_f32 v42, v42, v42
	global_store_short v[28:29], v42, off offset:128
	ds_read2st64_b32 v[42:43], v128 offset1:1
	v_add_u32_e32 v28, s93, v127
	s_waitcnt lgkmcnt(0)
	v_pk_mul_f32 v[48:49], v[42:43], v[42:43]
	s_nop 0
	v_add_f32_e32 v29, v48, v49
	ds_bpermute_b32 v48, v47, v29
	s_waitcnt lgkmcnt(0)
	v_add_f32_e32 v29, v29, v48
	ds_bpermute_b32 v48, v46, v29
	s_waitcnt lgkmcnt(0)
	v_add_f32_e32 v29, v29, v48
	ds_bpermute_b32 v48, v45, v29
	s_waitcnt lgkmcnt(0)
	v_add_f32_e32 v29, v29, v48
	ds_bpermute_b32 v48, v44, v29
	s_waitcnt lgkmcnt(0)
	v_add_f32_e32 v29, v29, v48
	ds_bpermute_b32 v48, v41, v29
	s_waitcnt lgkmcnt(0)
	v_add_f32_e32 v29, v29, v48
	ds_bpermute_b32 v48, v0, v29
	s_waitcnt lgkmcnt(0)
	v_add_f32_e32 v29, v29, v48
	v_fmamk_f32 v29, v29, 0x3c000000, v184
	v_cmp_gt_f32_e32 vcc, s29, v29
	v_mul_f32_e32 v48, 0x4b800000, v29
	s_nop 0
	v_cndmask_b32_e32 v29, v29, v48, vcc
	v_rsq_f32_e32 v29, v29
	s_nop 0
	v_mul_f32_e32 v48, 0x45800000, v29
	v_cndmask_b32_e32 v48, v29, v48, vcc
	v_mul_f32_e32 v29, v42, v48
	s_waitcnt vmcnt(15)
	v_lshlrev_b32_e32 v42, 16, v156
	v_mul_f32_e32 v49, 0xbfb8aa3b, v42
	v_exp_f32_e32 v49, v49
	v_mul_f32_e32 v29, v137, v29
	v_add_f32_e32 v49, 1.0, v49
	s_nop 0
	v_rcp_f32_e32 v49, v49
	s_nop 0
	v_mul_f32_e32 v42, v49, v42
	v_mul_f32_e32 v29, v42, v29
	v_cvt_pk_bf16_f32 v42, v29, v29
	v_ashrrev_i32_e32 v29, 31, v28
	v_lshlrev_b64 v[28:29], 11, v[28:29]
	v_lshl_add_u64 v[28:29], v[26:27], 0, v[28:29]
	global_store_short v[28:29], v42, off
	v_mul_f32_e32 v42, v43, v48
	s_waitcnt vmcnt(15)
	v_lshlrev_b32_e32 v43, 16, v157
	v_mul_f32_e32 v48, 0xbfb8aa3b, v43
	v_exp_f32_e32 v48, v48
	v_mul_f32_e32 v42, v159, v42
	v_add_f32_e32 v48, 1.0, v48
	s_nop 0
	v_rcp_f32_e32 v48, v48
	s_nop 0
	v_mul_f32_e32 v43, v48, v43
	v_mul_f32_e32 v42, v43, v42
	v_cvt_pk_bf16_f32 v42, v42, v42
	global_store_short v[28:29], v42, off offset:128
	ds_read2st64_b32 v[42:43], v130 offset1:1
	v_add_u32_e32 v28, s93, v129
	s_waitcnt lgkmcnt(0)
	v_pk_mul_f32 v[48:49], v[42:43], v[42:43]
	s_nop 0
	v_add_f32_e32 v29, v48, v49
	ds_bpermute_b32 v48, v47, v29
	s_waitcnt lgkmcnt(0)
	v_add_f32_e32 v29, v29, v48
	ds_bpermute_b32 v48, v46, v29
	s_waitcnt lgkmcnt(0)
	v_add_f32_e32 v29, v29, v48
	ds_bpermute_b32 v48, v45, v29
	s_waitcnt lgkmcnt(0)
	v_add_f32_e32 v29, v29, v48
	ds_bpermute_b32 v48, v44, v29
	s_waitcnt lgkmcnt(0)
	v_add_f32_e32 v29, v29, v48
	ds_bpermute_b32 v48, v41, v29
	s_waitcnt lgkmcnt(0)
	v_add_f32_e32 v29, v29, v48
	ds_bpermute_b32 v48, v0, v29
	s_waitcnt lgkmcnt(0)
	v_add_f32_e32 v29, v29, v48
	v_fmamk_f32 v29, v29, 0x3c000000, v184
	v_cmp_gt_f32_e32 vcc, s29, v29
	v_mul_f32_e32 v48, 0x4b800000, v29
	s_nop 0
	v_cndmask_b32_e32 v29, v29, v48, vcc
	v_rsq_f32_e32 v29, v29
	s_nop 0
	v_mul_f32_e32 v48, 0x45800000, v29
	v_cndmask_b32_e32 v48, v29, v48, vcc
	v_mul_f32_e32 v29, v42, v48
	s_waitcnt vmcnt(15)
	v_lshlrev_b32_e32 v42, 16, v158
	v_mul_f32_e32 v49, 0xbfb8aa3b, v42
	v_exp_f32_e32 v49, v49
	v_mul_f32_e32 v29, v137, v29
	v_add_f32_e32 v49, 1.0, v49
	s_nop 0
	v_rcp_f32_e32 v49, v49
	s_nop 0
	v_mul_f32_e32 v42, v49, v42
	v_mul_f32_e32 v29, v42, v29
	v_cvt_pk_bf16_f32 v42, v29, v29
	v_ashrrev_i32_e32 v29, 31, v28
	v_lshlrev_b64 v[28:29], 11, v[28:29]
	v_lshl_add_u64 v[28:29], v[26:27], 0, v[28:29]
	global_store_short v[28:29], v42, off
	v_mul_f32_e32 v42, v43, v48
	s_waitcnt vmcnt(15)
	v_lshlrev_b32_e32 v43, 16, v164
	v_mul_f32_e32 v48, 0xbfb8aa3b, v43
	v_exp_f32_e32 v48, v48
	v_mul_f32_e32 v42, v159, v42
	v_add_f32_e32 v48, 1.0, v48
	s_nop 0
	v_rcp_f32_e32 v48, v48
	s_nop 0
	v_mul_f32_e32 v43, v48, v43
	v_mul_f32_e32 v42, v43, v42
	v_cvt_pk_bf16_f32 v42, v42, v42
	global_store_short v[28:29], v42, off offset:128
	ds_read2st64_b32 v[42:43], v132 offset1:1
	v_add_u32_e32 v28, s93, v131
	s_waitcnt lgkmcnt(0)
	v_pk_mul_f32 v[48:49], v[42:43], v[42:43]
	s_nop 0
	v_add_f32_e32 v29, v48, v49
	ds_bpermute_b32 v48, v47, v29
	s_waitcnt lgkmcnt(0)
	v_add_f32_e32 v29, v29, v48
	ds_bpermute_b32 v48, v46, v29
	s_waitcnt lgkmcnt(0)
	v_add_f32_e32 v29, v29, v48
	ds_bpermute_b32 v48, v45, v29
	s_waitcnt lgkmcnt(0)
	v_add_f32_e32 v29, v29, v48
	ds_bpermute_b32 v48, v44, v29
	s_waitcnt lgkmcnt(0)
	v_add_f32_e32 v29, v29, v48
	ds_bpermute_b32 v48, v41, v29
	s_waitcnt lgkmcnt(0)
	v_add_f32_e32 v29, v29, v48
	ds_bpermute_b32 v48, v0, v29
	s_waitcnt lgkmcnt(0)
	v_add_f32_e32 v29, v29, v48
	v_fmamk_f32 v29, v29, 0x3c000000, v184
	v_cmp_gt_f32_e32 vcc, s29, v29
	v_mul_f32_e32 v48, 0x4b800000, v29
	s_nop 0
	v_cndmask_b32_e32 v29, v29, v48, vcc
	v_rsq_f32_e32 v29, v29
	s_nop 0
	v_mul_f32_e32 v48, 0x45800000, v29
	v_cndmask_b32_e32 v48, v29, v48, vcc
	v_mul_f32_e32 v29, v42, v48
	s_waitcnt vmcnt(15)
	v_lshlrev_b32_e32 v42, 16, v165
	v_mul_f32_e32 v49, 0xbfb8aa3b, v42
	v_exp_f32_e32 v49, v49
	v_mul_f32_e32 v29, v137, v29
	v_add_f32_e32 v49, 1.0, v49
	s_nop 0
	v_rcp_f32_e32 v49, v49
	s_nop 0
	v_mul_f32_e32 v42, v49, v42
	v_mul_f32_e32 v29, v42, v29
	v_cvt_pk_bf16_f32 v42, v29, v29
	v_ashrrev_i32_e32 v29, 31, v28
	v_lshlrev_b64 v[28:29], 11, v[28:29]
	v_lshl_add_u64 v[28:29], v[26:27], 0, v[28:29]
	global_store_short v[28:29], v42, off
	v_mul_f32_e32 v42, v43, v48
	s_waitcnt vmcnt(15)
	v_lshlrev_b32_e32 v43, 16, v166
	v_mul_f32_e32 v48, 0xbfb8aa3b, v43
	v_exp_f32_e32 v48, v48
	v_mul_f32_e32 v42, v159, v42
	v_add_f32_e32 v48, 1.0, v48
	s_nop 0
	v_rcp_f32_e32 v48, v48
	s_nop 0
	v_mul_f32_e32 v43, v48, v43
	v_mul_f32_e32 v42, v43, v42
	v_cvt_pk_bf16_f32 v42, v42, v42
	global_store_short v[28:29], v42, off offset:128
	ds_read2st64_b32 v[42:43], v134 offset1:1
	v_add_u32_e32 v28, s93, v133
	s_waitcnt lgkmcnt(0)
	v_pk_mul_f32 v[48:49], v[42:43], v[42:43]
	s_nop 0
	v_add_f32_e32 v29, v48, v49
	ds_bpermute_b32 v48, v47, v29
	s_waitcnt lgkmcnt(0)
	v_add_f32_e32 v29, v29, v48
	ds_bpermute_b32 v48, v46, v29
	s_waitcnt lgkmcnt(0)
	v_add_f32_e32 v29, v29, v48
	ds_bpermute_b32 v48, v45, v29
	s_waitcnt lgkmcnt(0)
	v_add_f32_e32 v29, v29, v48
	ds_bpermute_b32 v48, v44, v29
	s_waitcnt lgkmcnt(0)
	v_add_f32_e32 v29, v29, v48
	ds_bpermute_b32 v48, v41, v29
	s_waitcnt lgkmcnt(0)
	v_add_f32_e32 v29, v29, v48
	ds_bpermute_b32 v48, v0, v29
	s_waitcnt lgkmcnt(0)
	v_add_f32_e32 v29, v29, v48
	v_fmamk_f32 v29, v29, 0x3c000000, v184
	v_cmp_gt_f32_e32 vcc, s29, v29
	v_mul_f32_e32 v48, 0x4b800000, v29
	s_nop 0
	v_cndmask_b32_e32 v29, v29, v48, vcc
	v_rsq_f32_e32 v29, v29
	s_nop 0
	v_mul_f32_e32 v48, 0x45800000, v29
	v_cndmask_b32_e32 v48, v29, v48, vcc
	v_mul_f32_e32 v29, v42, v48
	s_waitcnt vmcnt(15)
	v_lshlrev_b32_e32 v42, 16, v167
	v_mul_f32_e32 v49, 0xbfb8aa3b, v42
	v_exp_f32_e32 v49, v49
	v_mul_f32_e32 v29, v137, v29
	v_add_f32_e32 v49, 1.0, v49
	s_nop 0
	v_rcp_f32_e32 v49, v49
	s_nop 0
	v_mul_f32_e32 v42, v49, v42
	v_mul_f32_e32 v29, v42, v29
	v_cvt_pk_bf16_f32 v42, v29, v29
	v_ashrrev_i32_e32 v29, 31, v28
	v_lshlrev_b64 v[28:29], 11, v[28:29]
	v_lshl_add_u64 v[28:29], v[26:27], 0, v[28:29]
	global_store_short v[28:29], v42, off
	v_mul_f32_e32 v42, v43, v48
	s_waitcnt vmcnt(15)
	v_lshlrev_b32_e32 v43, 16, v168
	v_mul_f32_e32 v48, 0xbfb8aa3b, v43
	v_exp_f32_e32 v48, v48
	v_mul_f32_e32 v42, v159, v42
	v_add_f32_e32 v48, 1.0, v48
	s_nop 0
	v_rcp_f32_e32 v48, v48
	s_nop 0
	v_mul_f32_e32 v43, v48, v43
	v_mul_f32_e32 v42, v43, v42
	v_cvt_pk_bf16_f32 v42, v42, v42
	global_store_short v[28:29], v42, off offset:128
	ds_read2st64_b32 v[42:43], v136 offset1:1
	v_add_u32_e32 v28, s93, v135
	s_waitcnt lgkmcnt(0)
	v_pk_mul_f32 v[48:49], v[42:43], v[42:43]
	s_nop 0
	v_add_f32_e32 v29, v48, v49
	ds_bpermute_b32 v47, v47, v29
	s_waitcnt lgkmcnt(0)
	v_add_f32_e32 v29, v29, v47
	ds_bpermute_b32 v46, v46, v29
	s_waitcnt lgkmcnt(0)
	v_add_f32_e32 v29, v29, v46
	ds_bpermute_b32 v45, v45, v29
	s_waitcnt lgkmcnt(0)
	v_add_f32_e32 v29, v29, v45
	ds_bpermute_b32 v44, v44, v29
	s_waitcnt lgkmcnt(0)
	v_add_f32_e32 v29, v29, v44
	ds_bpermute_b32 v41, v41, v29
	s_waitcnt lgkmcnt(0)
	v_add_f32_e32 v29, v29, v41
	ds_bpermute_b32 v0, v0, v29
	s_waitcnt vmcnt(15)
	v_lshlrev_b32_e32 v41, 16, v169
	s_waitcnt lgkmcnt(0)
	v_add_f32_e32 v0, v29, v0
	v_fmamk_f32 v0, v0, 0x3c000000, v184
	v_cmp_gt_f32_e32 vcc, s29, v0
	v_mul_f32_e32 v29, 0x4b800000, v0
	s_nop 0
	v_cndmask_b32_e32 v0, v0, v29, vcc
	v_rsq_f32_e32 v0, v0
	s_nop 0
	v_mul_f32_e32 v29, 0x45800000, v0
	v_cndmask_b32_e32 v0, v0, v29, vcc
	v_mul_f32_e32 v29, v42, v0
	v_mul_f32_e32 v42, 0xbfb8aa3b, v41
	v_exp_f32_e32 v42, v42
	v_mul_f32_e32 v29, v137, v29
	v_mul_f32_e32 v0, v43, v0
	v_mul_f32_e32 v0, v159, v0
	v_add_f32_e32 v42, 1.0, v42
	s_nop 0
	v_rcp_f32_e32 v42, v42
	s_nop 0
	v_mul_f32_e32 v41, v42, v41
	v_mul_f32_e32 v29, v41, v29
	v_cvt_pk_bf16_f32 v41, v29, v29
	v_ashrrev_i32_e32 v29, 31, v28
	v_lshlrev_b64 v[28:29], 11, v[28:29]
	v_lshl_add_u64 v[26:27], v[26:27], 0, v[28:29]
	s_waitcnt vmcnt(14)
	v_lshlrev_b32_e32 v28, 16, v170
	v_mul_f32_e32 v29, 0xbfb8aa3b, v28
	v_exp_f32_e32 v29, v29
	global_store_short v[26:27], v41, off
	v_add_f32_e32 v29, 1.0, v29
	v_readlane_b32 s0, v252, 0
	v_readlane_b32 s1, v252, 1
	v_rcp_f32_e32 v29, v29
	s_nop 0
	v_mul_f32_e32 v28, v29, v28
	v_mul_f32_e32 v0, v28, v0
	v_cvt_pk_bf16_f32 v0, v0, v0
	global_store_short v[26:27], v0, off offset:128
	s_waitcnt lgkmcnt(0)
	s_barrier
	s_load_dword s0, s[0:1], 0x10
	s_waitcnt lgkmcnt(0)
	s_lshr_b32 s0, s0, 16
	s_cmp_lg_u32 s0, 0
	s_cselect_b64 s[0:1], -1, 0
	s_cmp_lg_u64 s[0:1], 0
	s_addc_u32 s94, s92, 0
	s_cmpk_gt_i32 s94, 0x1ff
	s_cbranch_scc1 .LBB0_1190

.LBB0_1109:
	s_waitcnt vmcnt(6)
	ds_write_b128 v138, v[2:5]
	s_waitcnt vmcnt(5)
	ds_write_b128 v139, v[6:9]
	s_waitcnt vmcnt(4)
	ds_write_b128 v140, v[10:13]
	s_waitcnt vmcnt(3)
	ds_write_b128 v141, v[14:17]
	s_waitcnt vmcnt(2)
	ds_write_b128 v142, v[18:21]
	s_waitcnt vmcnt(1)
	ds_write_b128 v143, v[22:25]
	v_cndmask_b32_e64 v0, v69, v68, s[86:87]
	s_waitcnt lgkmcnt(0)
	s_barrier
	v_mad_u64_u32 v[172:173], s[0:1], v0, s13, v[32:33]
	ds_read_u16 v0, v172 offset:256
	s_waitcnt vmcnt(0)
	v_sub_f32_e32 v178, 1.0, v64
	s_waitcnt lgkmcnt(0)
	v_lshlrev_b32_e32 v0, 16, v0
	v_mul_f32_e32 v0, 0xbfb8aa3b, v0
	v_exp_f32_e32 v0, v0
	s_nop 0
	v_add_f32_e32 v0, 1.0, v0
	s_nop 0
	v_rcp_f32_e32 v0, v0
	s_nop 0
	v_fma_f32 v26, v178, v0, v64
	v_cmp_gt_f32_e32 vcc, s29, v26
	v_cndmask_b32_e64 v29, v71, v70, s[86:87]
	s_nop 0
	v_cndmask_b32_e64 v0, 0, 32, vcc
	v_ldexp_f32 v0, v26, v0
	v_log_f32_e32 v0, v0
	s_nop 0
	v_mul_f32_e32 v27, 0x3f317217, v0
	v_fma_f32 v27, v0, s31, -v27
	v_fmac_f32_e32 v27, 0x3377d1cf, v0
	v_fmac_f32_e32 v27, 0x3f317217, v0
	v_cmp_lt_f32_e64 s[0:1], |v0|, s96
	s_nop 1
	v_cndmask_b32_e64 v0, v0, v27, s[0:1]
	v_cndmask_b32_e32 v27, 0, v187, vcc
	v_sub_f32_e32 v0, v0, v27
	ds_read_u16 v28, v172
	ds_read_u16 v27, v172 offset:512
	v_mad_u64_u32 v[172:173], s[0:1], v29, s13, v[32:33]
	ds_read_u16 v29, v172 offset:256
	s_waitcnt lgkmcnt(0)
	v_lshlrev_b32_e32 v29, 16, v29
	v_mul_f32_e32 v29, 0xbfb8aa3b, v29
	v_exp_f32_e32 v29, v29
	s_nop 0
	v_add_f32_e32 v29, 1.0, v29
	s_nop 0
	v_rcp_f32_e32 v29, v29
	s_nop 0
	v_fma_f32 v41, v178, v29, v64
	v_cmp_gt_f32_e32 vcc, s29, v41
	s_nop 1
	v_cndmask_b32_e64 v29, 0, 32, vcc
	v_ldexp_f32 v29, v41, v29
	v_log_f32_e32 v29, v29
	s_nop 0
	v_mul_f32_e32 v171, 0x3f317217, v29
	v_fma_f32 v171, v29, s31, -v171
	v_fmac_f32_e32 v171, 0x3377d1cf, v29
	v_fmac_f32_e32 v171, 0x3f317217, v29
	v_cmp_lt_f32_e64 s[0:1], |v29|, s96
	s_nop 1
	v_cndmask_b32_e64 v29, v29, v171, s[0:1]
	v_cndmask_b32_e32 v171, 0, v187, vcc
	v_sub_f32_e32 v175, v29, v171
	ds_read_u16 v171, v172
	ds_read_u16 v29, v172 offset:512
	v_cndmask_b32_e64 v172, v73, v72, s[86:87]
	v_mad_u64_u32 v[180:181], s[0:1], v172, s13, v[32:33]
	ds_read_u16 v172, v180 offset:256
	v_add_f32_e32 v239, v0, v175
	s_waitcnt lgkmcnt(0)
	v_lshlrev_b32_e32 v172, 16, v172
	v_mul_f32_e32 v172, 0xbfb8aa3b, v172
	v_exp_f32_e32 v172, v172
	s_nop 0
	v_add_f32_e32 v172, 1.0, v172
	s_nop 0
	v_rcp_f32_e32 v172, v172
	s_nop 0
	v_fma_f32 v172, v178, v172, v64
	v_cmp_gt_f32_e32 vcc, s29, v172
	s_nop 1
	v_cndmask_b32_e64 v173, 0, 32, vcc
	v_ldexp_f32 v173, v172, v173
	v_log_f32_e32 v173, v173
	s_nop 0
	v_mul_f32_e32 v174, 0x3f317217, v173
	v_fma_f32 v174, v173, s31, -v174
	v_fmac_f32_e32 v174, 0x3377d1cf, v173
	v_fmac_f32_e32 v174, 0x3f317217, v173
	v_cmp_lt_f32_e64 s[0:1], |v173|, s96
	s_nop 1
	v_cndmask_b32_e64 v173, v173, v174, s[0:1]
	v_cndmask_b32_e32 v174, 0, v187, vcc
	v_sub_f32_e32 v176, v173, v174
	ds_read_u16 v174, v180
	ds_read_u16 v173, v180 offset:512
	v_cndmask_b32_e64 v180, v75, v74, s[86:87]
	v_mad_u64_u32 v[180:181], s[0:1], v180, s13, v[32:33]
	ds_read_u16 v181, v180 offset:256
	v_add_f32_e32 v238, v239, v176
	v_mov_b32_e32 v176, 0
	s_waitcnt lgkmcnt(0)
	v_lshlrev_b32_e32 v181, 16, v181
	v_mul_f32_e32 v181, 0xbfb8aa3b, v181
	v_exp_f32_e32 v181, v181
	s_nop 0
	v_add_f32_e32 v181, 1.0, v181
	s_nop 0
	v_rcp_f32_e32 v181, v181
	s_nop 0
	v_fma_f32 v181, v178, v181, v64
	v_cmp_gt_f32_e32 vcc, s29, v181
	s_nop 1
	v_cndmask_b32_e64 v188, 0, 32, vcc
	v_ldexp_f32 v188, v181, v188
	v_log_f32_e32 v188, v188
	s_nop 0
	v_mul_f32_e32 v189, 0x3f317217, v188
	v_fma_f32 v189, v188, s31, -v189
	v_fmac_f32_e32 v189, 0x3377d1cf, v188
	v_fmac_f32_e32 v189, 0x3f317217, v188
	v_cmp_lt_f32_e64 s[0:1], |v188|, s96
	s_nop 1
	v_cndmask_b32_e64 v188, v188, v189, s[0:1]
	v_cndmask_b32_e32 v189, 0, v187, vcc
	v_sub_f32_e32 v195, v188, v189
	v_cndmask_b32_e64 v189, v77, v76, s[86:87]
	v_mad_u64_u32 v[192:193], s[0:1], v189, s13, v[32:33]
	ds_read_u16 v188, v180
	ds_read_u16 v180, v180 offset:512
	ds_read_u16 v189, v192 offset:256
	v_add_f32_e32 v237, v238, v195
	s_waitcnt lgkmcnt(0)
	v_lshlrev_b32_e32 v189, 16, v189
	v_mul_f32_e32 v189, 0xbfb8aa3b, v189
	v_exp_f32_e32 v189, v189
	s_nop 0
	v_add_f32_e32 v189, 1.0, v189
	s_nop 0
	v_rcp_f32_e32 v189, v189
	s_nop 0
	v_fma_f32 v190, v178, v189, v64
	v_cmp_gt_f32_e32 vcc, s29, v190
	s_nop 1
	v_cndmask_b32_e64 v189, 0, 32, vcc
	v_ldexp_f32 v189, v190, v189
	v_log_f32_e32 v189, v189
	s_nop 0
	v_mul_f32_e32 v191, 0x3f317217, v189
	v_fma_f32 v191, v189, s31, -v191
	v_fmac_f32_e32 v191, 0x3377d1cf, v189
	v_fmac_f32_e32 v191, 0x3f317217, v189
	v_cmp_lt_f32_e64 s[0:1], |v189|, s96
	s_nop 1
	v_cndmask_b32_e64 v189, v189, v191, s[0:1]
	v_cndmask_b32_e32 v191, 0, v187, vcc
	v_sub_f32_e32 v199, v189, v191
	ds_read_u16 v191, v192
	ds_read_u16 v189, v192 offset:512
	v_cndmask_b32_e64 v192, v79, v78, s[86:87]
	v_mad_u64_u32 v[196:197], s[0:1], v192, s13, v[32:33]
	ds_read_u16 v192, v196 offset:256
	s_waitcnt lgkmcnt(0)
	v_lshlrev_b32_e32 v192, 16, v192
	v_mul_f32_e32 v192, 0xbfb8aa3b, v192
	v_exp_f32_e32 v192, v192
	s_nop 0
	v_add_f32_e32 v192, 1.0, v192
	s_nop 0
	v_rcp_f32_e32 v192, v192
	s_nop 0
	v_fma_f32 v192, v178, v192, v64
	v_cmp_gt_f32_e32 vcc, s29, v192
	s_nop 1
	v_cndmask_b32_e64 v193, 0, 32, vcc
	v_ldexp_f32 v193, v192, v193
	v_log_f32_e32 v193, v193
	s_nop 0
	v_mul_f32_e32 v194, 0x3f317217, v193
	v_fma_f32 v194, v193, s31, -v194
	v_fmac_f32_e32 v194, 0x3377d1cf, v193
	v_fmac_f32_e32 v194, 0x3f317217, v193
	v_cmp_lt_f32_e64 s[0:1], |v193|, s96
	s_nop 1
	v_cndmask_b32_e64 v193, v193, v194, s[0:1]
	v_cndmask_b32_e32 v194, 0, v187, vcc
	v_sub_f32_e32 v203, v193, v194
	ds_read_u16 v194, v196
	ds_read_u16 v193, v196 offset:512
	v_cndmask_b32_e64 v196, v81, v80, s[86:87]
	v_mad_u64_u32 v[196:197], s[0:1], v196, s13, v[32:33]
	ds_read_u16 v197, v196 offset:256
	s_waitcnt lgkmcnt(0)
	v_lshlrev_b32_e32 v197, 16, v197
	v_mul_f32_e32 v197, 0xbfb8aa3b, v197
	v_exp_f32_e32 v197, v197
	s_nop 0
	v_add_f32_e32 v197, 1.0, v197
	s_nop 0
	v_rcp_f32_e32 v197, v197
	s_nop 0
	v_fma_f32 v197, v178, v197, v64
	v_cmp_gt_f32_e32 vcc, s29, v197
	s_nop 1
	v_cndmask_b32_e64 v198, 0, 32, vcc
	v_ldexp_f32 v198, v197, v198
	v_log_f32_e32 v198, v198
	s_nop 0
	v_mul_f32_e32 v200, 0x3f317217, v198
	v_fma_f32 v200, v198, s31, -v200
	v_fmac_f32_e32 v200, 0x3377d1cf, v198
	v_fmac_f32_e32 v200, 0x3f317217, v198
	v_cmp_lt_f32_e64 s[0:1], |v198|, s96
	s_nop 1
	v_cndmask_b32_e64 v198, v198, v200, s[0:1]
	v_cndmask_b32_e32 v200, 0, v187, vcc
	v_sub_f32_e32 v208, v198, v200
	v_cndmask_b32_e64 v200, v83, v82, s[86:87]
	v_mad_u64_u32 v[204:205], s[0:1], v200, s13, v[32:33]
	ds_read_u16 v198, v196
	ds_read_u16 v196, v196 offset:512
	ds_read_u16 v200, v204 offset:256
	s_waitcnt lgkmcnt(0)
	v_lshlrev_b32_e32 v200, 16, v200
	v_mul_f32_e32 v200, 0xbfb8aa3b, v200
	v_exp_f32_e32 v200, v200
	s_nop 0
	v_add_f32_e32 v200, 1.0, v200
	s_nop 0
	v_rcp_f32_e32 v200, v200
	s_nop 0
	v_fma_f32 v200, v178, v200, v64
	v_cmp_gt_f32_e32 vcc, s29, v200
	s_nop 1
	v_cndmask_b32_e64 v201, 0, 32, vcc
	v_ldexp_f32 v201, v200, v201
	v_log_f32_e32 v201, v201
	s_nop 0
	v_mul_f32_e32 v202, 0x3f317217, v201
	v_fma_f32 v202, v201, s31, -v202
	v_fmac_f32_e32 v202, 0x3377d1cf, v201
	v_fmac_f32_e32 v202, 0x3f317217, v201
	v_cmp_lt_f32_e64 s[0:1], |v201|, s96
	s_nop 1
	v_cndmask_b32_e64 v201, v201, v202, s[0:1]
	v_cndmask_b32_e32 v202, 0, v187, vcc
	v_sub_f32_e32 v213, v201, v202
	ds_read_u16 v201, v204
	ds_read_u16 v202, v204 offset:512
	v_cndmask_b32_e64 v204, v85, v84, s[86:87]
	v_mad_u64_u32 v[204:205], s[0:1], v204, s13, v[32:33]
	ds_read_u16 v205, v204 offset:256
	s_waitcnt lgkmcnt(0)
	v_lshlrev_b32_e32 v205, 16, v205
	v_mul_f32_e32 v205, 0xbfb8aa3b, v205
	v_exp_f32_e32 v205, v205
	s_nop 0
	v_add_f32_e32 v205, 1.0, v205
	s_nop 0
	v_rcp_f32_e32 v205, v205
	s_nop 0
	v_fma_f32 v205, v178, v205, v64
	v_cmp_gt_f32_e32 vcc, s29, v205
	s_nop 1
	v_cndmask_b32_e64 v206, 0, 32, vcc
	v_ldexp_f32 v206, v205, v206
	v_log_f32_e32 v206, v206
	s_nop 0
	v_mul_f32_e32 v207, 0x3f317217, v206
	v_fma_f32 v207, v206, s31, -v207
	v_fmac_f32_e32 v207, 0x3377d1cf, v206
	v_fmac_f32_e32 v207, 0x3f317217, v206
	v_cmp_lt_f32_e64 s[0:1], |v206|, s96
	s_nop 1
	v_cndmask_b32_e64 v206, v206, v207, s[0:1]
	v_cndmask_b32_e32 v207, 0, v187, vcc
	v_sub_f32_e32 v221, v206, v207
	v_cndmask_b32_e64 v207, v87, v86, s[86:87]
	v_mad_u64_u32 v[214:215], s[0:1], v207, s13, v[32:33]
	ds_read_u16 v206, v204
	ds_read_u16 v204, v204 offset:512
	ds_read_u16 v207, v214 offset:256
	s_waitcnt lgkmcnt(0)
	v_lshlrev_b32_e32 v207, 16, v207
	v_mul_f32_e32 v207, 0xbfb8aa3b, v207
	v_exp_f32_e32 v207, v207
	s_nop 0
	v_add_f32_e32 v207, 1.0, v207
	s_nop 0
	v_rcp_f32_e32 v207, v207
	s_nop 0
	v_fma_f32 v209, v178, v207, v64
	v_cmp_gt_f32_e32 vcc, s29, v209
	v_cndmask_b32_e64 v211, v89, v88, s[86:87]
	s_nop 0
	v_cndmask_b32_e64 v207, 0, 32, vcc
	v_ldexp_f32 v207, v209, v207
	v_log_f32_e32 v207, v207
	s_nop 0
	v_mul_f32_e32 v210, 0x3f317217, v207
	v_fma_f32 v210, v207, s31, -v210
	v_fmac_f32_e32 v210, 0x3377d1cf, v207
	v_fmac_f32_e32 v210, 0x3f317217, v207
	v_cmp_lt_f32_e64 s[0:1], |v207|, s96
	s_nop 1
	v_cndmask_b32_e64 v207, v207, v210, s[0:1]
	v_cndmask_b32_e32 v210, 0, v187, vcc
	v_mad_u64_u32 v[216:217], s[0:1], v211, s13, v[32:33]
	v_sub_f32_e32 v225, v207, v210
	ds_read_u16 v210, v214
	ds_read_u16 v207, v214 offset:512
	ds_read_u16 v211, v216 offset:256
	s_waitcnt lgkmcnt(0)
	v_lshlrev_b32_e32 v211, 16, v211
	v_mul_f32_e32 v211, 0xbfb8aa3b, v211
	v_exp_f32_e32 v211, v211
	s_nop 0
	v_add_f32_e32 v211, 1.0, v211
	s_nop 0
	v_rcp_f32_e32 v211, v211
	s_nop 0
	v_fma_f32 v211, v178, v211, v64
	v_cmp_gt_f32_e32 vcc, s29, v211
	v_cndmask_b32_e64 v215, v91, v90, s[86:87]
	s_nop 0
	v_cndmask_b32_e64 v212, 0, 32, vcc
	v_ldexp_f32 v212, v211, v212
	v_log_f32_e32 v212, v212
	s_nop 0
	v_mul_f32_e32 v214, 0x3f317217, v212
	v_fma_f32 v214, v212, s31, -v214
	v_fmac_f32_e32 v214, 0x3377d1cf, v212
	v_fmac_f32_e32 v214, 0x3f317217, v212
	v_cmp_lt_f32_e64 s[0:1], |v212|, s96
	s_nop 1
	v_cndmask_b32_e64 v212, v212, v214, s[0:1]
	v_cndmask_b32_e32 v214, 0, v187, vcc
	v_mad_u64_u32 v[218:219], s[0:1], v215, s13, v[32:33]
	v_sub_f32_e32 v227, v212, v214
	ds_read_u16 v214, v216
	ds_read_u16 v212, v216 offset:512
	ds_read_u16 v215, v218 offset:256
	s_waitcnt lgkmcnt(0)
	v_lshlrev_b32_e32 v215, 16, v215
	v_mul_f32_e32 v215, 0xbfb8aa3b, v215
	v_exp_f32_e32 v215, v215
	s_nop 0
	v_add_f32_e32 v215, 1.0, v215
	s_nop 0
	v_rcp_f32_e32 v215, v215
	s_nop 0
	v_fma_f32 v216, v178, v215, v64
	v_cmp_gt_f32_e32 vcc, s29, v216
	s_nop 1
	v_cndmask_b32_e64 v215, 0, 32, vcc
	v_ldexp_f32 v215, v216, v215
	v_log_f32_e32 v215, v215
	s_nop 0
	v_mul_f32_e32 v217, 0x3f317217, v215
	v_fma_f32 v217, v215, s31, -v217
	v_fmac_f32_e32 v217, 0x3377d1cf, v215
	v_fmac_f32_e32 v217, 0x3f317217, v215
	v_cmp_lt_f32_e64 s[0:1], |v215|, s96
	s_nop 1
	v_cndmask_b32_e64 v215, v215, v217, s[0:1]
	v_cndmask_b32_e32 v217, 0, v187, vcc
	v_sub_f32_e32 v240, v215, v217
	ds_read_u16 v217, v218
	ds_read_u16 v215, v218 offset:512
	v_cndmask_b32_e64 v218, v93, v92, s[86:87]
	v_mad_u64_u32 v[218:219], s[0:1], v218, s13, v[32:33]
	ds_read_u16 v219, v218 offset:256
	s_waitcnt lgkmcnt(0)
	v_lshlrev_b32_e32 v219, 16, v219
	v_mul_f32_e32 v219, 0xbfb8aa3b, v219
	v_exp_f32_e32 v219, v219
	s_nop 0
	v_add_f32_e32 v219, 1.0, v219
	s_nop 0
	v_rcp_f32_e32 v219, v219
	s_nop 0
	v_fma_f32 v219, v178, v219, v64
	v_cmp_gt_f32_e32 vcc, s29, v219
	s_nop 1
	v_cndmask_b32_e64 v220, 0, 32, vcc
	v_ldexp_f32 v220, v219, v220
	v_log_f32_e32 v220, v220
	s_nop 0
	v_mul_f32_e32 v222, 0x3f317217, v220
	v_fma_f32 v222, v220, s31, -v222
	v_fmac_f32_e32 v222, 0x3377d1cf, v220
	v_fmac_f32_e32 v222, 0x3f317217, v220
	v_cmp_lt_f32_e64 s[0:1], |v220|, s96
	s_nop 1
	v_cndmask_b32_e64 v220, v220, v222, s[0:1]
	v_cndmask_b32_e32 v222, 0, v187, vcc
	v_sub_f32_e32 v241, v220, v222
	v_cndmask_b32_e64 v222, v95, v94, s[86:87]
	v_mad_u64_u32 v[228:229], s[0:1], v222, s13, v[32:33]
	ds_read_u16 v220, v218
	ds_read_u16 v218, v218 offset:512
	ds_read_u16 v222, v228 offset:256
	s_waitcnt lgkmcnt(0)
	v_lshlrev_b32_e32 v222, 16, v222
	v_mul_f32_e32 v222, 0xbfb8aa3b, v222
	v_exp_f32_e32 v222, v222
	s_nop 0
	v_add_f32_e32 v222, 1.0, v222
	s_nop 0
	v_rcp_f32_e32 v222, v222
	s_nop 0
	v_fma_f32 v222, v178, v222, v64
	v_cmp_gt_f32_e32 vcc, s29, v222
	v_cndmask_b32_e64 v226, v97, v96, s[86:87]
	s_nop 0
	v_cndmask_b32_e64 v223, 0, 32, vcc
	v_ldexp_f32 v223, v222, v223
	v_log_f32_e32 v223, v223
	s_nop 0
	v_mul_f32_e32 v224, 0x3f317217, v223
	v_fma_f32 v224, v223, s31, -v224
	v_fmac_f32_e32 v224, 0x3377d1cf, v223
	v_fmac_f32_e32 v224, 0x3f317217, v223
	v_cmp_lt_f32_e64 s[0:1], |v223|, s96
	s_nop 1
	v_cndmask_b32_e64 v223, v223, v224, s[0:1]
	v_cndmask_b32_e32 v224, 0, v187, vcc
	v_mad_u64_u32 v[232:233], s[0:1], v226, s13, v[32:33]
	v_sub_f32_e32 v242, v223, v224
	ds_read_u16 v224, v228
	ds_read_u16 v223, v228 offset:512
	ds_read_u16 v226, v232 offset:256
	s_waitcnt lgkmcnt(0)
	v_lshlrev_b32_e32 v226, 16, v226
	v_mul_f32_e32 v226, 0xbfb8aa3b, v226
	v_exp_f32_e32 v226, v226
	s_nop 0
	v_add_f32_e32 v226, 1.0, v226
	s_nop 0
	v_rcp_f32_e32 v226, v226
	s_nop 0
	v_fma_f32 v228, v178, v226, v64
	v_cmp_gt_f32_e32 vcc, s29, v228
	s_nop 1
	v_cndmask_b32_e64 v226, 0, 32, vcc
	v_ldexp_f32 v226, v228, v226
	v_log_f32_e32 v226, v226
	s_nop 0
	v_mul_f32_e32 v229, 0x3f317217, v226
	v_fma_f32 v229, v226, s31, -v229
	v_fmac_f32_e32 v229, 0x3377d1cf, v226
	v_fmac_f32_e32 v229, 0x3f317217, v226
	v_cmp_lt_f32_e64 s[0:1], |v226|, s96
	s_nop 1
	v_cndmask_b32_e64 v226, v226, v229, s[0:1]
	v_cndmask_b32_e32 v229, 0, v187, vcc
	v_sub_f32_e32 v243, v226, v229
	v_cndmask_b32_e64 v229, v99, v98, s[86:87]
	v_mad_u64_u32 v[234:235], s[0:1], v229, s13, v[32:33]
	ds_read_u16 v230, v232
	ds_read_u16 v226, v232 offset:512
	ds_read_u16 v229, v234 offset:256
	s_waitcnt lgkmcnt(0)
	v_lshlrev_b32_e32 v229, 16, v229
	v_mul_f32_e32 v229, 0xbfb8aa3b, v229
	v_exp_f32_e32 v229, v229
	s_nop 0
	v_add_f32_e32 v229, 1.0, v229
	s_nop 0
	v_rcp_f32_e32 v229, v229
	s_nop 0
	v_fma_f32 v232, v178, v229, v64
	v_cmp_gt_f32_e32 vcc, s29, v232
	v_add_f32_e32 v235, v237, v199
	ds_read_u16 v233, v234
	ds_read_u16 v236, v234 offset:512
	v_cndmask_b32_e64 v178, 0, 32, vcc
	v_ldexp_f32 v178, v232, v178
	v_log_f32_e32 v178, v178
	v_add_f32_e32 v234, v235, v203
	v_add_f32_e32 v231, v234, v208
	v_mul_f32_e32 v229, 0x3f317217, v178
	v_fma_f32 v229, v178, s31, -v229
	v_fmac_f32_e32 v229, 0x3377d1cf, v178
	v_fmac_f32_e32 v229, 0x3f317217, v178
	v_cmp_lt_f32_e64 s[0:1], |v178|, s96
	s_nop 1
	v_cndmask_b32_e64 v178, v178, v229, s[0:1]
	v_cndmask_b32_e32 v229, 0, v187, vcc
	v_sub_f32_e32 v244, v178, v229
	v_add_f32_e32 v229, v231, v213
	v_add_f32_e32 v221, v229, v221
	v_add_f32_e32 v213, v221, v225
	v_add_f32_e32 v208, v213, v227
	v_add_f32_e32 v203, v208, v240
	v_add_f32_e32 v199, v203, v241
	v_add_f32_e32 v195, v199, v242
	v_add_f32_e32 v178, v195, v243
	v_add_f32_e32 v175, v178, v244
	ds_write_b32 v101, v175
	s_waitcnt lgkmcnt(0)
	s_barrier
	s_and_saveexec_b64 s[0:1], s[62:63]
	s_cbranch_execnz .LBB0_1156
	s_or_b64 exec, exec, s[0:1]
	s_and_saveexec_b64 s[0:1], s[64:65]
	s_cbranch_execnz .LBB0_1157

.LBB0_1114:
	s_or_b64 exec, exec, s[0:1]
	v_lshlrev_b32_e32 v27, 16, v27
	v_sub_f32_e32 v227, 1.0, v26
	v_lshlrev_b32_e32 v26, 16, v28
	v_mul_f32_e32 v28, 0xbfb8aa3b, v27
	v_exp_f32_e32 v28, v28
	v_add_f32_e32 v0, v0, v176
	v_add_f32_e32 v28, 1.0, v28
	s_nop 0
	v_rcp_f32_e32 v28, v28
	s_nop 0
	v_mul_f32_e32 v240, v28, v27
	v_lshlrev_b32_e32 v28, 16, v29
	v_mul_f32_e32 v29, 0xbfb8aa3b, v28
	v_exp_f32_e32 v29, v29
	v_sub_f32_e32 v225, 1.0, v41
	v_lshlrev_b32_e32 v27, 16, v171
	v_cvt_pk_bf16_f32 v26, v26, v27
	v_add_f32_e32 v29, 1.0, v29
	s_nop 0
	v_rcp_f32_e32 v29, v29
	s_nop 0
	v_mul_f32_e32 v244, v29, v28
	v_lshlrev_b32_e32 v29, 16, v173
	v_mul_f32_e32 v41, 0xbfb8aa3b, v29
	v_exp_f32_e32 v41, v41
	v_sub_f32_e32 v241, 1.0, v172
	v_lshlrev_b32_e32 v28, 16, v174
	v_sub_f32_e32 v243, 1.0, v190
	v_add_f32_e32 v41, 1.0, v41
	s_nop 0
	v_rcp_f32_e32 v41, v41
	s_nop 0
	v_mul_f32_e32 v245, v41, v29
	v_lshlrev_b32_e32 v41, 16, v180
	v_mul_f32_e32 v171, 0xbfb8aa3b, v41
	v_exp_f32_e32 v171, v171
	v_sub_f32_e32 v242, 1.0, v181
	v_lshlrev_b32_e32 v29, 16, v188
	v_cvt_pk_bf16_f32 v27, v28, v29
	v_add_f32_e32 v171, 1.0, v171
	s_nop 0
	v_rcp_f32_e32 v171, v171
	s_nop 0
	v_mul_f32_e32 v246, v171, v41
	v_lshlrev_b32_e32 v171, 16, v189
	v_mul_f32_e32 v172, 0xbfb8aa3b, v171
	v_exp_f32_e32 v172, v172
	v_lshlrev_b32_e32 v41, 16, v191
	v_sub_f32_e32 v191, 1.0, v192
	v_sub_f32_e32 v192, 1.0, v197
	v_add_f32_e32 v172, 1.0, v172
	s_nop 0
	v_rcp_f32_e32 v172, v172
	s_nop 0
	v_mul_f32_e32 v247, v172, v171
	v_lshlrev_b32_e32 v172, 16, v193
	v_mul_f32_e32 v173, 0xbfb8aa3b, v172
	v_exp_f32_e32 v173, v173
	v_lshlrev_b32_e32 v171, 16, v194
	v_sub_f32_e32 v193, 1.0, v200
	v_cvt_pk_bf16_f32 v28, v41, v171
	v_add_f32_e32 v173, 1.0, v173
	s_nop 0
	v_rcp_f32_e32 v173, v173
	s_nop 0
	v_mul_f32_e32 v248, v173, v172
	v_lshlrev_b32_e32 v173, 16, v196
	v_mul_f32_e32 v174, 0xbfb8aa3b, v173
	v_exp_f32_e32 v174, v174
	v_lshlrev_b32_e32 v172, 16, v198
	v_sub_f32_e32 v196, 1.0, v205
	v_add_f32_e32 v174, 1.0, v174
	s_nop 0
	v_rcp_f32_e32 v174, v174
	s_nop 0
	v_mul_f32_e32 v249, v174, v173
	v_lshlrev_b32_e32 v174, 16, v202
	v_mul_f32_e32 v180, 0xbfb8aa3b, v174
	v_exp_f32_e32 v180, v180
	v_lshlrev_b32_e32 v173, 16, v201
	v_cvt_pk_bf16_f32 v29, v172, v173
	v_add_f32_e32 v180, 1.0, v180
	s_nop 0
	v_rcp_f32_e32 v180, v180
	s_nop 0
	v_mul_f32_e32 v250, v180, v174
	v_lshlrev_b32_e32 v180, 16, v204
	v_mul_f32_e32 v181, 0xbfb8aa3b, v180
	v_exp_f32_e32 v181, v181
	v_lshlrev_b32_e32 v174, 16, v206
	v_add_f32_e32 v181, 1.0, v181
	s_nop 0
	v_rcp_f32_e32 v181, v181
	s_nop 0
	v_mul_f32_e32 v251, v181, v180
	v_lshlrev_b32_e32 v181, 16, v207
	v_mul_f32_e32 v188, 0xbfb8aa3b, v181
	v_exp_f32_e32 v188, v188
	v_sub_f32_e32 v197, 1.0, v209
	v_lshlrev_b32_e32 v180, 16, v210
	v_cvt_pk_bf16_f32 v172, v174, v180
	v_add_f32_e32 v188, 1.0, v188
	s_nop 0
	v_rcp_f32_e32 v188, v188
	s_nop 0
	v_mul_f32_e32 v207, v188, v181
	v_lshlrev_b32_e32 v188, 16, v212
	v_mul_f32_e32 v189, 0xbfb8aa3b, v188
	v_exp_f32_e32 v189, v189
	v_sub_f32_e32 v198, 1.0, v211
	v_lshlrev_b32_e32 v181, 16, v214
	v_add_f32_e32 v189, 1.0, v189
	s_nop 0
	v_rcp_f32_e32 v189, v189
	s_nop 0
	v_mul_f32_e32 v209, v189, v188
	v_lshlrev_b32_e32 v189, 16, v215
	v_mul_f32_e32 v190, 0xbfb8aa3b, v189
	v_exp_f32_e32 v190, v190
	v_sub_f32_e32 v200, 1.0, v216
	v_lshlrev_b32_e32 v188, 16, v217
	v_cvt_pk_bf16_f32 v173, v181, v188
	v_add_f32_e32 v190, 1.0, v190
	s_nop 0
	v_rcp_f32_e32 v190, v190
	s_nop 0
	v_mul_f32_e32 v210, v190, v189
	v_lshlrev_b32_e32 v190, 16, v218
	v_mul_f32_e32 v194, 0xbfb8aa3b, v190
	v_exp_f32_e32 v194, v194
	v_sub_f32_e32 v201, 1.0, v219
	v_lshlrev_b32_e32 v189, 16, v220
	v_add_f32_e32 v194, 1.0, v194
	s_nop 0
	v_rcp_f32_e32 v194, v194
	s_nop 0
	v_mul_f32_e32 v211, v194, v190
	v_lshlrev_b32_e32 v194, 16, v223
	v_mul_f32_e32 v204, 0xbfb8aa3b, v194
	v_exp_f32_e32 v204, v204
	v_sub_f32_e32 v202, 1.0, v222
	v_lshlrev_b32_e32 v190, 16, v224
	v_cvt_pk_bf16_f32 v174, v189, v190
	v_add_f32_e32 v204, 1.0, v204
	s_nop 0
	v_rcp_f32_e32 v204, v204
	s_nop 0
	v_mul_f32_e32 v212, v204, v194
	v_lshlrev_b32_e32 v204, 16, v226
	v_mul_f32_e32 v206, 0xbfb8aa3b, v204
	v_exp_f32_e32 v206, v206
	v_sub_f32_e32 v205, 1.0, v228
	v_lshlrev_b32_e32 v194, 16, v230
	v_add_f32_e32 v206, 1.0, v206
	s_nop 0
	s_waitcnt lgkmcnt(1)
	v_lshlrev_b32_e32 v215, 16, v236
	v_mul_f32_e32 v216, 0xbfb8aa3b, v215
	v_exp_f32_e32 v216, v216
	v_rcp_f32_e32 v206, v206
	s_nop 0
	v_mul_f32_e32 v214, v206, v204
	v_sub_f32_e32 v206, 1.0, v232
	v_add_f32_e32 v216, 1.0, v216
	v_lshlrev_b32_e32 v204, 16, v233
	v_rcp_f32_e32 v216, v216
	s_nop 0
	v_mul_f32_e32 v215, v216, v215
	ds_read2st64_b32 v[216:217], v102 offset1:2
	s_waitcnt lgkmcnt(0)
	v_add_f32_e32 v216, v216, v217
	v_mul_f32_e32 v217, 0x3fb8aa3b, v0
	v_exp_f32_e32 v217, v217
	s_nop 0
	v_mul_f32_e32 v217, v240, v217
	v_cvt_pk_bf16_f32 v217, v217, v217
	ds_write_b16 v110, v217
	v_sub_f32_e32 v217, v0, v216
	v_sub_f32_e32 v0, v216, v0
	v_mul_f32_e32 v0, 0x3fb8aa3b, v0
	v_mul_f32_e32 v217, 0x3fb8aa3b, v217
	v_exp_f32_e32 v0, v0
	v_exp_f32_e32 v217, v217
	v_mul_f32_e32 v0, v227, v0
	v_mul_f32_e32 v217, v240, v217
	v_cvt_pk_bf16_f32 v0, v0, v0
	v_cvt_pk_bf16_f32 v217, v217, v217
	ds_write_b16 v110, v0 offset:34816
	v_add_f32_e32 v0, v239, v176
	ds_write_b16 v110, v217 offset:17408
	v_mul_f32_e32 v217, 0x3fb8aa3b, v0
	v_exp_f32_e32 v217, v217
	s_nop 0
	v_mul_f32_e32 v217, v244, v217
	v_cvt_pk_bf16_f32 v217, v217, v217
	ds_write_b16 v110, v217 offset:272
	v_sub_f32_e32 v217, v0, v216
	v_sub_f32_e32 v0, v216, v0
	v_mul_f32_e32 v0, 0x3fb8aa3b, v0
	v_mul_f32_e32 v217, 0x3fb8aa3b, v217
	v_exp_f32_e32 v0, v0
	v_exp_f32_e32 v217, v217
	v_mul_f32_e32 v0, v225, v0
	v_mul_f32_e32 v217, v244, v217
	v_cvt_pk_bf16_f32 v0, v0, v0
	v_cvt_pk_bf16_f32 v217, v217, v217
	ds_write_b16 v110, v0 offset:35088
	v_add_f32_e32 v0, v238, v176
	ds_write_b16 v110, v217 offset:17680
	v_mul_f32_e32 v217, 0x3fb8aa3b, v0
	v_exp_f32_e32 v217, v217
	s_nop 0
	v_mul_f32_e32 v217, v245, v217
	v_cvt_pk_bf16_f32 v217, v217, v217
	ds_write_b16 v110, v217 offset:544
	v_sub_f32_e32 v217, v0, v216
	v_sub_f32_e32 v0, v216, v0
	v_mul_f32_e32 v0, 0x3fb8aa3b, v0
	v_mul_f32_e32 v217, 0x3fb8aa3b, v217
	v_exp_f32_e32 v0, v0
	v_exp_f32_e32 v217, v217
	v_mul_f32_e32 v0, v241, v0
	v_mul_f32_e32 v217, v245, v217
	v_cvt_pk_bf16_f32 v0, v0, v0
	v_cvt_pk_bf16_f32 v217, v217, v217
	ds_write_b16 v110, v0 offset:35360
	v_add_f32_e32 v0, v237, v176
	ds_write_b16 v110, v217 offset:17952
	v_mul_f32_e32 v217, 0x3fb8aa3b, v0
	v_exp_f32_e32 v217, v217
	s_nop 0
	v_mul_f32_e32 v217, v246, v217
	v_cvt_pk_bf16_f32 v217, v217, v217
	ds_write_b16 v110, v217 offset:816
	v_sub_f32_e32 v217, v0, v216
	v_sub_f32_e32 v0, v216, v0
	v_mul_f32_e32 v0, 0x3fb8aa3b, v0
	v_mul_f32_e32 v217, 0x3fb8aa3b, v217
	v_exp_f32_e32 v0, v0
	v_exp_f32_e32 v217, v217
	v_mul_f32_e32 v0, v242, v0
	v_mul_f32_e32 v217, v246, v217
	v_cvt_pk_bf16_f32 v0, v0, v0
	v_cvt_pk_bf16_f32 v217, v217, v217
	ds_write_b16 v110, v0 offset:35632
	v_add_f32_e32 v0, v235, v176
	ds_write_b16 v110, v217 offset:18224
	v_mul_f32_e32 v217, 0x3fb8aa3b, v0
	v_exp_f32_e32 v217, v217
	s_nop 0
	v_mul_f32_e32 v217, v247, v217
	v_cvt_pk_bf16_f32 v217, v217, v217
	ds_write_b16 v110, v217 offset:1088
	v_sub_f32_e32 v217, v0, v216
	v_sub_f32_e32 v0, v216, v0
	v_mul_f32_e32 v0, 0x3fb8aa3b, v0
	v_mul_f32_e32 v217, 0x3fb8aa3b, v217
	v_exp_f32_e32 v0, v0
	v_exp_f32_e32 v217, v217
	v_mul_f32_e32 v0, v243, v0
	v_mul_f32_e32 v217, v247, v217
	v_cvt_pk_bf16_f32 v0, v0, v0
	v_cvt_pk_bf16_f32 v217, v217, v217
	ds_write_b16 v110, v0 offset:35904
	v_add_f32_e32 v0, v234, v176
	ds_write_b16 v110, v217 offset:18496
	v_mul_f32_e32 v217, 0x3fb8aa3b, v0
	v_exp_f32_e32 v217, v217
	s_nop 0
	v_mul_f32_e32 v217, v248, v217
	v_cvt_pk_bf16_f32 v217, v217, v217
	ds_write_b16 v110, v217 offset:1360
	v_sub_f32_e32 v217, v0, v216
	v_sub_f32_e32 v0, v216, v0
	v_mul_f32_e32 v0, 0x3fb8aa3b, v0
	v_exp_f32_e32 v0, v0
	v_mul_f32_e32 v217, 0x3fb8aa3b, v217
	v_exp_f32_e32 v217, v217
	v_mul_f32_e32 v0, v191, v0
	v_cvt_pk_bf16_f32 v0, v0, v0
	ds_write_b16 v110, v0 offset:36176
	v_add_f32_e32 v0, v231, v176
	v_mul_f32_e32 v191, 0x3fb8aa3b, v0
	v_exp_f32_e32 v191, v191
	v_mul_f32_e32 v217, v248, v217
	v_cvt_pk_bf16_f32 v217, v217, v217
	ds_write_b16 v110, v217 offset:18768
	v_mul_f32_e32 v191, v249, v191
	v_cvt_pk_bf16_f32 v191, v191, v191
	ds_write_b16 v110, v191 offset:1632
	v_sub_f32_e32 v191, v0, v216
	v_sub_f32_e32 v0, v216, v0
	v_mul_f32_e32 v0, 0x3fb8aa3b, v0
	v_mul_f32_e32 v191, 0x3fb8aa3b, v191
	v_exp_f32_e32 v0, v0
	v_exp_f32_e32 v191, v191
	v_mul_f32_e32 v0, v192, v0
	v_mul_f32_e32 v191, v249, v191
	v_cvt_pk_bf16_f32 v0, v0, v0
	v_cvt_pk_bf16_f32 v191, v191, v191
	ds_write_b16 v110, v0 offset:36448
	v_add_f32_e32 v0, v229, v176
	ds_write_b16 v110, v191 offset:19040
	v_mul_f32_e32 v191, 0x3fb8aa3b, v0
	v_exp_f32_e32 v191, v191
	s_nop 0
	v_mul_f32_e32 v191, v250, v191
	v_cvt_pk_bf16_f32 v191, v191, v191
	ds_write_b16 v110, v191 offset:1904
	v_sub_f32_e32 v191, v0, v216
	v_sub_f32_e32 v0, v216, v0
	v_mul_f32_e32 v0, 0x3fb8aa3b, v0
	v_mul_f32_e32 v191, 0x3fb8aa3b, v191
	v_exp_f32_e32 v0, v0
	v_exp_f32_e32 v191, v191
	v_mul_f32_e32 v0, v193, v0
	v_mul_f32_e32 v191, v250, v191
	v_cvt_pk_bf16_f32 v0, v0, v0
	v_cvt_pk_bf16_f32 v191, v191, v191
	ds_write_b16 v110, v0 offset:36720
	v_add_f32_e32 v0, v221, v176
	ds_write_b16 v110, v191 offset:19312
	v_mul_f32_e32 v191, 0x3fb8aa3b, v0
	v_exp_f32_e32 v191, v191
	s_nop 0
	v_mul_f32_e32 v191, v251, v191
	v_cvt_pk_bf16_f32 v191, v191, v191
	ds_write_b16 v110, v191 offset:2176
	v_sub_f32_e32 v191, v0, v216
	v_sub_f32_e32 v0, v216, v0
	v_mul_f32_e32 v0, 0x3fb8aa3b, v0
	v_mul_f32_e32 v191, 0x3fb8aa3b, v191
	v_exp_f32_e32 v0, v0
	v_exp_f32_e32 v191, v191
	v_mul_f32_e32 v0, v196, v0
	v_mul_f32_e32 v191, v251, v191
	v_cvt_pk_bf16_f32 v0, v0, v0
	v_cvt_pk_bf16_f32 v191, v191, v191
	ds_write_b16 v110, v0 offset:36992
	v_add_f32_e32 v0, v213, v176
	ds_write_b16 v110, v191 offset:19584
	v_mul_f32_e32 v191, 0x3fb8aa3b, v0
	v_exp_f32_e32 v191, v191
	s_nop 0
	v_mul_f32_e32 v191, v207, v191
	v_cvt_pk_bf16_f32 v191, v191, v191
	ds_write_b16 v110, v191 offset:2448
	v_sub_f32_e32 v191, v0, v216
	v_sub_f32_e32 v0, v216, v0
	v_mul_f32_e32 v0, 0x3fb8aa3b, v0
	v_mul_f32_e32 v191, 0x3fb8aa3b, v191
	v_exp_f32_e32 v0, v0
	v_exp_f32_e32 v191, v191
	v_mul_f32_e32 v0, v197, v0
	v_mul_f32_e32 v191, v207, v191
	v_cvt_pk_bf16_f32 v0, v0, v0
	v_cvt_pk_bf16_f32 v191, v191, v191
	ds_write_b16 v110, v0 offset:37264
	v_add_f32_e32 v0, v208, v176
	ds_write_b16 v110, v191 offset:19856
	v_mul_f32_e32 v191, 0x3fb8aa3b, v0
	v_exp_f32_e32 v191, v191
	s_nop 0
	v_mul_f32_e32 v191, v209, v191
	v_cvt_pk_bf16_f32 v191, v191, v191
	ds_write_b16 v110, v191 offset:2720
	v_sub_f32_e32 v191, v0, v216
	v_sub_f32_e32 v0, v216, v0
	v_mul_f32_e32 v0, 0x3fb8aa3b, v0
	v_mul_f32_e32 v191, 0x3fb8aa3b, v191
	v_exp_f32_e32 v0, v0
	v_exp_f32_e32 v191, v191
	v_mul_f32_e32 v0, v198, v0
	v_mul_f32_e32 v191, v209, v191
	v_cvt_pk_bf16_f32 v0, v0, v0
	v_cvt_pk_bf16_f32 v191, v191, v191
	ds_write_b16 v110, v0 offset:37536
	v_add_f32_e32 v0, v203, v176
	ds_write_b16 v110, v191 offset:20128
	v_mul_f32_e32 v191, 0x3fb8aa3b, v0
	v_exp_f32_e32 v191, v191
	s_nop 0
	v_mul_f32_e32 v191, v210, v191
	v_cvt_pk_bf16_f32 v191, v191, v191
	ds_write_b16 v110, v191 offset:2992
	v_sub_f32_e32 v191, v0, v216
	v_sub_f32_e32 v0, v216, v0
	v_mul_f32_e32 v0, 0x3fb8aa3b, v0
	v_mul_f32_e32 v191, 0x3fb8aa3b, v191
	v_exp_f32_e32 v0, v0
	v_exp_f32_e32 v191, v191
	v_mul_f32_e32 v0, v200, v0
	v_mul_f32_e32 v191, v210, v191
	v_cvt_pk_bf16_f32 v0, v0, v0
	v_cvt_pk_bf16_f32 v191, v191, v191
	ds_write_b16 v110, v0 offset:37808
	v_add_f32_e32 v0, v199, v176
	ds_write_b16 v110, v191 offset:20400
	v_mul_f32_e32 v191, 0x3fb8aa3b, v0
	v_exp_f32_e32 v191, v191
	s_nop 0
	v_mul_f32_e32 v191, v211, v191
	v_cvt_pk_bf16_f32 v191, v191, v191
	ds_write_b16 v110, v191 offset:3264
	v_sub_f32_e32 v191, v0, v216
	v_sub_f32_e32 v0, v216, v0
	v_mul_f32_e32 v0, 0x3fb8aa3b, v0
	v_mul_f32_e32 v191, 0x3fb8aa3b, v191
	v_exp_f32_e32 v0, v0
	v_exp_f32_e32 v191, v191
	v_mul_f32_e32 v0, v201, v0
	v_mul_f32_e32 v191, v211, v191
	v_cvt_pk_bf16_f32 v0, v0, v0
	v_cvt_pk_bf16_f32 v191, v191, v191
	ds_write_b16 v110, v0 offset:38080
	v_add_f32_e32 v0, v195, v176
	ds_write_b16 v110, v191 offset:20672
	v_mul_f32_e32 v191, 0x3fb8aa3b, v0
	v_exp_f32_e32 v191, v191
	s_nop 0
	v_mul_f32_e32 v191, v212, v191
	v_cvt_pk_bf16_f32 v191, v191, v191
	ds_write_b16 v110, v191 offset:3536
	v_sub_f32_e32 v191, v0, v216
	v_sub_f32_e32 v0, v216, v0
	v_mul_f32_e32 v0, 0x3fb8aa3b, v0
	v_exp_f32_e32 v0, v0
	v_mul_f32_e32 v191, 0x3fb8aa3b, v191
	v_exp_f32_e32 v191, v191
	v_mul_f32_e32 v0, v202, v0
	v_cvt_pk_bf16_f32 v0, v0, v0
	ds_write_b16 v110, v0 offset:38352
	v_add_f32_e32 v0, v178, v176
	v_mul_f32_e32 v178, 0x3fb8aa3b, v0
	v_exp_f32_e32 v178, v178
	v_mul_f32_e32 v191, v212, v191
	v_cvt_pk_bf16_f32 v191, v191, v191
	ds_write_b16 v110, v191 offset:20944
	v_mul_f32_e32 v178, v214, v178
	v_cvt_pk_bf16_f32 v178, v178, v178
	ds_write_b16 v110, v178 offset:3808
	v_sub_f32_e32 v178, v0, v216
	v_sub_f32_e32 v0, v216, v0
	v_mul_f32_e32 v0, 0x3fb8aa3b, v0
	v_exp_f32_e32 v0, v0
	v_mul_f32_e32 v178, 0x3fb8aa3b, v178
	v_exp_f32_e32 v178, v178
	v_mul_f32_e32 v0, v205, v0
	v_cvt_pk_bf16_f32 v0, v0, v0
	ds_write_b16 v110, v0 offset:38624
	v_add_f32_e32 v0, v175, v176
	v_mul_f32_e32 v175, 0x3fb8aa3b, v0
	v_exp_f32_e32 v175, v175
	v_mul_f32_e32 v178, v214, v178
	v_cvt_pk_bf16_f32 v178, v178, v178
	ds_write_b16 v110, v178 offset:21216
	v_mul_f32_e32 v175, v215, v175
	v_cvt_pk_bf16_f32 v175, v175, v175
	ds_write_b16 v110, v175 offset:4080
	v_sub_f32_e32 v175, v0, v216
	v_mul_f32_e32 v175, 0x3fb8aa3b, v175
	v_sub_f32_e32 v0, v216, v0
	v_exp_f32_e32 v175, v175
	v_mul_f32_e32 v0, 0x3fb8aa3b, v0
	v_exp_f32_e32 v0, v0
	v_mul_f32_e32 v175, v215, v175
	v_cvt_pk_bf16_f32 v175, v175, v175
	v_mul_f32_e32 v0, v206, v0
	ds_write_b16 v110, v175 offset:21488
	v_cvt_pk_bf16_f32 v0, v0, v0
	ds_write_b16 v110, v0 offset:38896
	v_cvt_pk_bf16_f32 v175, v194, v204
	ds_write_b128 v144, v[26:29] offset:52224
	ds_write_b128 v144, v[172:175] offset:52240
	s_and_saveexec_b64 s[0:1], s[36:37]
	s_cbranch_execz .LBB0_1117
	s_or_b32 s24, s10, s28
	v_readlane_b32 s25, v255, 20
	s_lshl_b32 s88, s24, s25
	s_and_b64 s[24:25], s[86:87], exec
	s_cselect_b32 s24, s95, s33
	s_add_i32 s24, s88, s24
	s_ashr_i32 s25, s24, 31
	v_readlane_b32 s40, v252, 51
	s_lshl_b64 s[24:25], s[24:25], 16
	v_readlane_b32 s54, v253, 1
	v_readlane_b32 s55, v253, 2
	s_add_u32 s88, s54, s24
	s_addc_u32 s89, s55, s25
	s_mov_b64 s[24:25], 0
	v_mov_b32_e32 v26, v100
	v_mov_b32_e32 v27, v30
	v_readlane_b32 s41, v252, 52
	v_readlane_b32 s42, v252, 53
	v_readlane_b32 s43, v252, 54
	v_readlane_b32 s44, v252, 55
	v_readlane_b32 s45, v252, 56
	v_readlane_b32 s46, v252, 57
	v_readlane_b32 s47, v252, 58
	v_readlane_b32 s48, v252, 59
	v_readlane_b32 s49, v252, 60
	v_readlane_b32 s50, v252, 61
	v_readlane_b32 s51, v252, 62
	v_readlane_b32 s52, v252, 63
	v_readlane_b32 s53, v253, 0

.LBB0_1431:
	s_or_b64 exec, exec, s[0:1]
	s_waitcnt lgkmcnt(0)
	v_mov_b32_e32 v0, v177
	s_barrier
	s_and_b32 s0, s72, 7
	s_lshl_b32 s0, s0, 5
	s_lshr_b32 s1, s72, 3
	s_add_i32 s0, s0, s1
	s_lshl_b32 s0, s0, 9
	s_mul_hi_i32 s1, s74, 0x2e8ba2e9
	s_lshr_b32 s4, s1, 31
	v_add_u32_e32 v0, s0, v0
	s_mov_b32 s0, 0x2e8ba2e9
	v_mul_hi_i32 v1, v0, s0
	s_ashr_i32 s12, s1, 6
	v_lshrrev_b32_e32 v2, 31, v1
	v_ashrrev_i32_e32 v1, 6, v1
	s_add_i32 s12, s12, s4
	v_add_u32_e32 v170, v1, v2
	v_cmp_gt_i32_e32 vcc, s12, v170
	s_and_saveexec_b64 s[4:5], vcc
	s_cbranch_execz .LBB0_1447
	s_mov_b32 s0, 0x580000
	v_cmp_gt_i32_e32 vcc, s0, v0
	s_and_b64 exec, exec, vcc
	s_cbranch_execz .LBB0_1447
	v_mul_i32_i24_e32 v1, 0x160, v170
	v_sub_u32_e32 v0, v0, v1
	v_lshlrev_b32_e32 v80, 3, v0
	v_readlane_b32 s40, v252, 51
	v_ashrrev_i32_e32 v81, 31, v80
	v_readlane_b32 s42, v252, 53
	v_readlane_b32 s43, v252, 54
	v_readlane_b32 s46, v252, 57
	v_readlane_b32 s47, v252, 58
	v_lshlrev_b64 v[72:73], 2, v[80:81]
	s_mov_b64 s[42:43], s[46:47]
	v_lshl_add_u64 v[64:65], s[42:43], 0, v[72:73]
	v_add_co_u32_e32 v8, vcc, 0x2000, v64
	s_mov_b64 s[0:1], 0x2c00
	s_nop 0
	v_addc_co_u32_e32 v9, vcc, 0, v65, vcc
	v_add_co_u32_e32 v16, vcc, 0x5000, v64
	v_lshl_add_u64 v[12:13], v[64:65], 0, s[0:1]
	s_nop 0
	v_addc_co_u32_e32 v17, vcc, 0, v65, vcc
	v_add_co_u32_e32 v24, vcc, 0x8000, v64
	s_mov_b64 s[0:1], 0x5800
	s_nop 0
	v_addc_co_u32_e32 v25, vcc, 0, v65, vcc
	v_add_co_u32_e32 v32, vcc, 0xb000, v64
	v_lshl_add_u64 v[20:21], v[64:65], 0, s[0:1]
	s_nop 0
	v_addc_co_u32_e32 v33, vcc, 0, v65, vcc
	s_mov_b64 s[0:1], 0x8400
	v_add_co_u32_e32 v40, vcc, 0xd000, v64
	v_lshl_add_u64 v[28:29], v[64:65], 0, s[0:1]
	s_mov_b64 s[0:1], 0xb000
	v_addc_co_u32_e32 v41, vcc, 0, v65, vcc
	v_lshl_add_u64 v[36:37], v[64:65], 0, s[0:1]
	s_mov_b64 s[0:1], 0xdc00
	v_add_co_u32_e32 v48, vcc, 0x10000, v64
	v_lshl_add_u64 v[44:45], v[64:65], 0, s[0:1]
	s_mov_b64 s[0:1], 0x10800
	v_addc_co_u32_e32 v49, vcc, 0, v65, vcc
	v_lshl_add_u64 v[52:53], v[64:65], 0, s[0:1]
	s_mov_b64 s[0:1], 0x13400
	v_add_co_u32_e32 v56, vcc, 0x13000, v64
	v_readlane_b32 s44, v252, 55
	v_readlane_b32 s45, v252, 56
	v_readlane_b32 s48, v252, 59
	v_readlane_b32 s49, v252, 60
	v_lshl_add_u64 v[60:61], v[64:65], 0, s[0:1]
	v_addc_co_u32_e32 v57, vcc, 0, v65, vcc
	s_mov_b64 s[0:1], 0x16000
	s_mov_b64 s[44:45], s[48:49]
	global_load_dwordx4 v[0:3], v[64:65], off
	global_load_dwordx4 v[4:7], v[64:65], off offset:16
	v_lshl_add_u64 v[68:69], v[64:65], 0, s[0:1]
	v_add_co_u32_e32 v64, vcc, 0x16000, v64
	v_lshl_add_u64 v[76:77], s[44:45], 0, v[72:73]
	s_nop 0
	v_addc_co_u32_e32 v65, vcc, 0, v65, vcc
	global_load_dwordx4 v[8:11], v[8:9], off offset:3072
	s_nop 0
	global_load_dwordx4 v[12:15], v[12:13], off offset:16
	s_nop 0
	global_load_dwordx4 v[16:19], v[16:17], off offset:2048
	s_nop 0
	global_load_dwordx4 v[20:23], v[20:21], off offset:16
	s_nop 0
	global_load_dwordx4 v[24:27], v[24:25], off offset:1024
	s_nop 0
	global_load_dwordx4 v[28:31], v[28:29], off offset:16
	s_nop 0
	global_load_dwordx4 v[32:35], v[32:33], off
	s_nop 0
	global_load_dwordx4 v[36:39], v[36:37], off offset:16
	s_nop 0
	global_load_dwordx4 v[40:43], v[40:41], off offset:3072
	s_nop 0
	global_load_dwordx4 v[44:47], v[44:45], off offset:16
	s_nop 0
	global_load_dwordx4 v[48:51], v[48:49], off offset:2048
	s_nop 0
	global_load_dwordx4 v[52:55], v[52:53], off offset:16
	s_nop 0
	global_load_dwordx4 v[56:59], v[56:57], off offset:1024
	s_nop 0
	global_load_dwordx4 v[60:63], v[60:61], off offset:16
	s_nop 0
	global_load_dwordx4 v[64:67], v[64:65], off
	s_nop 0
	global_load_dwordx4 v[68:71], v[68:69], off offset:16
	s_nop 0
	global_load_dwordx4 v[72:75], v[76:77], off
	s_nop 0
	global_load_dwordx4 v[76:79], v[76:77], off offset:16
	v_lshlrev_b64 v[80:81], 1, v[80:81]
	v_lshl_add_u64 v[164:165], s[2:3], 0, v[80:81]
	v_lshl_add_u64 v[166:167], s[16:17], 0, v[80:81]
	s_mov_b64 s[6:7], 0
	s_movk_i32 s13, 0x4000
	s_movk_i32 s14, 0x1fff
	s_movk_i32 s15, 0x1600
	v_mov_b32_e32 v169, 0
	s_movk_i32 s16, 0xff
	v_mov_b32_e32 v172, v170
	v_readlane_b32 s41, v252, 52
	v_readlane_b32 s50, v252, 61
	v_readlane_b32 s51, v252, 62
	v_readlane_b32 s52, v252, 63
	v_readlane_b32 s53, v253, 0
	v_readlane_b32 s54, v253, 1
	v_readlane_b32 s55, v253, 2
	s_branch .LBB0_1435

.LBB0_1443:
	s_or_b64 exec, exec, s[0:1]
	s_waitcnt vmcnt(23)
	v_mul_f32_e32 v168, v0, v190
	s_waitcnt vmcnt(9)
	v_lshlrev_b32_e32 v191, 16, v136
	s_waitcnt vmcnt(5)
	v_fma_f32 v168, v168, v191, v72
	v_mul_f32_e32 v191, v1, v190
	v_and_b32_e32 v136, 0xffff0000, v136
	v_fma_f32 v136, v191, v136, v73
	v_mul_f32_e32 v191, v2, v190
	v_lshlrev_b32_e32 v192, 16, v137
	v_fma_f32 v191, v191, v192, v74
	v_mul_f32_e32 v192, v3, v190
	v_and_b32_e32 v137, 0xffff0000, v137
	v_fma_f32 v137, v192, v137, v75
	v_mul_f32_e32 v192, v4, v190
	v_lshlrev_b32_e32 v193, 16, v138
	s_waitcnt vmcnt(4)
	v_fma_f32 v192, v192, v193, v76
	v_mul_f32_e32 v193, v5, v190
	v_and_b32_e32 v138, 0xffff0000, v138
	v_fma_f32 v138, v193, v138, v77
	v_mul_f32_e32 v193, v6, v190
	v_lshlrev_b32_e32 v194, 16, v139
	v_mul_f32_e32 v190, v7, v190
	v_and_b32_e32 v139, 0xffff0000, v139
	v_fma_f32 v193, v193, v194, v78
	v_fma_f32 v139, v190, v139, v79
	v_mul_f32_e32 v190, v8, v188
	v_lshlrev_b32_e32 v194, 16, v124
	v_fmac_f32_e32 v168, v190, v194
	v_mul_f32_e32 v190, v9, v188
	v_and_b32_e32 v124, 0xffff0000, v124
	v_fmac_f32_e32 v136, v190, v124
	v_mul_f32_e32 v124, v10, v188
	v_lshlrev_b32_e32 v190, 16, v125
	v_fmac_f32_e32 v191, v124, v190
	v_mul_f32_e32 v124, v11, v188
	v_and_b32_e32 v125, 0xffff0000, v125
	v_fmac_f32_e32 v137, v124, v125
	v_mul_f32_e32 v124, v12, v188
	v_lshlrev_b32_e32 v125, 16, v126
	v_fmac_f32_e32 v192, v124, v125
	v_mul_f32_e32 v124, v13, v188
	v_and_b32_e32 v125, 0xffff0000, v126
	v_fmac_f32_e32 v138, v124, v125
	v_mul_f32_e32 v124, v14, v188
	v_lshlrev_b32_e32 v125, 16, v127
	v_fmac_f32_e32 v193, v124, v125
	v_mul_f32_e32 v124, v15, v188
	v_and_b32_e32 v125, 0xffff0000, v127
	v_fmac_f32_e32 v139, v124, v125
	v_mul_f32_e32 v124, v16, v189
	v_lshlrev_b32_e32 v125, 16, v128
	v_fmac_f32_e32 v168, v124, v125
	v_mul_f32_e32 v124, v17, v189
	v_and_b32_e32 v125, 0xffff0000, v128
	v_fmac_f32_e32 v136, v124, v125
	v_mul_f32_e32 v124, v18, v189
	v_lshlrev_b32_e32 v125, 16, v129
	v_fmac_f32_e32 v191, v124, v125
	v_mul_f32_e32 v124, v19, v189
	v_and_b32_e32 v125, 0xffff0000, v129
	v_fmac_f32_e32 v137, v124, v125
	v_mul_f32_e32 v124, v20, v189
	v_lshlrev_b32_e32 v125, 16, v130
	v_fmac_f32_e32 v192, v124, v125
	v_mul_f32_e32 v124, v21, v189
	v_and_b32_e32 v125, 0xffff0000, v130
	v_fmac_f32_e32 v138, v124, v125
	v_mul_f32_e32 v124, v22, v189
	v_lshlrev_b32_e32 v125, 16, v131
	v_fmac_f32_e32 v193, v124, v125
	v_mul_f32_e32 v124, v23, v189
	v_and_b32_e32 v125, 0xffff0000, v131
	v_fmac_f32_e32 v139, v124, v125
	v_mul_f32_e32 v124, v24, v187
	s_waitcnt vmcnt(3)
	v_lshlrev_b32_e32 v125, 16, v156
	v_fmac_f32_e32 v168, v124, v125
	v_mul_f32_e32 v124, v25, v187
	v_and_b32_e32 v125, 0xffff0000, v156
	v_fmac_f32_e32 v136, v124, v125
	v_mul_f32_e32 v124, v26, v187
	v_lshlrev_b32_e32 v125, 16, v157
	v_fmac_f32_e32 v191, v124, v125
	v_mul_f32_e32 v124, v27, v187
	v_and_b32_e32 v125, 0xffff0000, v157
	v_fmac_f32_e32 v137, v124, v125
	v_mul_f32_e32 v124, v28, v187
	v_lshlrev_b32_e32 v125, 16, v158
	v_fmac_f32_e32 v192, v124, v125
	v_mul_f32_e32 v124, v29, v187
	v_and_b32_e32 v125, 0xffff0000, v158
	v_fmac_f32_e32 v138, v124, v125
	v_mul_f32_e32 v124, v30, v187
	v_lshlrev_b32_e32 v125, 16, v159
	v_fmac_f32_e32 v193, v124, v125
	v_mul_f32_e32 v124, v31, v187
	v_and_b32_e32 v125, 0xffff0000, v159
	v_fmac_f32_e32 v139, v124, v125
	s_waitcnt vmcnt(2)
	v_lshlrev_b32_e32 v124, 16, v152
	v_fmac_f32_e32 v168, v32, v124
	v_and_b32_e32 v124, 0xffff0000, v152
	v_fmac_f32_e32 v136, v33, v124
	v_lshlrev_b32_e32 v124, 16, v153
	v_fmac_f32_e32 v191, v34, v124
	v_and_b32_e32 v124, 0xffff0000, v153
	v_fmac_f32_e32 v137, v35, v124
	v_lshlrev_b32_e32 v124, 16, v154
	v_fmac_f32_e32 v192, v36, v124
	v_and_b32_e32 v124, 0xffff0000, v154
	v_fmac_f32_e32 v138, v37, v124
	v_lshlrev_b32_e32 v124, 16, v155
	v_fmac_f32_e32 v193, v38, v124
	v_and_b32_e32 v124, 0xffff0000, v155
	v_fmac_f32_e32 v139, v39, v124
	v_mul_f32_e32 v124, v40, v184
	s_waitcnt vmcnt(1)
	v_lshlrev_b32_e32 v125, 16, v148
	v_fmac_f32_e32 v168, v124, v125
	v_mul_f32_e32 v124, v41, v184
	v_and_b32_e32 v125, 0xffff0000, v148
	v_fmac_f32_e32 v136, v124, v125
	v_mul_f32_e32 v124, v42, v184
	v_lshlrev_b32_e32 v125, 16, v149
	v_fmac_f32_e32 v191, v124, v125
	v_mul_f32_e32 v124, v43, v184
	v_and_b32_e32 v125, 0xffff0000, v149
	v_fmac_f32_e32 v137, v124, v125
	v_mul_f32_e32 v124, v44, v184
	v_lshlrev_b32_e32 v125, 16, v150
	v_fmac_f32_e32 v192, v124, v125
	v_mul_f32_e32 v124, v45, v184
	v_and_b32_e32 v125, 0xffff0000, v150
	v_fmac_f32_e32 v138, v124, v125
	v_mul_f32_e32 v124, v46, v184
	v_lshlrev_b32_e32 v125, 16, v151
	v_fmac_f32_e32 v193, v124, v125
	v_mul_f32_e32 v124, v47, v184
	v_and_b32_e32 v125, 0xffff0000, v151
	v_fmac_f32_e32 v139, v124, v125
	v_mul_f32_e32 v124, v48, v186
	v_lshlrev_b32_e32 v125, 16, v120
	v_fmac_f32_e32 v168, v124, v125
	v_mul_f32_e32 v124, v49, v186
	v_and_b32_e32 v120, 0xffff0000, v120
	v_fmac_f32_e32 v136, v124, v120
	v_mul_f32_e32 v120, v50, v186
	v_lshlrev_b32_e32 v124, 16, v121
	v_fmac_f32_e32 v191, v120, v124
	v_mul_f32_e32 v120, v51, v186
	v_and_b32_e32 v121, 0xffff0000, v121
	v_fmac_f32_e32 v137, v120, v121
	v_mul_f32_e32 v120, v52, v186
	v_lshlrev_b32_e32 v121, 16, v122
	v_fmac_f32_e32 v192, v120, v121
	v_mul_f32_e32 v120, v53, v186
	v_and_b32_e32 v121, 0xffff0000, v122
	v_fmac_f32_e32 v138, v120, v121
	v_mul_f32_e32 v120, v54, v186
	v_lshlrev_b32_e32 v121, 16, v123
	v_fmac_f32_e32 v193, v120, v121
	v_mul_f32_e32 v120, v55, v186
	v_and_b32_e32 v121, 0xffff0000, v123
	v_fmac_f32_e32 v139, v120, v121
	v_mul_f32_e32 v120, v56, v183
	v_lshlrev_b32_e32 v121, 16, v112
	v_fmac_f32_e32 v168, v120, v121
	v_mul_f32_e32 v120, v57, v183
	v_and_b32_e32 v112, 0xffff0000, v112
	v_fmac_f32_e32 v136, v120, v112
	v_mul_f32_e32 v112, v58, v183
	v_lshlrev_b32_e32 v120, 16, v113
	v_fmac_f32_e32 v191, v112, v120
	v_mul_f32_e32 v112, v59, v183
	v_and_b32_e32 v113, 0xffff0000, v113
	v_fmac_f32_e32 v137, v112, v113
	v_mul_f32_e32 v112, v60, v183
	v_lshlrev_b32_e32 v113, 16, v114
	v_fmac_f32_e32 v192, v112, v113
	v_mul_f32_e32 v112, v61, v183
	v_and_b32_e32 v113, 0xffff0000, v114
	v_fmac_f32_e32 v138, v112, v113
	v_mul_f32_e32 v112, v62, v183
	v_lshlrev_b32_e32 v113, 16, v115
	v_fmac_f32_e32 v193, v112, v113
	v_mul_f32_e32 v112, v63, v183
	v_and_b32_e32 v113, 0xffff0000, v115
	v_fmac_f32_e32 v139, v112, v113
	v_mul_f32_e32 v112, v64, v180
	v_lshlrev_b32_e32 v113, 16, v96
	v_fmac_f32_e32 v168, v112, v113
	v_mul_f32_e32 v112, v65, v180
	v_and_b32_e32 v96, 0xffff0000, v96
	v_fmac_f32_e32 v136, v112, v96
	v_mul_f32_e32 v96, v66, v180
	v_lshlrev_b32_e32 v112, 16, v97
	v_fmac_f32_e32 v191, v96, v112
	v_mul_f32_e32 v96, v67, v180
	v_and_b32_e32 v97, 0xffff0000, v97
	v_fmac_f32_e32 v137, v96, v97
	v_mul_f32_e32 v96, v68, v180
	v_lshlrev_b32_e32 v97, 16, v98
	v_fmac_f32_e32 v192, v96, v97
	v_mul_f32_e32 v96, v69, v180
	v_and_b32_e32 v97, 0xffff0000, v98
	v_fmac_f32_e32 v138, v96, v97
	v_mul_f32_e32 v96, 0x3d372713, v168
	v_mul_f32_e32 v96, v168, v96
	v_fma_f32 v96, v168, v96, v168
	v_mul_f32_e32 v96, 0x3f4c422a, v96
	v_add_f32_e32 v96, v96, v96
	v_mul_f32_e32 v96, 0x3fb8aa3b, v96
	v_exp_f32_e32 v96, v96
	v_mul_f32_e32 v97, v70, v180
	v_lshlrev_b32_e32 v98, 16, v99
	v_fmac_f32_e32 v193, v97, v98
	v_add_f32_e32 v96, 1.0, v96
	v_mul_f32_e32 v112, v71, v180
	v_and_b32_e32 v99, 0xffff0000, v99
	v_fmac_f32_e32 v139, v112, v99
	v_mul_f32_e32 v99, 0x3d372713, v136
	v_mul_f32_e32 v99, v136, v99
	v_fma_f32 v99, v136, v99, v136
	v_mul_f32_e32 v99, 0x3f4c422a, v99
	v_add_f32_e32 v99, v99, v99
	v_mul_f32_e32 v99, 0x3fb8aa3b, v99
	v_exp_f32_e32 v99, v99
	v_rcp_f32_e32 v97, v96
	s_nop 0
	v_mul_f32_e32 v96, v168, v97
	v_sub_f32_e32 v96, v168, v96
	v_add_f32_e32 v97, 1.0, v99
	s_waitcnt vmcnt(0)
	v_lshlrev_b32_e32 v112, 16, v100
	v_mul_f32_e32 v96, v96, v112
	v_and_b32_e32 v100, 0xffff0000, v100
	v_mul_f32_e32 v112, 0x3d372713, v191
	v_mul_f32_e32 v112, v191, v112
	v_fma_f32 v112, v191, v112, v191
	v_mul_f32_e32 v112, 0x3f4c422a, v112
	v_add_f32_e32 v112, v112, v112
	v_mul_f32_e32 v112, 0x3fb8aa3b, v112
	v_exp_f32_e32 v112, v112
	v_rcp_f32_e32 v98, v97
	s_nop 0
	v_mul_f32_e32 v97, v136, v98
	v_sub_f32_e32 v97, v136, v97
	v_add_f32_e32 v98, 1.0, v112
	v_mul_f32_e32 v97, v97, v100
	v_cvt_pk_bf16_f32 v96, v96, v97
	v_mad_u64_u32 v[132:133], s[0:1], v86, s15, v[166:167]
	v_mul_f32_e32 v99, 0x3d372713, v137
	v_mul_f32_e32 v99, v137, v99
	v_fma_f32 v99, v137, v99, v137
	v_mul_f32_e32 v99, 0x3f4c422a, v99
	v_add_f32_e32 v99, v99, v99
	v_mul_f32_e32 v99, 0x3fb8aa3b, v99
	v_exp_f32_e32 v99, v99
	v_rcp_f32_e32 v97, v98
	s_nop 0
	v_mul_f32_e32 v97, v191, v97
	v_sub_f32_e32 v97, v191, v97
	v_add_f32_e32 v98, 1.0, v99
	v_lshlrev_b32_e32 v112, 16, v101
	v_mul_f32_e32 v97, v97, v112
	v_mov_b32_e32 v86, v133
	v_mul_f32_e32 v112, 0x3d372713, v192
	v_mul_f32_e32 v112, v192, v112
	v_fma_f32 v112, v192, v112, v192
	v_mad_u64_u32 v[86:87], s[0:1], v87, s15, v[86:87]
	v_mul_f32_e32 v112, 0x3f4c422a, v112
	v_mov_b32_e32 v133, v86
	v_mad_u64_u32 v[86:87], s[0:1], v84, s15, v[166:167]
	v_mul_lo_u32 v134, v85, s15
	v_cndmask_b32_e64 v85, 0, 1, s[8:9]
	v_add_f32_e32 v112, v112, v112
	v_add_u32_e32 v87, v134, v87
	v_add_u32_e32 v85, v84, v85
	v_mul_f32_e32 v112, 0x3fb8aa3b, v112
	global_load_dwordx4 v[144:147], v[132:133], off
	global_load_dwordx4 v[140:143], v[86:87], off
	v_mad_i64_i32 v[86:87], s[0:1], v85, s15, v[166:167]
	v_mad_u64_u32 v[84:85], s[0:1], v84, s15, v[164:165]
	v_exp_f32_e32 v112, v112
	v_add_u32_e32 v85, v134, v85
	global_load_dwordx4 v[132:135], v[86:87], off
	s_nop 0
	global_load_dwordx4 v[84:87], v[84:85], off
	v_rcp_f32_e32 v99, v98
	s_nop 0
	v_mul_f32_e32 v98, v137, v99
	v_add_f32_e32 v99, 1.0, v112
	v_sub_f32_e32 v98, v137, v98
	v_and_b32_e32 v101, 0xffff0000, v101
	v_mul_f32_e32 v98, v98, v101
	v_cvt_pk_bf16_f32 v97, v97, v98
	v_mul_f32_e32 v100, 0x3d372713, v138
	v_mul_f32_e32 v100, v138, v100
	v_fma_f32 v100, v138, v100, v138
	v_mul_f32_e32 v100, 0x3f4c422a, v100
	v_add_f32_e32 v100, v100, v100
	v_mul_f32_e32 v100, 0x3fb8aa3b, v100
	v_exp_f32_e32 v100, v100
	v_rcp_f32_e32 v98, v99
	s_nop 0
	v_mul_f32_e32 v98, v192, v98
	v_sub_f32_e32 v98, v192, v98
	v_add_f32_e32 v99, 1.0, v100
	v_lshlrev_b32_e32 v112, 16, v102
	v_mul_f32_e32 v98, v98, v112
	v_and_b32_e32 v102, 0xffff0000, v102
	v_mul_f32_e32 v112, 0x3d372713, v193
	v_mul_f32_e32 v112, v193, v112
	v_fma_f32 v112, v193, v112, v193
	v_mul_f32_e32 v112, 0x3f4c422a, v112
	v_add_f32_e32 v112, v112, v112
	v_mul_f32_e32 v112, 0x3fb8aa3b, v112
	v_exp_f32_e32 v112, v112
	v_rcp_f32_e32 v100, v99
	s_nop 0
	v_mul_f32_e32 v99, v138, v100
	v_sub_f32_e32 v99, v138, v99
	v_add_f32_e32 v100, 1.0, v112
	v_mul_f32_e32 v99, v99, v102
	v_cvt_pk_bf16_f32 v98, v98, v99
	v_mul_f32_e32 v101, 0x3d372713, v139
	v_mul_f32_e32 v101, v139, v101
	v_fma_f32 v101, v139, v101, v139
	v_mul_f32_e32 v101, 0x3f4c422a, v101
	v_add_f32_e32 v101, v101, v101
	v_mul_f32_e32 v101, 0x3fb8aa3b, v101
	v_exp_f32_e32 v101, v101
	v_rcp_f32_e32 v99, v100
	s_nop 0
	v_mul_f32_e32 v99, v193, v99
	v_sub_f32_e32 v99, v193, v99
	v_add_f32_e32 v100, 1.0, v101
	v_lshlrev_b32_e32 v112, 16, v103
	v_mul_f32_e32 v99, v99, v112
	v_rcp_f32_e32 v101, v100
	s_nop 0
	v_mul_f32_e32 v100, v139, v101
	v_sub_f32_e32 v100, v139, v100
	v_and_b32_e32 v101, 0xffff0000, v103
	v_mul_f32_e32 v100, v100, v101
	v_cvt_pk_bf16_f32 v99, v99, v100
	s_and_saveexec_b64 s[0:1], s[40:41]
	s_cbranch_execz .LBB0_1445
	v_mad_i64_i32 v[100:101], s[8:9], v172, s15, v[164:165]
	global_store_dwordx4 v[100:101], v[96:99], off sc1
.LBB0_1445:
	s_or_b64 exec, exec, s[0:1]
	s_nop 0
	v_mul_f32_e32 v96, v0, v185
	v_lshlrev_b32_e32 v97, 16, v116
	v_fma_f32 v96, v96, v97, v72
	v_mul_f32_e32 v97, v1, v185
	v_and_b32_e32 v98, 0xffff0000, v116
	v_fma_f32 v97, v97, v98, v73
	v_mul_f32_e32 v98, v2, v185
	v_lshlrev_b32_e32 v99, 16, v117
	v_fma_f32 v98, v98, v99, v74
	v_mul_f32_e32 v99, v3, v185
	v_and_b32_e32 v100, 0xffff0000, v117
	v_fma_f32 v99, v99, v100, v75
	v_mul_f32_e32 v100, v4, v185
	v_lshlrev_b32_e32 v101, 16, v118
	v_fma_f32 v100, v100, v101, v76
	v_mul_f32_e32 v101, v5, v185
	v_and_b32_e32 v102, 0xffff0000, v118
	v_fma_f32 v101, v101, v102, v77
	v_mul_f32_e32 v102, v6, v185
	v_lshlrev_b32_e32 v103, 16, v119
	v_fma_f32 v102, v102, v103, v78
	v_mul_f32_e32 v103, v7, v185
	v_and_b32_e32 v112, 0xffff0000, v119
	v_fma_f32 v103, v103, v112, v79
	v_mul_f32_e32 v112, v8, v181
	v_lshlrev_b32_e32 v113, 16, v104
	v_fmac_f32_e32 v96, v112, v113
	v_mul_f32_e32 v112, v9, v181
	v_and_b32_e32 v104, 0xffff0000, v104
	v_fmac_f32_e32 v97, v112, v104
	v_mul_f32_e32 v104, v10, v181
	v_lshlrev_b32_e32 v112, 16, v105
	v_fmac_f32_e32 v98, v104, v112
	v_mul_f32_e32 v104, v11, v181
	v_and_b32_e32 v105, 0xffff0000, v105
	v_fmac_f32_e32 v99, v104, v105
	v_mul_f32_e32 v104, v12, v181
	v_lshlrev_b32_e32 v105, 16, v106
	v_fmac_f32_e32 v100, v104, v105
	v_mul_f32_e32 v104, v13, v181
	v_and_b32_e32 v105, 0xffff0000, v106
	v_fmac_f32_e32 v101, v104, v105
	v_mul_f32_e32 v104, v14, v181
	v_lshlrev_b32_e32 v105, 16, v107
	v_fmac_f32_e32 v102, v104, v105
	v_mul_f32_e32 v104, v15, v181
	v_and_b32_e32 v105, 0xffff0000, v107
	v_fmac_f32_e32 v103, v104, v105
	v_mul_f32_e32 v104, v16, v182
	v_lshlrev_b32_e32 v105, 16, v108
	v_fmac_f32_e32 v96, v104, v105
	v_mul_f32_e32 v104, v17, v182
	v_and_b32_e32 v105, 0xffff0000, v108
	v_fmac_f32_e32 v97, v104, v105
	v_mul_f32_e32 v104, v18, v182
	v_lshlrev_b32_e32 v105, 16, v109
	v_fmac_f32_e32 v98, v104, v105
	v_mul_f32_e32 v104, v19, v182
	v_and_b32_e32 v105, 0xffff0000, v109
	v_fmac_f32_e32 v99, v104, v105
	v_mul_f32_e32 v104, v20, v182
	v_lshlrev_b32_e32 v105, 16, v110
	v_fmac_f32_e32 v100, v104, v105
	v_mul_f32_e32 v104, v21, v182
	v_and_b32_e32 v105, 0xffff0000, v110
	v_fmac_f32_e32 v101, v104, v105
	v_mul_f32_e32 v104, v22, v182
	v_lshlrev_b32_e32 v105, 16, v111
	v_fmac_f32_e32 v102, v104, v105
	v_mul_f32_e32 v104, v23, v182
	v_and_b32_e32 v105, 0xffff0000, v111
	v_fmac_f32_e32 v103, v104, v105
	v_mul_f32_e32 v104, v24, v178
	s_waitcnt vmcnt(3)
	v_lshlrev_b32_e32 v105, 16, v144
	v_fmac_f32_e32 v96, v104, v105
	v_mul_f32_e32 v104, v25, v178
	v_and_b32_e32 v105, 0xffff0000, v144
	v_fmac_f32_e32 v97, v104, v105
	v_mul_f32_e32 v104, v26, v178
	v_lshlrev_b32_e32 v105, 16, v145
	v_fmac_f32_e32 v98, v104, v105
	v_mul_f32_e32 v104, v27, v178
	v_and_b32_e32 v105, 0xffff0000, v145
	v_fmac_f32_e32 v99, v104, v105
	v_mul_f32_e32 v104, v28, v178
	v_lshlrev_b32_e32 v105, 16, v146
	v_fmac_f32_e32 v100, v104, v105
	v_mul_f32_e32 v104, v29, v178
	v_and_b32_e32 v105, 0xffff0000, v146
	v_fmac_f32_e32 v101, v104, v105
	v_mul_f32_e32 v104, v30, v178
	v_lshlrev_b32_e32 v105, 16, v147
	v_fmac_f32_e32 v102, v104, v105
	v_mul_f32_e32 v104, v31, v178
	v_and_b32_e32 v105, 0xffff0000, v147
	v_fmac_f32_e32 v103, v104, v105
	s_waitcnt vmcnt(2)
	v_lshlrev_b32_e32 v104, 16, v140
	v_fmac_f32_e32 v96, v32, v104
	v_and_b32_e32 v104, 0xffff0000, v140
	v_fmac_f32_e32 v97, v33, v104
	v_lshlrev_b32_e32 v104, 16, v141
	v_fmac_f32_e32 v98, v34, v104
	v_and_b32_e32 v104, 0xffff0000, v141
	v_fmac_f32_e32 v99, v35, v104
	v_lshlrev_b32_e32 v104, 16, v142
	v_fmac_f32_e32 v100, v36, v104
	v_and_b32_e32 v104, 0xffff0000, v142
	v_fmac_f32_e32 v101, v37, v104
	v_lshlrev_b32_e32 v104, 16, v143
	v_fmac_f32_e32 v102, v38, v104
	v_and_b32_e32 v104, 0xffff0000, v143
	v_fmac_f32_e32 v103, v39, v104
	v_mul_f32_e32 v104, v40, v175
	s_waitcnt vmcnt(1)
	v_lshlrev_b32_e32 v105, 16, v132
	v_fmac_f32_e32 v96, v104, v105
	v_mul_f32_e32 v104, v41, v175
	v_and_b32_e32 v105, 0xffff0000, v132
	v_fmac_f32_e32 v97, v104, v105
	v_mul_f32_e32 v104, v42, v175
	v_lshlrev_b32_e32 v105, 16, v133
	v_fmac_f32_e32 v98, v104, v105
	v_mul_f32_e32 v104, v43, v175
	v_and_b32_e32 v105, 0xffff0000, v133
	v_fmac_f32_e32 v99, v104, v105
	v_mul_f32_e32 v104, v44, v175
	v_lshlrev_b32_e32 v105, 16, v134
	v_fmac_f32_e32 v100, v104, v105
	v_mul_f32_e32 v104, v45, v175
	v_and_b32_e32 v105, 0xffff0000, v134
	v_fmac_f32_e32 v101, v104, v105
	v_mul_f32_e32 v104, v46, v175
	v_lshlrev_b32_e32 v105, 16, v135
	v_fmac_f32_e32 v102, v104, v105
	v_mul_f32_e32 v104, v47, v175
	v_and_b32_e32 v105, 0xffff0000, v135
	v_fmac_f32_e32 v103, v104, v105
	v_mul_f32_e32 v104, v48, v176
	v_lshlrev_b32_e32 v105, 16, v92
	v_fmac_f32_e32 v96, v104, v105
	v_mul_f32_e32 v104, v49, v176
	v_and_b32_e32 v92, 0xffff0000, v92
	v_fmac_f32_e32 v97, v104, v92
	v_mul_f32_e32 v92, v50, v176
	v_lshlrev_b32_e32 v104, 16, v93
	v_fmac_f32_e32 v98, v92, v104
	v_mul_f32_e32 v92, v51, v176
	v_and_b32_e32 v93, 0xffff0000, v93
	v_fmac_f32_e32 v99, v92, v93
	v_mul_f32_e32 v92, v52, v176
	v_lshlrev_b32_e32 v93, 16, v94
	v_fmac_f32_e32 v100, v92, v93
	v_mul_f32_e32 v92, v53, v176
	v_and_b32_e32 v93, 0xffff0000, v94
	v_fmac_f32_e32 v101, v92, v93
	v_mul_f32_e32 v92, v54, v176
	v_lshlrev_b32_e32 v93, 16, v95
	v_fmac_f32_e32 v102, v92, v93
	v_mul_f32_e32 v92, v55, v176
	v_and_b32_e32 v93, 0xffff0000, v95
	v_fmac_f32_e32 v103, v92, v93
	v_mul_f32_e32 v92, v56, v174
	v_lshlrev_b32_e32 v93, 16, v88
	v_fmac_f32_e32 v96, v92, v93
	v_mul_f32_e32 v92, v57, v174
	v_and_b32_e32 v88, 0xffff0000, v88
	v_fmac_f32_e32 v97, v92, v88
	v_mul_f32_e32 v88, v58, v174
	v_lshlrev_b32_e32 v92, 16, v89
	v_fmac_f32_e32 v98, v88, v92
	v_mul_f32_e32 v88, v59, v174
	v_and_b32_e32 v89, 0xffff0000, v89
	v_fmac_f32_e32 v99, v88, v89
	v_mul_f32_e32 v88, v60, v174
	v_lshlrev_b32_e32 v89, 16, v90
	v_fmac_f32_e32 v100, v88, v89
	v_mul_f32_e32 v88, v61, v174
	v_and_b32_e32 v89, 0xffff0000, v90
	v_fmac_f32_e32 v101, v88, v89
	v_mul_f32_e32 v88, v62, v174
	v_lshlrev_b32_e32 v89, 16, v91
	v_fmac_f32_e32 v102, v88, v89
	v_mul_f32_e32 v88, v63, v174
	v_and_b32_e32 v89, 0xffff0000, v91
	v_fmac_f32_e32 v103, v88, v89
	v_mul_f32_e32 v88, v64, v173
	v_lshlrev_b32_e32 v89, 16, v80
	v_fmac_f32_e32 v96, v88, v89
	v_mul_f32_e32 v88, v65, v173
	v_and_b32_e32 v80, 0xffff0000, v80
	v_fmac_f32_e32 v97, v88, v80
	v_mul_f32_e32 v80, v66, v173
	v_lshlrev_b32_e32 v88, 16, v81
	v_fmac_f32_e32 v98, v80, v88
	v_mul_f32_e32 v80, v67, v173
	v_and_b32_e32 v81, 0xffff0000, v81
	v_fmac_f32_e32 v99, v80, v81
	v_mul_f32_e32 v80, v68, v173
	v_lshlrev_b32_e32 v81, 16, v82
	v_fmac_f32_e32 v100, v80, v81
	v_mul_f32_e32 v80, v69, v173
	v_and_b32_e32 v81, 0xffff0000, v82
	v_fmac_f32_e32 v101, v80, v81
	v_mul_f32_e32 v80, 0x3d372713, v96
	v_mul_f32_e32 v80, v96, v80
	v_fma_f32 v80, v96, v80, v96
	v_mul_f32_e32 v80, 0x3f4c422a, v80
	v_add_f32_e32 v80, v80, v80
	v_mul_f32_e32 v80, 0x3fb8aa3b, v80
	v_exp_f32_e32 v80, v80
	v_mul_f32_e32 v81, v70, v173
	v_lshlrev_b32_e32 v82, 16, v83
	v_fmac_f32_e32 v102, v81, v82
	v_add_f32_e32 v80, 1.0, v80
	v_mul_f32_e32 v88, v71, v173
	v_and_b32_e32 v83, 0xffff0000, v83
	v_fmac_f32_e32 v103, v88, v83
	v_mul_f32_e32 v83, 0x3d372713, v97
	v_mul_f32_e32 v83, v97, v83
	v_fma_f32 v83, v97, v83, v97
	v_mul_f32_e32 v83, 0x3f4c422a, v83
	v_add_f32_e32 v83, v83, v83
	v_mul_f32_e32 v83, 0x3fb8aa3b, v83
	v_exp_f32_e32 v83, v83
	v_rcp_f32_e32 v81, v80
	s_nop 0
	v_mul_f32_e32 v80, v96, v81
	v_sub_f32_e32 v80, v96, v80
	v_add_f32_e32 v81, 1.0, v83
	s_waitcnt vmcnt(0)
	v_lshlrev_b32_e32 v88, 16, v84
	v_mul_f32_e32 v80, v80, v88
	v_and_b32_e32 v84, 0xffff0000, v84
	v_mul_f32_e32 v88, 0x3d372713, v98
	v_mul_f32_e32 v88, v98, v88
	v_fma_f32 v88, v98, v88, v98
	v_mul_f32_e32 v88, 0x3f4c422a, v88
	v_add_f32_e32 v88, v88, v88
	v_mul_f32_e32 v88, 0x3fb8aa3b, v88
	v_exp_f32_e32 v88, v88
	v_rcp_f32_e32 v82, v81
	s_nop 0
	v_mul_f32_e32 v81, v97, v82
	v_sub_f32_e32 v81, v97, v81
	v_add_f32_e32 v82, 1.0, v88
	v_mul_f32_e32 v81, v81, v84
	v_cvt_pk_bf16_f32 v80, v80, v81
	v_mul_f32_e32 v83, 0x3d372713, v99
	v_mul_f32_e32 v83, v99, v83
	v_fma_f32 v83, v99, v83, v99
	v_mul_f32_e32 v83, 0x3f4c422a, v83
	v_add_f32_e32 v83, v83, v83
	v_mul_f32_e32 v83, 0x3fb8aa3b, v83
	v_exp_f32_e32 v83, v83
	v_rcp_f32_e32 v81, v82
	s_nop 0
	v_mul_f32_e32 v81, v98, v81
	v_sub_f32_e32 v81, v98, v81
	v_add_f32_e32 v82, 1.0, v83
	v_lshlrev_b32_e32 v88, 16, v85
	v_mul_f32_e32 v81, v81, v88
	v_and_b32_e32 v85, 0xffff0000, v85
	v_mul_f32_e32 v88, 0x3d372713, v100
	v_mul_f32_e32 v88, v100, v88
	v_fma_f32 v88, v100, v88, v100
	v_mul_f32_e32 v88, 0x3f4c422a, v88
	v_add_f32_e32 v88, v88, v88
	v_mul_f32_e32 v88, 0x3fb8aa3b, v88
	v_exp_f32_e32 v88, v88
	v_rcp_f32_e32 v83, v82
	s_nop 0
	v_mul_f32_e32 v82, v99, v83
	v_sub_f32_e32 v82, v99, v82
	v_add_f32_e32 v83, 1.0, v88
	v_mul_f32_e32 v82, v82, v85
	v_cvt_pk_bf16_f32 v81, v81, v82
	v_mul_f32_e32 v84, 0x3d372713, v101
	v_mul_f32_e32 v84, v101, v84
	v_fma_f32 v84, v101, v84, v101
	v_mul_f32_e32 v84, 0x3f4c422a, v84
	v_add_f32_e32 v84, v84, v84
	v_mul_f32_e32 v84, 0x3fb8aa3b, v84
	v_exp_f32_e32 v84, v84
	v_rcp_f32_e32 v82, v83
	s_nop 0
	v_mul_f32_e32 v82, v100, v82
	v_sub_f32_e32 v82, v100, v82
	v_add_f32_e32 v83, 1.0, v84
	v_lshlrev_b32_e32 v88, 16, v86
	v_mul_f32_e32 v82, v82, v88
	v_and_b32_e32 v86, 0xffff0000, v86
	v_mul_f32_e32 v88, 0x3d372713, v102
	v_mul_f32_e32 v88, v102, v88
	v_fma_f32 v88, v102, v88, v102
	v_mul_f32_e32 v88, 0x3f4c422a, v88
	v_add_f32_e32 v88, v88, v88
	v_mul_f32_e32 v88, 0x3fb8aa3b, v88
	v_exp_f32_e32 v88, v88
	v_rcp_f32_e32 v84, v83
	s_nop 0
	v_mul_f32_e32 v83, v101, v84
	v_sub_f32_e32 v83, v101, v83
	v_add_f32_e32 v84, 1.0, v88
	v_mul_f32_e32 v83, v83, v86
	v_cvt_pk_bf16_f32 v82, v82, v83
	v_mul_f32_e32 v85, 0x3d372713, v103
	v_mul_f32_e32 v85, v103, v85
	v_fma_f32 v85, v103, v85, v103
	v_mul_f32_e32 v85, 0x3f4c422a, v85
	v_add_f32_e32 v85, v85, v85
	v_mul_f32_e32 v85, 0x3fb8aa3b, v85
	v_exp_f32_e32 v85, v85
	v_rcp_f32_e32 v83, v84
	s_nop 0
	v_mul_f32_e32 v83, v102, v83
	v_sub_f32_e32 v83, v102, v83
	v_add_f32_e32 v84, 1.0, v85
	v_lshlrev_b32_e32 v88, 16, v87
	v_mul_f32_e32 v83, v83, v88
	v_rcp_f32_e32 v85, v84
	s_nop 0
	v_mul_f32_e32 v84, v103, v85
	v_sub_f32_e32 v84, v103, v84
	v_and_b32_e32 v85, 0xffff0000, v87
	v_mul_f32_e32 v84, v84, v85
	v_cvt_pk_bf16_f32 v83, v83, v84
	s_and_saveexec_b64 s[0:1], s[38:39]
	s_cbranch_execz .LBB0_1434
	v_mad_i64_i32 v[84:85], s[8:9], v171, s15, v[164:165]
	global_store_dwordx4 v[84:85], v[80:83], off sc1
	s_branch .LBB0_1434
